# loop-edge edit (doc 7.11): GEMM K-loop induction updates + exit compare moved in front of the loop-back barrier in 10 loops
# speedup vs baseline: 1.0048x; 1.0048x over previous
; #define PG8_STAGE(bufoff, gbase, voff) do { _Pragma("unroll") for (int _i = 0; _i < 2; ++_i) \
;         __builtin_amdgcn_global_load_lds((const unsigned*)((const char*)(gbase) + (voff)[_i]), (LAS unsigned*)(lds + (bufoff) + ldsw + _i * 8192), 16, 0, 0); } while (0)
; #define PG8_LDA(dst, b, h) do { _Pragma("unroll") for (int m = 0; m < 4; ++m) _Pragma("unroll") for (int k = 0; k < 2; ++k) dst[m][k] = *(const LAS bf16x8*)(lds + PG8_SA(b, h) + aoff + m * 2048 + k * 1024); } while (0)
; #define PG8_LDB(dst, b, h) do { _Pragma("unroll") for (int n = 0; n < 2; ++n) _Pragma("unroll") for (int k = 0; k < 2; ++k) dst[n][k] = *(const LAS bf16x8*)(lds + PG8_SB(b, h) + boff + n * 2048 + k * 1024); } while (0)
; #define PG8_MMA(ai, bj, At, Bt) do { __builtin_amdgcn_s_setprio(1); _Pragma("unroll") for (int m = 0; m < 4; ++m) _Pragma("unroll") for (int n = 0; n < 2; ++n) _Pragma("unroll") for (int k = 0; k < 2; ++k) \
;         acc[ai][bj][m][n] = __builtin_amdgcn_mfma_f32_16x16x32_bf16(Bt[n][k], At[m][k], acc[ai][bj][m][n], 0, 0, 0); __builtin_amdgcn_s_setprio(0); } while (0)
; #define PG8_WAIT_V(n) asm volatile("s_waitcnt vmcnt(" #n ")" ::: "memory")
; #define PG8_WAIT_L(n) asm volatile("s_waitcnt lgkmcnt(" #n ")" ::: "memory")
; #define PG8_BAR __builtin_amdgcn_s_barrier()
; #define PG8_SCHED __builtin_amdgcn_sched_barrier(0)
; template <class Epi, class Sched>
; __device__ __forceinline__ void gemm_phase(LAS unsigned char* lds, const Gemm g, const Sched& S, const Epi& E, int wave_id) {
;     ...
;         for (int t = 0; t < nt; t += 2) {
;             const bool last = (t == nt - 2);
;             const char* a1 = cA + (size_t)(t + 1) * kstep;
;             const char* a2 = last ? nA : cA + (size_t)(t + 2) * kstep; const char* b2 = last ? nB : cB + (size_t)(t + 2) * kstep;
;             const char* a3 = a2 + kstep; const char* b3 = b2 + kstep;
;             PG8_LDB(B0, 0, 0); PG8_LDB(B1, 0, 1); PG8_SCHED; PG8_LDA(At, 0, 0); PG8_STAGE(PG8_SA(1, 1), a1 + hstepA, voffA);
;             PG8_WAIT_V(8); PG8_WAIT_L(0); PG8_BAR; PG8_MMA(0, 0, At, B0); PG8_MMA(0, 1, At, B1); PG8_BAR; PG8_SCHED;
;             PG8_LDA(At, 0, 1); PG8_STAGE(PG8_SB(0, 0), b2, voffB); PG8_STAGE(PG8_SB(0, 1), b2 + hstepB, voffB); PG8_STAGE(PG8_SA(0, 0), a2, voffA);
;             PG8_WAIT_V(8); PG8_WAIT_L(0); PG8_BAR; PG8_MMA(1, 0, At, B0); PG8_MMA(1, 1, At, B1); PG8_BAR; PG8_SCHED;
.LBB0_252:
	ds_read_b128 v[16:19], v183
	ds_read_b128 v[20:23], v183 offset:1024
	ds_read_b128 v[32:35], v183 offset:2048
	ds_read_b128 v[36:39], v183 offset:3072
	ds_read_b128 v[184:187], v190
	ds_read_b128 v[194:197], v190 offset:1024
	ds_read_b128 v[198:201], v190 offset:2048
	ds_read_b128 v[202:205], v190 offset:3072
	s_add_u32 s12, s10, 0xfffc0080
	s_addc_u32 s13, s11, -1
	s_cmp_eq_u32 s45, 12
	s_cselect_b32 s15, s2, s13
	s_cselect_b32 s14, s7, s12
	s_cselect_b32 s13, s9, s39
	s_cselect_b32 s12, s18, s33
	v_lshl_add_u64 v[168:169], s[10:11], 0, v[158:159]
	s_add_i32 m0, s55, 0xc000
	ds_read_b128 v[206:209], v191
	ds_read_b128 v[210:213], v191 offset:1024
	ds_read_b128 v[214:217], v191 offset:2048
	ds_read_b128 v[218:221], v191 offset:3072
	ds_read_b128 v[222:225], v191 offset:4096
	ds_read_b128 v[226:229], v191 offset:5120
	ds_read_b128 v[230:233], v191 offset:6144
	ds_read_b128 v[234:237], v191 offset:7168
	global_load_lds_dwordx4 v[168:169], off
	v_lshl_add_u64 v[168:169], s[10:11], 0, v[160:161]
	s_add_i32 m0, s55, 0xe000
	s_nop 0
	global_load_lds_dwordx4 v[168:169], off
	s_waitcnt vmcnt(8)
	s_waitcnt lgkmcnt(0)
	s_barrier
	s_setprio 1
	s_waitcnt lgkmcnt(0)
	v_mfma_f32_16x16x32_bf16 v[140:143], v[16:19], v[206:209], v[140:143]
	v_mfma_f32_16x16x32_bf16 v[136:139], v[32:35], v[206:209], v[136:139]
	v_mfma_f32_16x16x32_bf16 v[124:127], v[16:19], v[214:217], v[124:127]
	v_mfma_f32_16x16x32_bf16 v[120:123], v[32:35], v[214:217], v[120:123]
	v_mfma_f32_16x16x32_bf16 v[108:111], v[16:19], v[222:225], v[108:111]
	v_mfma_f32_16x16x32_bf16 v[104:107], v[32:35], v[222:225], v[104:107]
	v_mfma_f32_16x16x32_bf16 v[92:95], v[16:19], v[230:233], v[92:95]
	v_mfma_f32_16x16x32_bf16 v[88:91], v[32:35], v[230:233], v[88:91]
	v_mfma_f32_16x16x32_bf16 v[140:143], v[20:23], v[210:213], v[140:143]
	v_mfma_f32_16x16x32_bf16 v[136:139], v[36:39], v[210:213], v[136:139]
	v_mfma_f32_16x16x32_bf16 v[124:127], v[20:23], v[218:221], v[124:127]
	v_mfma_f32_16x16x32_bf16 v[120:123], v[36:39], v[218:221], v[120:123]
	v_mfma_f32_16x16x32_bf16 v[108:111], v[20:23], v[226:229], v[108:111]
	v_mfma_f32_16x16x32_bf16 v[104:107], v[36:39], v[226:229], v[104:107]
	v_mfma_f32_16x16x32_bf16 v[92:95], v[20:23], v[234:237], v[92:95]
	v_mfma_f32_16x16x32_bf16 v[88:91], v[36:39], v[234:237], v[88:91]
	s_setprio 0
	s_setprio 1
	v_mfma_f32_16x16x32_bf16 v[132:135], v[184:187], v[206:209], v[132:135]
	v_mfma_f32_16x16x32_bf16 v[128:131], v[198:201], v[206:209], v[128:131]
	v_mfma_f32_16x16x32_bf16 v[116:119], v[184:187], v[214:217], v[116:119]
	v_mfma_f32_16x16x32_bf16 v[112:115], v[198:201], v[214:217], v[112:115]
	v_mfma_f32_16x16x32_bf16 v[100:103], v[184:187], v[222:225], v[100:103]
	v_mfma_f32_16x16x32_bf16 v[96:99], v[198:201], v[222:225], v[96:99]
	v_mfma_f32_16x16x32_bf16 v[84:87], v[184:187], v[230:233], v[84:87]
	v_mfma_f32_16x16x32_bf16 v[80:83], v[198:201], v[230:233], v[80:83]
	v_mfma_f32_16x16x32_bf16 v[132:135], v[194:197], v[210:213], v[132:135]
	v_mfma_f32_16x16x32_bf16 v[128:131], v[202:205], v[210:213], v[128:131]
	v_mfma_f32_16x16x32_bf16 v[116:119], v[194:197], v[218:221], v[116:119]
	v_mfma_f32_16x16x32_bf16 v[112:115], v[202:205], v[218:221], v[112:115]
	v_mfma_f32_16x16x32_bf16 v[100:103], v[194:197], v[226:229], v[100:103]
	v_mfma_f32_16x16x32_bf16 v[96:99], v[202:205], v[226:229], v[96:99]
	v_mfma_f32_16x16x32_bf16 v[84:87], v[194:197], v[234:237], v[84:87]
	v_mfma_f32_16x16x32_bf16 v[80:83], v[202:205], v[234:237], v[80:83]
	s_setprio 0
	s_barrier
	s_add_i32 s50, s67, s54
	v_lshl_add_u64 v[168:169], s[12:13], 0, v[146:147]
	s_mov_b32 m0, s50
	ds_read_b128 v[206:209], v191 offset:16384
	ds_read_b128 v[210:213], v191 offset:17408
	ds_read_b128 v[214:217], v191 offset:18432
	ds_read_b128 v[218:221], v191 offset:19456
	ds_read_b128 v[222:225], v191 offset:20480
	ds_read_b128 v[226:229], v191 offset:21504
	ds_read_b128 v[230:233], v191 offset:22528
	ds_read_b128 v[234:237], v191 offset:23552
	global_load_lds_dwordx4 v[168:169], off
	s_add_i32 m0, s50, 0x2000
	s_add_u32 s50, s12, 0x40000
	v_lshl_add_u64 v[188:189], s[12:13], 0, v[150:151]
	s_addc_u32 s51, s13, 0
	s_add_i32 s78, s72, s54
	global_load_lds_dwordx4 v[188:189], off
	v_lshl_add_u64 v[238:239], s[50:51], 0, v[146:147]
	s_mov_b32 m0, s78
	v_lshl_add_u64 v[240:241], s[14:15], 0, v[148:149]
	global_load_lds_dwordx4 v[238:239], off
	v_lshl_add_u64 v[238:239], s[50:51], 0, v[150:151]
	s_add_i32 m0, s78, 0x2000
	s_nop 0
	global_load_lds_dwordx4 v[238:239], off
	v_lshl_add_u64 v[238:239], s[14:15], 0, v[144:145]
	s_mov_b32 m0, s55
	s_nop 0
	global_load_lds_dwordx4 v[238:239], off
	s_mov_b32 m0, s58
	s_nop 0
	global_load_lds_dwordx4 v[240:241], off
	s_waitcnt vmcnt(8)
	s_waitcnt lgkmcnt(0)
	s_barrier
; #define PG8_STAGE(bufoff, gbase, voff) do { _Pragma("unroll") for (int _i = 0; _i < 2; ++_i) \
;         __builtin_amdgcn_global_load_lds((const unsigned*)((const char*)(gbase) + (voff)[_i]), (LAS unsigned*)(lds + (bufoff) + ldsw + _i * 8192), 16, 0, 0); } while (0)
; #define PG8_LDA(dst, b, h) do { _Pragma("unroll") for (int m = 0; m < 4; ++m) _Pragma("unroll") for (int k = 0; k < 2; ++k) dst[m][k] = *(const LAS bf16x8*)(lds + PG8_SA(b, h) + aoff + m * 2048 + k * 1024); } while (0)
; #define PG8_LDB(dst, b, h) do { _Pragma("unroll") for (int n = 0; n < 2; ++n) _Pragma("unroll") for (int k = 0; k < 2; ++k) dst[n][k] = *(const LAS bf16x8*)(lds + PG8_SB(b, h) + boff + n * 2048 + k * 1024); } while (0)
; #define PG8_MMA(ai, bj, At, Bt) do { __builtin_amdgcn_s_setprio(1); _Pragma("unroll") for (int m = 0; m < 4; ++m) _Pragma("unroll") for (int n = 0; n < 2; ++n) _Pragma("unroll") for (int k = 0; k < 2; ++k) \
;         acc[ai][bj][m][n] = __builtin_amdgcn_mfma_f32_16x16x32_bf16(Bt[n][k], At[m][k], acc[ai][bj][m][n], 0, 0, 0); __builtin_amdgcn_s_setprio(0); } while (0)
; #define PG8_WAIT_V(n) asm volatile("s_waitcnt vmcnt(" #n ")" ::: "memory")
; #define PG8_WAIT_L(n) asm volatile("s_waitcnt lgkmcnt(" #n ")" ::: "memory")
; #define PG8_BAR __builtin_amdgcn_s_barrier()
; #define PG8_SCHED __builtin_amdgcn_sched_barrier(0)
; template <class Epi, class Sched>
; __device__ __forceinline__ void gemm_phase(LAS unsigned char* lds, const Gemm g, const Sched& S, const Epi& E, int wave_id) {
;     ...
;             PG8_WAIT_V(8); PG8_WAIT_L(0); PG8_BAR; PG8_MMA(1, 0, At, B0); PG8_MMA(1, 1, At, B1); PG8_BAR; PG8_SCHED;
;             PG8_LDB(B0, 1, 0); PG8_LDB(B1, 1, 1); PG8_SCHED; PG8_LDA(At, 1, 0); PG8_STAGE(PG8_SA(0, 1), a2 + hstepA, voffA);
;             PG8_WAIT_V(8); PG8_WAIT_L(0); PG8_BAR; PG8_MMA(0, 0, At, B0); PG8_MMA(0, 1, At, B1); PG8_BAR; PG8_SCHED;
	s_setprio 1
	s_waitcnt lgkmcnt(0)
	v_mfma_f32_16x16x32_bf16 v[76:79], v[16:19], v[206:209], v[76:79]
	v_mfma_f32_16x16x32_bf16 v[72:75], v[32:35], v[206:209], v[72:75]
	v_mfma_f32_16x16x32_bf16 v[60:63], v[16:19], v[214:217], v[60:63]
	v_mfma_f32_16x16x32_bf16 v[56:59], v[32:35], v[214:217], v[56:59]
	v_mfma_f32_16x16x32_bf16 v[44:47], v[16:19], v[222:225], v[44:47]
	v_mfma_f32_16x16x32_bf16 v[40:43], v[32:35], v[222:225], v[40:43]
	v_mfma_f32_16x16x32_bf16 v[12:15], v[16:19], v[230:233], v[12:15]
	v_mfma_f32_16x16x32_bf16 v[8:11], v[32:35], v[230:233], v[8:11]
	v_mfma_f32_16x16x32_bf16 v[76:79], v[20:23], v[210:213], v[76:79]
	v_mfma_f32_16x16x32_bf16 v[72:75], v[36:39], v[210:213], v[72:75]
	v_mfma_f32_16x16x32_bf16 v[60:63], v[20:23], v[218:221], v[60:63]
	v_mfma_f32_16x16x32_bf16 v[56:59], v[36:39], v[218:221], v[56:59]
	v_mfma_f32_16x16x32_bf16 v[44:47], v[20:23], v[226:229], v[44:47]
	v_mfma_f32_16x16x32_bf16 v[40:43], v[36:39], v[226:229], v[40:43]
	v_mfma_f32_16x16x32_bf16 v[12:15], v[20:23], v[234:237], v[12:15]
	v_mfma_f32_16x16x32_bf16 v[8:11], v[36:39], v[234:237], v[8:11]
	s_setprio 0
	s_setprio 1
	v_mfma_f32_16x16x32_bf16 v[28:31], v[184:187], v[222:225], v[28:31]
	v_mfma_f32_16x16x32_bf16 v[24:27], v[198:201], v[222:225], v[24:27]
	v_mfma_f32_16x16x32_bf16 v[4:7], v[184:187], v[230:233], v[4:7]
	v_mfma_f32_16x16x32_bf16 v[0:3], v[198:201], v[230:233], v[0:3]
	v_mfma_f32_16x16x32_bf16 v[16:19], v[184:187], v[206:209], v[68:71]
	v_mfma_f32_16x16x32_bf16 v[20:23], v[198:201], v[206:209], v[64:67]
	v_mfma_f32_16x16x32_bf16 v[32:35], v[184:187], v[214:217], v[52:55]
	v_mfma_f32_16x16x32_bf16 v[36:39], v[198:201], v[214:217], v[48:51]
	v_mfma_f32_16x16x32_bf16 v[28:31], v[194:197], v[226:229], v[28:31]
	v_mfma_f32_16x16x32_bf16 v[24:27], v[202:205], v[226:229], v[24:27]
	v_mfma_f32_16x16x32_bf16 v[4:7], v[194:197], v[234:237], v[4:7]
	v_mfma_f32_16x16x32_bf16 v[0:3], v[202:205], v[234:237], v[0:3]
	v_mfma_f32_16x16x32_bf16 v[16:19], v[194:197], v[210:213], v[16:19]
	v_mfma_f32_16x16x32_bf16 v[20:23], v[202:205], v[210:213], v[20:23]
	v_mfma_f32_16x16x32_bf16 v[32:35], v[194:197], v[218:221], v[32:35]
	v_mfma_f32_16x16x32_bf16 v[36:39], v[202:205], v[218:221], v[36:39]
	s_setprio 0
	s_barrier
	s_add_i32 s50, 0, 0x18000
	s_add_i32 s51, 0, 0x1c000
	v_add_u32_e32 v68, s50, v171
	v_add_u32_e32 v152, s51, v171
	ds_read_b128 v[48:51], v68
	ds_read_b128 v[52:55], v68 offset:1024
	ds_read_b128 v[64:67], v68 offset:2048
	ds_read_b128 v[68:71], v68 offset:3072
	ds_read_b128 v[184:187], v152
	ds_read_b128 v[194:197], v152 offset:1024
	ds_read_b128 v[198:201], v152 offset:2048
	ds_read_b128 v[202:205], v152 offset:3072
	s_add_u32 s14, s14, 0x40000
	s_addc_u32 s15, s15, 0
	s_mov_b32 m0, s59
	v_lshl_add_u64 v[242:243], s[14:15], 0, v[144:145]
	ds_read_b128 v[206:209], v191 offset:32768
	ds_read_b128 v[210:213], v191 offset:33792
	ds_read_b128 v[214:217], v191 offset:34816
	ds_read_b128 v[218:221], v191 offset:35840
	ds_read_b128 v[222:225], v191 offset:36864
	ds_read_b128 v[226:229], v191 offset:37888
	ds_read_b128 v[230:233], v191 offset:38912
	ds_read_b128 v[234:237], v191 offset:39936
	global_load_lds_dwordx4 v[242:243], off
	v_lshl_add_u64 v[242:243], s[14:15], 0, v[148:149]
	s_mov_b32 m0, s60
	s_nop 0
	global_load_lds_dwordx4 v[242:243], off
	s_waitcnt vmcnt(8)
	s_waitcnt lgkmcnt(0)
	s_barrier
	s_setprio 1
	s_waitcnt lgkmcnt(0)
	v_mfma_f32_16x16x32_bf16 v[140:143], v[48:51], v[206:209], v[140:143]
	v_mfma_f32_16x16x32_bf16 v[136:139], v[64:67], v[206:209], v[136:139]
	v_mfma_f32_16x16x32_bf16 v[124:127], v[48:51], v[214:217], v[124:127]
	v_mfma_f32_16x16x32_bf16 v[120:123], v[64:67], v[214:217], v[120:123]
	v_mfma_f32_16x16x32_bf16 v[108:111], v[48:51], v[222:225], v[108:111]
	v_mfma_f32_16x16x32_bf16 v[104:107], v[64:67], v[222:225], v[104:107]
	v_mfma_f32_16x16x32_bf16 v[92:95], v[48:51], v[230:233], v[92:95]
	v_mfma_f32_16x16x32_bf16 v[88:91], v[64:67], v[230:233], v[88:91]
	v_mfma_f32_16x16x32_bf16 v[140:143], v[52:55], v[210:213], v[140:143]
	v_mfma_f32_16x16x32_bf16 v[136:139], v[68:71], v[210:213], v[136:139]
	v_mfma_f32_16x16x32_bf16 v[124:127], v[52:55], v[218:221], v[124:127]
	v_mfma_f32_16x16x32_bf16 v[120:123], v[68:71], v[218:221], v[120:123]
	v_mfma_f32_16x16x32_bf16 v[108:111], v[52:55], v[226:229], v[108:111]
	v_mfma_f32_16x16x32_bf16 v[104:107], v[68:71], v[226:229], v[104:107]
	v_mfma_f32_16x16x32_bf16 v[92:95], v[52:55], v[234:237], v[92:95]
	v_mfma_f32_16x16x32_bf16 v[88:91], v[68:71], v[234:237], v[88:91]
	s_setprio 0
	s_setprio 1
	v_mfma_f32_16x16x32_bf16 v[132:135], v[184:187], v[206:209], v[132:135]
	v_mfma_f32_16x16x32_bf16 v[128:131], v[198:201], v[206:209], v[128:131]
	v_mfma_f32_16x16x32_bf16 v[116:119], v[184:187], v[214:217], v[116:119]
	v_mfma_f32_16x16x32_bf16 v[112:115], v[198:201], v[214:217], v[112:115]
	v_mfma_f32_16x16x32_bf16 v[100:103], v[184:187], v[222:225], v[100:103]
	v_mfma_f32_16x16x32_bf16 v[96:99], v[198:201], v[222:225], v[96:99]
	v_mfma_f32_16x16x32_bf16 v[84:87], v[184:187], v[230:233], v[84:87]
	v_mfma_f32_16x16x32_bf16 v[80:83], v[198:201], v[230:233], v[80:83]
	v_mfma_f32_16x16x32_bf16 v[132:135], v[194:197], v[210:213], v[132:135]
	v_mfma_f32_16x16x32_bf16 v[128:131], v[202:205], v[210:213], v[128:131]
	v_mfma_f32_16x16x32_bf16 v[116:119], v[194:197], v[218:221], v[116:119]
	v_mfma_f32_16x16x32_bf16 v[112:115], v[202:205], v[218:221], v[112:115]
	v_mfma_f32_16x16x32_bf16 v[100:103], v[194:197], v[226:229], v[100:103]
	v_mfma_f32_16x16x32_bf16 v[96:99], v[202:205], v[226:229], v[96:99]
	v_mfma_f32_16x16x32_bf16 v[84:87], v[194:197], v[234:237], v[84:87]
	v_mfma_f32_16x16x32_bf16 v[80:83], v[202:205], v[234:237], v[80:83]
	s_setprio 0
	s_barrier
; #define PG8_STAGE(bufoff, gbase, voff) do { _Pragma("unroll") for (int _i = 0; _i < 2; ++_i) \
;         __builtin_amdgcn_global_load_lds((const unsigned*)((const char*)(gbase) + (voff)[_i]), (LAS unsigned*)(lds + (bufoff) + ldsw + _i * 8192), 16, 0, 0); } while (0)
; #define PG8_LDA(dst, b, h) do { _Pragma("unroll") for (int m = 0; m < 4; ++m) _Pragma("unroll") for (int k = 0; k < 2; ++k) dst[m][k] = *(const LAS bf16x8*)(lds + PG8_SA(b, h) + aoff + m * 2048 + k * 1024); } while (0)
; #define PG8_MMA(ai, bj, At, Bt) do { __builtin_amdgcn_s_setprio(1); _Pragma("unroll") for (int m = 0; m < 4; ++m) _Pragma("unroll") for (int n = 0; n < 2; ++n) _Pragma("unroll") for (int k = 0; k < 2; ++k) \
;         acc[ai][bj][m][n] = __builtin_amdgcn_mfma_f32_16x16x32_bf16(Bt[n][k], At[m][k], acc[ai][bj][m][n], 0, 0, 0); __builtin_amdgcn_s_setprio(0); } while (0)
; #define PG8_WAIT_V(n) asm volatile("s_waitcnt vmcnt(" #n ")" ::: "memory")
; #define PG8_WAIT_L(n) asm volatile("s_waitcnt lgkmcnt(" #n ")" ::: "memory")
; #define PG8_BAR __builtin_amdgcn_s_barrier()
; #define PG8_SCHED __builtin_amdgcn_sched_barrier(0)
; template <class Epi, class Sched>
; __device__ __forceinline__ void gemm_phase(LAS unsigned char* lds, const Gemm g, const Sched& S, const Epi& E, int wave_id) {
;     ...
;             PG8_LDA(At, 1, 1); PG8_STAGE(PG8_SB(1, 0), b3, voffB); PG8_STAGE(PG8_SB(1, 1), b3 + hstepB, voffB); PG8_STAGE(PG8_SA(1, 0), a3, voffA);
;             PG8_WAIT_V(8); PG8_WAIT_L(0); PG8_BAR; PG8_MMA(1, 0, At, B0); PG8_MMA(1, 1, At, B1); PG8_BAR; PG8_SCHED;
;         }
	s_add_i32 s14, s50, s54
	v_lshl_add_u64 v[168:169], v[168:169], 0, s[22:23]
	s_mov_b32 m0, s14
	ds_read_b128 v[206:209], v191 offset:49152
	ds_read_b128 v[210:213], v191 offset:50176
	ds_read_b128 v[214:217], v191 offset:51200
	ds_read_b128 v[218:221], v191 offset:52224
	ds_read_b128 v[222:225], v191 offset:53248
	ds_read_b128 v[226:229], v191 offset:54272
	ds_read_b128 v[230:233], v191 offset:55296
	ds_read_b128 v[234:237], v191 offset:56320
	global_load_lds_dwordx4 v[168:169], off
	s_add_i32 m0, s14, 0x2000
	s_add_u32 s12, s12, 0x40080
	v_lshl_add_u64 v[168:169], v[188:189], 0, s[22:23]
	s_addc_u32 s13, s13, 0
	s_add_i32 s14, s51, s54
	global_load_lds_dwordx4 v[168:169], off
	v_lshl_add_u64 v[168:169], s[12:13], 0, v[146:147]
	s_mov_b32 m0, s14
	s_nop 0
	global_load_lds_dwordx4 v[168:169], off
	v_lshl_add_u64 v[168:169], s[12:13], 0, v[150:151]
	s_add_i32 m0, s14, 0x2000
	s_nop 0
	global_load_lds_dwordx4 v[168:169], off
	v_lshl_add_u64 v[168:169], v[238:239], 0, s[22:23]
	s_mov_b32 m0, s62
	s_nop 0
	global_load_lds_dwordx4 v[168:169], off
	v_lshl_add_u64 v[168:169], v[240:241], 0, s[22:23]
	s_mov_b32 m0, s63
	s_nop 0
	global_load_lds_dwordx4 v[168:169], off
	s_waitcnt vmcnt(8)
	s_waitcnt lgkmcnt(0)
	s_barrier
	s_setprio 1
	s_waitcnt lgkmcnt(0)
	v_mfma_f32_16x16x32_bf16 v[76:79], v[48:51], v[206:209], v[76:79]
	v_mfma_f32_16x16x32_bf16 v[72:75], v[64:67], v[206:209], v[72:75]
	v_mfma_f32_16x16x32_bf16 v[60:63], v[48:51], v[214:217], v[60:63]
	v_mfma_f32_16x16x32_bf16 v[56:59], v[64:67], v[214:217], v[56:59]
	v_mfma_f32_16x16x32_bf16 v[44:47], v[48:51], v[222:225], v[44:47]
	v_mfma_f32_16x16x32_bf16 v[40:43], v[64:67], v[222:225], v[40:43]
	v_mfma_f32_16x16x32_bf16 v[12:15], v[48:51], v[230:233], v[12:15]
	v_mfma_f32_16x16x32_bf16 v[8:11], v[64:67], v[230:233], v[8:11]
	v_mfma_f32_16x16x32_bf16 v[76:79], v[52:55], v[210:213], v[76:79]
	v_mfma_f32_16x16x32_bf16 v[72:75], v[68:71], v[210:213], v[72:75]
	v_mfma_f32_16x16x32_bf16 v[60:63], v[52:55], v[218:221], v[60:63]
	v_mfma_f32_16x16x32_bf16 v[56:59], v[68:71], v[218:221], v[56:59]
	v_mfma_f32_16x16x32_bf16 v[44:47], v[52:55], v[226:229], v[44:47]
	v_mfma_f32_16x16x32_bf16 v[40:43], v[68:71], v[226:229], v[40:43]
	v_mfma_f32_16x16x32_bf16 v[12:15], v[52:55], v[234:237], v[12:15]
	v_mfma_f32_16x16x32_bf16 v[8:11], v[68:71], v[234:237], v[8:11]
	s_setprio 0
	s_setprio 1
	v_mfma_f32_16x16x32_bf16 v[16:19], v[184:187], v[206:209], v[16:19]
	v_mfma_f32_16x16x32_bf16 v[68:71], v[194:197], v[210:213], v[16:19]
	v_mfma_f32_16x16x32_bf16 v[16:19], v[198:201], v[206:209], v[20:23]
	v_mfma_f32_16x16x32_bf16 v[64:67], v[202:205], v[210:213], v[16:19]
	v_mfma_f32_16x16x32_bf16 v[16:19], v[184:187], v[214:217], v[32:35]
	v_mfma_f32_16x16x32_bf16 v[52:55], v[194:197], v[218:221], v[16:19]
	v_mfma_f32_16x16x32_bf16 v[16:19], v[198:201], v[214:217], v[36:39]
	v_mfma_f32_16x16x32_bf16 v[48:51], v[202:205], v[218:221], v[16:19]
	v_mfma_f32_16x16x32_bf16 v[16:19], v[184:187], v[222:225], v[28:31]
	v_mfma_f32_16x16x32_bf16 v[28:31], v[194:197], v[226:229], v[16:19]
	v_mfma_f32_16x16x32_bf16 v[16:19], v[198:201], v[222:225], v[24:27]
	v_mfma_f32_16x16x32_bf16 v[4:7], v[184:187], v[230:233], v[4:7]
	v_mfma_f32_16x16x32_bf16 v[0:3], v[198:201], v[230:233], v[0:3]
	v_mfma_f32_16x16x32_bf16 v[24:27], v[202:205], v[226:229], v[16:19]
	v_mfma_f32_16x16x32_bf16 v[4:7], v[194:197], v[234:237], v[4:7]
	v_mfma_f32_16x16x32_bf16 v[0:3], v[202:205], v[234:237], v[0:3]
	s_setprio 0
	s_add_i32 s45, s45, 2
	s_add_u32 s10, s10, 0x100
	s_addc_u32 s11, s11, 0
	s_add_u32 s33, s33, 0x100
	s_addc_u32 s39, s39, 0
	s_cmp_gt_u32 s45, 13
	s_barrier
	s_cbranch_scc0 .LBB0_252
	s_and_b64 vcc, exec, s[24:25]
	s_cbranch_vccz .LBB0_255
	s_barrier

; #define PG8_STAGE(bufoff, gbase, voff) do { _Pragma("unroll") for (int _i = 0; _i < 2; ++_i) \
;         __builtin_amdgcn_global_load_lds((const unsigned*)((const char*)(gbase) + (voff)[_i]), (LAS unsigned*)(lds + (bufoff) + ldsw + _i * 8192), 16, 0, 0); } while (0)
; #define PG8_LDA(dst, b, h) do { _Pragma("unroll") for (int m = 0; m < 4; ++m) _Pragma("unroll") for (int k = 0; k < 2; ++k) dst[m][k] = *(const LAS bf16x8*)(lds + PG8_SA(b, h) + aoff + m * 2048 + k * 1024); } while (0)
; #define PG8_LDB(dst, b, h) do { _Pragma("unroll") for (int n = 0; n < 2; ++n) _Pragma("unroll") for (int k = 0; k < 2; ++k) dst[n][k] = *(const LAS bf16x8*)(lds + PG8_SB(b, h) + boff + n * 2048 + k * 1024); } while (0)
; #define PG8_MMA(ai, bj, At, Bt) do { __builtin_amdgcn_s_setprio(1); _Pragma("unroll") for (int m = 0; m < 4; ++m) _Pragma("unroll") for (int n = 0; n < 2; ++n) _Pragma("unroll") for (int k = 0; k < 2; ++k) \
;         acc[ai][bj][m][n] = __builtin_amdgcn_mfma_f32_16x16x32_bf16(Bt[n][k], At[m][k], acc[ai][bj][m][n], 0, 0, 0); __builtin_amdgcn_s_setprio(0); } while (0)
; #define PG8_WAIT_V(n) asm volatile("s_waitcnt vmcnt(" #n ")" ::: "memory")
; #define PG8_WAIT_L(n) asm volatile("s_waitcnt lgkmcnt(" #n ")" ::: "memory")
; #define PG8_BAR __builtin_amdgcn_s_barrier()
; #define PG8_SCHED __builtin_amdgcn_sched_barrier(0)
; template <class Epi, class Sched>
; __device__ __forceinline__ void gemm_phase(LAS unsigned char* lds, const Gemm g, const Sched& S, const Epi& E, int wave_id) {
;     ...
;         for (int t = 0; t < nt; t += 2) {
;             const bool last = (t == nt - 2);
;             const char* a1 = cA + (size_t)(t + 1) * kstep;
;             const char* a2 = last ? nA : cA + (size_t)(t + 2) * kstep; const char* b2 = last ? nB : cB + (size_t)(t + 2) * kstep;
;             const char* a3 = a2 + kstep; const char* b3 = b2 + kstep;
;             PG8_LDB(B0, 0, 0); PG8_LDB(B1, 0, 1); PG8_SCHED; PG8_LDA(At, 0, 0); PG8_STAGE(PG8_SA(1, 1), a1 + hstepA, voffA);
;             PG8_WAIT_V(8); PG8_WAIT_L(0); PG8_BAR; PG8_MMA(0, 0, At, B0); PG8_MMA(0, 1, At, B1); PG8_BAR; PG8_SCHED;
;             PG8_LDA(At, 0, 1); PG8_STAGE(PG8_SB(0, 0), b2, voffB); PG8_STAGE(PG8_SB(0, 1), b2 + hstepB, voffB); PG8_STAGE(PG8_SA(0, 0), a2, voffA);
;             PG8_WAIT_V(8); PG8_WAIT_L(0); PG8_BAR; PG8_MMA(1, 0, At, B0); PG8_MMA(1, 1, At, B1); PG8_BAR; PG8_SCHED;
.LBB0_673:
	ds_read_b128 v[142:145], v161
	ds_read_b128 v[146:149], v161 offset:1024
	ds_read_b128 v[150:153], v161 offset:2048
	ds_read_b128 v[154:157], v161 offset:3072
	ds_read_b128 v[164:167], v162
	ds_read_b128 v[168:171], v162 offset:1024
	ds_read_b128 v[172:175], v162 offset:2048
	ds_read_b128 v[176:179], v162 offset:3072
	s_add_u32 s36, s34, 0xfffc0080
	s_addc_u32 s37, s35, -1
	s_cmp_eq_u32 s65, 12
	s_cselect_b32 s39, s23, s37
	s_cselect_b32 s38, s61, s36
	s_cselect_b32 s37, s17, s64
	s_cselect_b32 s36, s62, s63
	v_lshl_add_u64 v[212:213], s[34:35], 0, v[136:137]
	s_add_i32 m0, s31, 0xc000
	ds_read_b128 v[180:183], v163
	ds_read_b128 v[184:187], v163 offset:1024
	ds_read_b128 v[188:191], v163 offset:2048
	ds_read_b128 v[192:195], v163 offset:3072
	ds_read_b128 v[196:199], v163 offset:4096
	ds_read_b128 v[200:203], v163 offset:5120
	ds_read_b128 v[204:207], v163 offset:6144
	ds_read_b128 v[208:211], v163 offset:7168
	global_load_lds_dwordx4 v[212:213], off
	v_lshl_add_u64 v[212:213], s[34:35], 0, v[138:139]
	s_add_i32 m0, s31, 0xe000
	s_nop 0
	global_load_lds_dwordx4 v[212:213], off
	s_waitcnt vmcnt(8)
	s_waitcnt lgkmcnt(0)
	s_barrier
	s_setprio 1
	s_waitcnt lgkmcnt(0)
	v_mfma_f32_16x16x32_bf16 v[124:127], v[142:145], v[180:183], v[124:127]
	v_mfma_f32_16x16x32_bf16 v[120:123], v[150:153], v[180:183], v[120:123]
	v_mfma_f32_16x16x32_bf16 v[108:111], v[142:145], v[188:191], v[108:111]
	v_mfma_f32_16x16x32_bf16 v[104:107], v[150:153], v[188:191], v[104:107]
	v_mfma_f32_16x16x32_bf16 v[92:95], v[142:145], v[196:199], v[92:95]
	v_mfma_f32_16x16x32_bf16 v[88:91], v[150:153], v[196:199], v[88:91]
	v_mfma_f32_16x16x32_bf16 v[76:79], v[142:145], v[204:207], v[76:79]
	v_mfma_f32_16x16x32_bf16 v[72:75], v[150:153], v[204:207], v[72:75]
	v_mfma_f32_16x16x32_bf16 v[124:127], v[146:149], v[184:187], v[124:127]
	v_mfma_f32_16x16x32_bf16 v[120:123], v[154:157], v[184:187], v[120:123]
	v_mfma_f32_16x16x32_bf16 v[108:111], v[146:149], v[192:195], v[108:111]
	v_mfma_f32_16x16x32_bf16 v[104:107], v[154:157], v[192:195], v[104:107]
	v_mfma_f32_16x16x32_bf16 v[92:95], v[146:149], v[200:203], v[92:95]
	v_mfma_f32_16x16x32_bf16 v[88:91], v[154:157], v[200:203], v[88:91]
	v_mfma_f32_16x16x32_bf16 v[76:79], v[146:149], v[208:211], v[76:79]
	v_mfma_f32_16x16x32_bf16 v[72:75], v[154:157], v[208:211], v[72:75]
	s_setprio 0
	s_setprio 1
	v_mfma_f32_16x16x32_bf16 v[116:119], v[164:167], v[180:183], v[116:119]
	v_mfma_f32_16x16x32_bf16 v[112:115], v[172:175], v[180:183], v[112:115]
	v_mfma_f32_16x16x32_bf16 v[100:103], v[164:167], v[188:191], v[100:103]
	v_mfma_f32_16x16x32_bf16 v[96:99], v[172:175], v[188:191], v[96:99]
	v_mfma_f32_16x16x32_bf16 v[84:87], v[164:167], v[196:199], v[84:87]
	v_mfma_f32_16x16x32_bf16 v[80:83], v[172:175], v[196:199], v[80:83]
	v_mfma_f32_16x16x32_bf16 v[68:71], v[164:167], v[204:207], v[68:71]
	v_mfma_f32_16x16x32_bf16 v[64:67], v[172:175], v[204:207], v[64:67]
	v_mfma_f32_16x16x32_bf16 v[116:119], v[168:171], v[184:187], v[116:119]
	v_mfma_f32_16x16x32_bf16 v[112:115], v[176:179], v[184:187], v[112:115]
	v_mfma_f32_16x16x32_bf16 v[100:103], v[168:171], v[192:195], v[100:103]
	v_mfma_f32_16x16x32_bf16 v[96:99], v[176:179], v[192:195], v[96:99]
	v_mfma_f32_16x16x32_bf16 v[84:87], v[168:171], v[200:203], v[84:87]
	v_mfma_f32_16x16x32_bf16 v[80:83], v[176:179], v[200:203], v[80:83]
	v_mfma_f32_16x16x32_bf16 v[68:71], v[168:171], v[208:211], v[68:71]
	v_mfma_f32_16x16x32_bf16 v[64:67], v[176:179], v[208:211], v[64:67]
	s_setprio 0
	s_barrier
	s_add_i32 s66, s55, s46
	v_lshl_add_u64 v[212:213], s[36:37], 0, v[130:131]
	s_mov_b32 m0, s66
	ds_read_b128 v[180:183], v163 offset:16384
	ds_read_b128 v[184:187], v163 offset:17408
	ds_read_b128 v[188:191], v163 offset:18432
	ds_read_b128 v[192:195], v163 offset:19456
	ds_read_b128 v[196:199], v163 offset:20480
	ds_read_b128 v[200:203], v163 offset:21504
	ds_read_b128 v[204:207], v163 offset:22528
	ds_read_b128 v[208:211], v163 offset:23552
	global_load_lds_dwordx4 v[212:213], off
	s_add_i32 m0, s66, 0x2000
	s_add_u32 s66, s36, 0x40000
	v_lshl_add_u64 v[214:215], s[36:37], 0, v[134:135]
	s_addc_u32 s67, s37, 0
	s_add_i32 s72, s58, s46
	global_load_lds_dwordx4 v[214:215], off
	v_lshl_add_u64 v[216:217], s[66:67], 0, v[130:131]
	s_mov_b32 m0, s72
	v_lshl_add_u64 v[218:219], s[38:39], 0, v[132:133]
	global_load_lds_dwordx4 v[216:217], off
	v_lshl_add_u64 v[216:217], s[66:67], 0, v[134:135]
	s_add_i32 m0, s72, 0x2000
	s_nop 0
	global_load_lds_dwordx4 v[216:217], off
	v_lshl_add_u64 v[216:217], s[38:39], 0, v[128:129]
	s_mov_b32 m0, s31
	s_nop 0
	global_load_lds_dwordx4 v[216:217], off
	s_mov_b32 m0, s47
	s_nop 0
	global_load_lds_dwordx4 v[218:219], off
	s_waitcnt vmcnt(8)
	s_waitcnt lgkmcnt(0)
	s_barrier
; #define PG8_STAGE(bufoff, gbase, voff) do { _Pragma("unroll") for (int _i = 0; _i < 2; ++_i) \
;         __builtin_amdgcn_global_load_lds((const unsigned*)((const char*)(gbase) + (voff)[_i]), (LAS unsigned*)(lds + (bufoff) + ldsw + _i * 8192), 16, 0, 0); } while (0)
; #define PG8_LDA(dst, b, h) do { _Pragma("unroll") for (int m = 0; m < 4; ++m) _Pragma("unroll") for (int k = 0; k < 2; ++k) dst[m][k] = *(const LAS bf16x8*)(lds + PG8_SA(b, h) + aoff + m * 2048 + k * 1024); } while (0)
; #define PG8_LDB(dst, b, h) do { _Pragma("unroll") for (int n = 0; n < 2; ++n) _Pragma("unroll") for (int k = 0; k < 2; ++k) dst[n][k] = *(const LAS bf16x8*)(lds + PG8_SB(b, h) + boff + n * 2048 + k * 1024); } while (0)
; #define PG8_MMA(ai, bj, At, Bt) do { __builtin_amdgcn_s_setprio(1); _Pragma("unroll") for (int m = 0; m < 4; ++m) _Pragma("unroll") for (int n = 0; n < 2; ++n) _Pragma("unroll") for (int k = 0; k < 2; ++k) \
;         acc[ai][bj][m][n] = __builtin_amdgcn_mfma_f32_16x16x32_bf16(Bt[n][k], At[m][k], acc[ai][bj][m][n], 0, 0, 0); __builtin_amdgcn_s_setprio(0); } while (0)
; #define PG8_WAIT_V(n) asm volatile("s_waitcnt vmcnt(" #n ")" ::: "memory")
; #define PG8_WAIT_L(n) asm volatile("s_waitcnt lgkmcnt(" #n ")" ::: "memory")
; #define PG8_BAR __builtin_amdgcn_s_barrier()
; #define PG8_SCHED __builtin_amdgcn_sched_barrier(0)
; template <class Epi, class Sched>
; __device__ __forceinline__ void gemm_phase(LAS unsigned char* lds, const Gemm g, const Sched& S, const Epi& E, int wave_id) {
;     ...
;             PG8_WAIT_V(8); PG8_WAIT_L(0); PG8_BAR; PG8_MMA(1, 0, At, B0); PG8_MMA(1, 1, At, B1); PG8_BAR; PG8_SCHED;
;             PG8_LDB(B0, 1, 0); PG8_LDB(B1, 1, 1); PG8_SCHED; PG8_LDA(At, 1, 0); PG8_STAGE(PG8_SA(0, 1), a2 + hstepA, voffA);
;             PG8_WAIT_V(8); PG8_WAIT_L(0); PG8_BAR; PG8_MMA(0, 0, At, B0); PG8_MMA(0, 1, At, B1); PG8_BAR; PG8_SCHED;
	s_setprio 1
	s_waitcnt lgkmcnt(0)
	v_mfma_f32_16x16x32_bf16 v[60:63], v[142:145], v[180:183], v[60:63]
	v_mfma_f32_16x16x32_bf16 v[56:59], v[150:153], v[180:183], v[56:59]
	v_mfma_f32_16x16x32_bf16 v[44:47], v[142:145], v[188:191], v[44:47]
	v_mfma_f32_16x16x32_bf16 v[40:43], v[150:153], v[188:191], v[40:43]
	v_mfma_f32_16x16x32_bf16 v[28:31], v[142:145], v[196:199], v[28:31]
	v_mfma_f32_16x16x32_bf16 v[24:27], v[150:153], v[196:199], v[24:27]
	v_mfma_f32_16x16x32_bf16 v[12:15], v[142:145], v[204:207], v[12:15]
	v_mfma_f32_16x16x32_bf16 v[8:11], v[150:153], v[204:207], v[8:11]
	v_mfma_f32_16x16x32_bf16 v[60:63], v[146:149], v[184:187], v[60:63]
	v_mfma_f32_16x16x32_bf16 v[56:59], v[154:157], v[184:187], v[56:59]
	v_mfma_f32_16x16x32_bf16 v[44:47], v[146:149], v[192:195], v[44:47]
	v_mfma_f32_16x16x32_bf16 v[40:43], v[154:157], v[192:195], v[40:43]
	v_mfma_f32_16x16x32_bf16 v[28:31], v[146:149], v[200:203], v[28:31]
	v_mfma_f32_16x16x32_bf16 v[24:27], v[154:157], v[200:203], v[24:27]
	v_mfma_f32_16x16x32_bf16 v[12:15], v[146:149], v[208:211], v[12:15]
	v_mfma_f32_16x16x32_bf16 v[8:11], v[154:157], v[208:211], v[8:11]
	s_setprio 0
	s_setprio 1
	v_mfma_f32_16x16x32_bf16 v[52:55], v[164:167], v[180:183], v[52:55]
	v_mfma_f32_16x16x32_bf16 v[48:51], v[172:175], v[180:183], v[48:51]
	v_mfma_f32_16x16x32_bf16 v[36:39], v[164:167], v[188:191], v[36:39]
	v_mfma_f32_16x16x32_bf16 v[32:35], v[172:175], v[188:191], v[32:35]
	v_mfma_f32_16x16x32_bf16 v[20:23], v[164:167], v[196:199], v[20:23]
	v_mfma_f32_16x16x32_bf16 v[16:19], v[172:175], v[196:199], v[16:19]
	v_mfma_f32_16x16x32_bf16 v[4:7], v[164:167], v[204:207], v[4:7]
	v_mfma_f32_16x16x32_bf16 v[0:3], v[172:175], v[204:207], v[0:3]
	v_mfma_f32_16x16x32_bf16 v[52:55], v[168:171], v[184:187], v[52:55]
	v_mfma_f32_16x16x32_bf16 v[48:51], v[176:179], v[184:187], v[48:51]
	v_mfma_f32_16x16x32_bf16 v[36:39], v[168:171], v[192:195], v[36:39]
	v_mfma_f32_16x16x32_bf16 v[32:35], v[176:179], v[192:195], v[32:35]
	v_mfma_f32_16x16x32_bf16 v[20:23], v[168:171], v[200:203], v[20:23]
	v_mfma_f32_16x16x32_bf16 v[16:19], v[176:179], v[200:203], v[16:19]
	v_mfma_f32_16x16x32_bf16 v[4:7], v[168:171], v[208:211], v[4:7]
	v_mfma_f32_16x16x32_bf16 v[0:3], v[176:179], v[208:211], v[0:3]
	s_setprio 0
	s_barrier
	s_add_i32 s66, 0, 0x18000
	s_add_i32 s67, 0, 0x1c000
	v_add_u32_e32 v154, s66, v159
	v_add_u32_e32 v176, s67, v159
	ds_read_b128 v[142:145], v154
	ds_read_b128 v[146:149], v154 offset:1024
	ds_read_b128 v[150:153], v154 offset:2048
	ds_read_b128 v[154:157], v154 offset:3072
	ds_read_b128 v[164:167], v176
	ds_read_b128 v[168:171], v176 offset:1024
	ds_read_b128 v[172:175], v176 offset:2048
	ds_read_b128 v[176:179], v176 offset:3072
	s_add_u32 s38, s38, 0x40000
	s_addc_u32 s39, s39, 0
	s_mov_b32 m0, s48
	v_lshl_add_u64 v[220:221], s[38:39], 0, v[128:129]
	ds_read_b128 v[180:183], v163 offset:32768
	ds_read_b128 v[184:187], v163 offset:33792
	ds_read_b128 v[188:191], v163 offset:34816
	ds_read_b128 v[192:195], v163 offset:35840
	ds_read_b128 v[196:199], v163 offset:36864
	ds_read_b128 v[200:203], v163 offset:37888
	ds_read_b128 v[204:207], v163 offset:38912
	ds_read_b128 v[208:211], v163 offset:39936
	global_load_lds_dwordx4 v[220:221], off
	v_lshl_add_u64 v[220:221], s[38:39], 0, v[132:133]
	s_mov_b32 m0, s49
	s_nop 0
	global_load_lds_dwordx4 v[220:221], off
	s_waitcnt vmcnt(8)
	s_waitcnt lgkmcnt(0)
	s_barrier
	s_setprio 1
	s_waitcnt lgkmcnt(0)
	v_mfma_f32_16x16x32_bf16 v[124:127], v[142:145], v[180:183], v[124:127]
	v_mfma_f32_16x16x32_bf16 v[120:123], v[150:153], v[180:183], v[120:123]
	v_mfma_f32_16x16x32_bf16 v[108:111], v[142:145], v[188:191], v[108:111]
	v_mfma_f32_16x16x32_bf16 v[104:107], v[150:153], v[188:191], v[104:107]
	v_mfma_f32_16x16x32_bf16 v[92:95], v[142:145], v[196:199], v[92:95]
	v_mfma_f32_16x16x32_bf16 v[88:91], v[150:153], v[196:199], v[88:91]
	v_mfma_f32_16x16x32_bf16 v[76:79], v[142:145], v[204:207], v[76:79]
	v_mfma_f32_16x16x32_bf16 v[72:75], v[150:153], v[204:207], v[72:75]
	v_mfma_f32_16x16x32_bf16 v[124:127], v[146:149], v[184:187], v[124:127]
	v_mfma_f32_16x16x32_bf16 v[120:123], v[154:157], v[184:187], v[120:123]
	v_mfma_f32_16x16x32_bf16 v[108:111], v[146:149], v[192:195], v[108:111]
	v_mfma_f32_16x16x32_bf16 v[104:107], v[154:157], v[192:195], v[104:107]
	v_mfma_f32_16x16x32_bf16 v[92:95], v[146:149], v[200:203], v[92:95]
	v_mfma_f32_16x16x32_bf16 v[88:91], v[154:157], v[200:203], v[88:91]
	v_mfma_f32_16x16x32_bf16 v[76:79], v[146:149], v[208:211], v[76:79]
	v_mfma_f32_16x16x32_bf16 v[72:75], v[154:157], v[208:211], v[72:75]
	s_setprio 0
	s_setprio 1
	v_mfma_f32_16x16x32_bf16 v[116:119], v[164:167], v[180:183], v[116:119]
	v_mfma_f32_16x16x32_bf16 v[112:115], v[172:175], v[180:183], v[112:115]
	v_mfma_f32_16x16x32_bf16 v[100:103], v[164:167], v[188:191], v[100:103]
	v_mfma_f32_16x16x32_bf16 v[96:99], v[172:175], v[188:191], v[96:99]
	v_mfma_f32_16x16x32_bf16 v[84:87], v[164:167], v[196:199], v[84:87]
	v_mfma_f32_16x16x32_bf16 v[80:83], v[172:175], v[196:199], v[80:83]
	v_mfma_f32_16x16x32_bf16 v[68:71], v[164:167], v[204:207], v[68:71]
	v_mfma_f32_16x16x32_bf16 v[64:67], v[172:175], v[204:207], v[64:67]
	v_mfma_f32_16x16x32_bf16 v[116:119], v[168:171], v[184:187], v[116:119]
	v_mfma_f32_16x16x32_bf16 v[112:115], v[176:179], v[184:187], v[112:115]
	v_mfma_f32_16x16x32_bf16 v[100:103], v[168:171], v[192:195], v[100:103]
	v_mfma_f32_16x16x32_bf16 v[96:99], v[176:179], v[192:195], v[96:99]
	v_mfma_f32_16x16x32_bf16 v[84:87], v[168:171], v[200:203], v[84:87]
	v_mfma_f32_16x16x32_bf16 v[80:83], v[176:179], v[200:203], v[80:83]
	v_mfma_f32_16x16x32_bf16 v[68:71], v[168:171], v[208:211], v[68:71]
	v_mfma_f32_16x16x32_bf16 v[64:67], v[176:179], v[208:211], v[64:67]
	s_setprio 0
	s_barrier
; #define PG8_STAGE(bufoff, gbase, voff) do { _Pragma("unroll") for (int _i = 0; _i < 2; ++_i) \
;         __builtin_amdgcn_global_load_lds((const unsigned*)((const char*)(gbase) + (voff)[_i]), (LAS unsigned*)(lds + (bufoff) + ldsw + _i * 8192), 16, 0, 0); } while (0)
; #define PG8_LDA(dst, b, h) do { _Pragma("unroll") for (int m = 0; m < 4; ++m) _Pragma("unroll") for (int k = 0; k < 2; ++k) dst[m][k] = *(const LAS bf16x8*)(lds + PG8_SA(b, h) + aoff + m * 2048 + k * 1024); } while (0)
; #define PG8_MMA(ai, bj, At, Bt) do { __builtin_amdgcn_s_setprio(1); _Pragma("unroll") for (int m = 0; m < 4; ++m) _Pragma("unroll") for (int n = 0; n < 2; ++n) _Pragma("unroll") for (int k = 0; k < 2; ++k) \
;         acc[ai][bj][m][n] = __builtin_amdgcn_mfma_f32_16x16x32_bf16(Bt[n][k], At[m][k], acc[ai][bj][m][n], 0, 0, 0); __builtin_amdgcn_s_setprio(0); } while (0)
; #define PG8_WAIT_V(n) asm volatile("s_waitcnt vmcnt(" #n ")" ::: "memory")
; #define PG8_WAIT_L(n) asm volatile("s_waitcnt lgkmcnt(" #n ")" ::: "memory")
; #define PG8_BAR __builtin_amdgcn_s_barrier()
; #define PG8_SCHED __builtin_amdgcn_sched_barrier(0)
; template <class Epi, class Sched>
; __device__ __forceinline__ void gemm_phase(LAS unsigned char* lds, const Gemm g, const Sched& S, const Epi& E, int wave_id) {
;     ...
;             PG8_LDA(At, 1, 1); PG8_STAGE(PG8_SB(1, 0), b3, voffB); PG8_STAGE(PG8_SB(1, 1), b3 + hstepB, voffB); PG8_STAGE(PG8_SA(1, 0), a3, voffA);
;             PG8_WAIT_V(8); PG8_WAIT_L(0); PG8_BAR; PG8_MMA(1, 0, At, B0); PG8_MMA(1, 1, At, B1); PG8_BAR; PG8_SCHED;
;         }
	s_add_i32 s38, s66, s46
	v_lshl_add_u64 v[212:213], v[212:213], 0, s[6:7]
	s_mov_b32 m0, s38
	ds_read_b128 v[180:183], v163 offset:49152
	ds_read_b128 v[184:187], v163 offset:50176
	ds_read_b128 v[188:191], v163 offset:51200
	ds_read_b128 v[192:195], v163 offset:52224
	ds_read_b128 v[196:199], v163 offset:53248
	ds_read_b128 v[200:203], v163 offset:54272
	ds_read_b128 v[204:207], v163 offset:55296
	ds_read_b128 v[208:211], v163 offset:56320
	global_load_lds_dwordx4 v[212:213], off
	s_add_i32 m0, s38, 0x2000
	s_add_u32 s36, s36, 0x40080
	v_lshl_add_u64 v[212:213], v[214:215], 0, s[6:7]
	s_addc_u32 s37, s37, 0
	s_add_i32 s38, s67, s46
	global_load_lds_dwordx4 v[212:213], off
	v_lshl_add_u64 v[212:213], s[36:37], 0, v[130:131]
	s_mov_b32 m0, s38
	s_nop 0
	global_load_lds_dwordx4 v[212:213], off
	v_lshl_add_u64 v[212:213], s[36:37], 0, v[134:135]
	s_add_i32 m0, s38, 0x2000
	s_nop 0
	global_load_lds_dwordx4 v[212:213], off
	v_lshl_add_u64 v[212:213], v[216:217], 0, s[6:7]
	s_mov_b32 m0, s52
	s_nop 0
	global_load_lds_dwordx4 v[212:213], off
	v_lshl_add_u64 v[212:213], v[218:219], 0, s[6:7]
	s_mov_b32 m0, s53
	s_nop 0
	global_load_lds_dwordx4 v[212:213], off
	s_waitcnt vmcnt(8)
	s_waitcnt lgkmcnt(0)
	s_barrier
	s_setprio 1
	s_waitcnt lgkmcnt(0)
	v_mfma_f32_16x16x32_bf16 v[60:63], v[142:145], v[180:183], v[60:63]
	v_mfma_f32_16x16x32_bf16 v[56:59], v[150:153], v[180:183], v[56:59]
	v_mfma_f32_16x16x32_bf16 v[44:47], v[142:145], v[188:191], v[44:47]
	v_mfma_f32_16x16x32_bf16 v[40:43], v[150:153], v[188:191], v[40:43]
	v_mfma_f32_16x16x32_bf16 v[28:31], v[142:145], v[196:199], v[28:31]
	v_mfma_f32_16x16x32_bf16 v[24:27], v[150:153], v[196:199], v[24:27]
	v_mfma_f32_16x16x32_bf16 v[12:15], v[142:145], v[204:207], v[12:15]
	v_mfma_f32_16x16x32_bf16 v[8:11], v[150:153], v[204:207], v[8:11]
	v_mfma_f32_16x16x32_bf16 v[60:63], v[146:149], v[184:187], v[60:63]
	v_mfma_f32_16x16x32_bf16 v[56:59], v[154:157], v[184:187], v[56:59]
	v_mfma_f32_16x16x32_bf16 v[44:47], v[146:149], v[192:195], v[44:47]
	v_mfma_f32_16x16x32_bf16 v[40:43], v[154:157], v[192:195], v[40:43]
	v_mfma_f32_16x16x32_bf16 v[28:31], v[146:149], v[200:203], v[28:31]
	v_mfma_f32_16x16x32_bf16 v[24:27], v[154:157], v[200:203], v[24:27]
	v_mfma_f32_16x16x32_bf16 v[12:15], v[146:149], v[208:211], v[12:15]
	v_mfma_f32_16x16x32_bf16 v[8:11], v[154:157], v[208:211], v[8:11]
	s_setprio 0
	s_setprio 1
	v_mfma_f32_16x16x32_bf16 v[52:55], v[164:167], v[180:183], v[52:55]
	v_mfma_f32_16x16x32_bf16 v[48:51], v[172:175], v[180:183], v[48:51]
	v_mfma_f32_16x16x32_bf16 v[36:39], v[164:167], v[188:191], v[36:39]
	v_mfma_f32_16x16x32_bf16 v[32:35], v[172:175], v[188:191], v[32:35]
	v_mfma_f32_16x16x32_bf16 v[20:23], v[164:167], v[196:199], v[20:23]
	v_mfma_f32_16x16x32_bf16 v[16:19], v[172:175], v[196:199], v[16:19]
	v_mfma_f32_16x16x32_bf16 v[4:7], v[164:167], v[204:207], v[4:7]
	v_mfma_f32_16x16x32_bf16 v[0:3], v[172:175], v[204:207], v[0:3]
	v_mfma_f32_16x16x32_bf16 v[52:55], v[168:171], v[184:187], v[52:55]
	v_mfma_f32_16x16x32_bf16 v[48:51], v[176:179], v[184:187], v[48:51]
	v_mfma_f32_16x16x32_bf16 v[36:39], v[168:171], v[192:195], v[36:39]
	v_mfma_f32_16x16x32_bf16 v[32:35], v[176:179], v[192:195], v[32:35]
	v_mfma_f32_16x16x32_bf16 v[20:23], v[168:171], v[200:203], v[20:23]
	v_mfma_f32_16x16x32_bf16 v[16:19], v[176:179], v[200:203], v[16:19]
	v_mfma_f32_16x16x32_bf16 v[4:7], v[168:171], v[208:211], v[4:7]
	v_mfma_f32_16x16x32_bf16 v[0:3], v[176:179], v[208:211], v[0:3]
	s_setprio 0
	s_add_i32 s65, s65, 2
	s_add_u32 s34, s34, 0x100
	s_addc_u32 s35, s35, 0
	s_add_u32 s63, s63, 0x100
	s_addc_u32 s64, s64, 0
	s_cmp_gt_u32 s65, 13
	s_barrier
	s_cbranch_scc0 .LBB0_673
	s_and_b64 vcc, exec, s[8:9]
	s_cbranch_vccz .LBB0_676
	s_barrier

; #define PG8_STAGE(bufoff, gbase, voff) do { _Pragma("unroll") for (int _i = 0; _i < 2; ++_i) \
;         __builtin_amdgcn_global_load_lds((const unsigned*)((const char*)(gbase) + (voff)[_i]), (LAS unsigned*)(lds + (bufoff) + ldsw + _i * 8192), 16, 0, 0); } while (0)
; #define PG8_LDA(dst, b, h) do { _Pragma("unroll") for (int m = 0; m < 4; ++m) _Pragma("unroll") for (int k = 0; k < 2; ++k) dst[m][k] = *(const LAS bf16x8*)(lds + PG8_SA(b, h) + aoff + m * 2048 + k * 1024); } while (0)
; #define PG8_LDB(dst, b, h) do { _Pragma("unroll") for (int n = 0; n < 2; ++n) _Pragma("unroll") for (int k = 0; k < 2; ++k) dst[n][k] = *(const LAS bf16x8*)(lds + PG8_SB(b, h) + boff + n * 2048 + k * 1024); } while (0)
; #define PG8_MMA(ai, bj, At, Bt) do { __builtin_amdgcn_s_setprio(1); _Pragma("unroll") for (int m = 0; m < 4; ++m) _Pragma("unroll") for (int n = 0; n < 2; ++n) _Pragma("unroll") for (int k = 0; k < 2; ++k) \
;         acc[ai][bj][m][n] = __builtin_amdgcn_mfma_f32_16x16x32_bf16(Bt[n][k], At[m][k], acc[ai][bj][m][n], 0, 0, 0); __builtin_amdgcn_s_setprio(0); } while (0)
; #define PG8_WAIT_V(n) asm volatile("s_waitcnt vmcnt(" #n ")" ::: "memory")
; #define PG8_WAIT_L(n) asm volatile("s_waitcnt lgkmcnt(" #n ")" ::: "memory")
; #define PG8_BAR __builtin_amdgcn_s_barrier()
; #define PG8_SCHED __builtin_amdgcn_sched_barrier(0)
; template <class Epi, class Sched>
; __device__ __forceinline__ void gemm_phase(LAS unsigned char* lds, const Gemm g, const Sched& S, const Epi& E, int wave_id) {
;     ...
;         for (int t = 0; t < nt; t += 2) {
;             const bool last = (t == nt - 2);
;             const char* a1 = cA + (size_t)(t + 1) * kstep;
;             const char* a2 = last ? nA : cA + (size_t)(t + 2) * kstep; const char* b2 = last ? nB : cB + (size_t)(t + 2) * kstep;
;             const char* a3 = a2 + kstep; const char* b3 = b2 + kstep;
;             PG8_LDB(B0, 0, 0); PG8_LDB(B1, 0, 1); PG8_SCHED; PG8_LDA(At, 0, 0); PG8_STAGE(PG8_SA(1, 1), a1 + hstepA, voffA);
;             PG8_WAIT_V(8); PG8_WAIT_L(0); PG8_BAR; PG8_MMA(0, 0, At, B0); PG8_MMA(0, 1, At, B1); PG8_BAR; PG8_SCHED;
;             PG8_LDA(At, 0, 1); PG8_STAGE(PG8_SB(0, 0), b2, voffB); PG8_STAGE(PG8_SB(0, 1), b2 + hstepB, voffB); PG8_STAGE(PG8_SA(0, 0), a2, voffA);
;             PG8_WAIT_V(8); PG8_WAIT_L(0); PG8_BAR; PG8_MMA(1, 0, At, B0); PG8_MMA(1, 1, At, B1); PG8_BAR; PG8_SCHED;
.LBB0_728:
	ds_read_b128 v[142:145], v161
	ds_read_b128 v[146:149], v161 offset:1024
	ds_read_b128 v[150:153], v161 offset:2048
	ds_read_b128 v[154:157], v161 offset:3072
	ds_read_b128 v[164:167], v162
	ds_read_b128 v[168:171], v162 offset:1024
	ds_read_b128 v[172:175], v162 offset:2048
	ds_read_b128 v[176:179], v162 offset:3072
	s_add_u32 s34, s30, 0xfffc0080
	s_addc_u32 s35, s31, -1
	s_cmp_eq_u32 s63, 12
	s_cselect_b32 s37, s21, s35
	s_cselect_b32 s36, s59, s34
	s_cselect_b32 s35, s17, s62
	s_cselect_b32 s34, s60, s61
	v_lshl_add_u64 v[212:213], s[30:31], 0, v[136:137]
	s_add_i32 m0, s29, 0xc000
	ds_read_b128 v[180:183], v163
	ds_read_b128 v[184:187], v163 offset:1024
	ds_read_b128 v[188:191], v163 offset:2048
	ds_read_b128 v[192:195], v163 offset:3072
	ds_read_b128 v[196:199], v163 offset:4096
	ds_read_b128 v[200:203], v163 offset:5120
	ds_read_b128 v[204:207], v163 offset:6144
	ds_read_b128 v[208:211], v163 offset:7168
	global_load_lds_dwordx4 v[212:213], off
	v_lshl_add_u64 v[212:213], s[30:31], 0, v[138:139]
	s_add_i32 m0, s29, 0xe000
	s_nop 0
	global_load_lds_dwordx4 v[212:213], off
	s_waitcnt vmcnt(8)
	s_waitcnt lgkmcnt(0)
	s_barrier
	s_setprio 1
	s_waitcnt lgkmcnt(0)
	v_mfma_f32_16x16x32_bf16 v[124:127], v[142:145], v[180:183], v[124:127]
	v_mfma_f32_16x16x32_bf16 v[120:123], v[150:153], v[180:183], v[120:123]
	v_mfma_f32_16x16x32_bf16 v[108:111], v[142:145], v[188:191], v[108:111]
	v_mfma_f32_16x16x32_bf16 v[104:107], v[150:153], v[188:191], v[104:107]
	v_mfma_f32_16x16x32_bf16 v[92:95], v[142:145], v[196:199], v[92:95]
	v_mfma_f32_16x16x32_bf16 v[88:91], v[150:153], v[196:199], v[88:91]
	v_mfma_f32_16x16x32_bf16 v[76:79], v[142:145], v[204:207], v[76:79]
	v_mfma_f32_16x16x32_bf16 v[72:75], v[150:153], v[204:207], v[72:75]
	v_mfma_f32_16x16x32_bf16 v[124:127], v[146:149], v[184:187], v[124:127]
	v_mfma_f32_16x16x32_bf16 v[120:123], v[154:157], v[184:187], v[120:123]
	v_mfma_f32_16x16x32_bf16 v[108:111], v[146:149], v[192:195], v[108:111]
	v_mfma_f32_16x16x32_bf16 v[104:107], v[154:157], v[192:195], v[104:107]
	v_mfma_f32_16x16x32_bf16 v[92:95], v[146:149], v[200:203], v[92:95]
	v_mfma_f32_16x16x32_bf16 v[88:91], v[154:157], v[200:203], v[88:91]
	v_mfma_f32_16x16x32_bf16 v[76:79], v[146:149], v[208:211], v[76:79]
	v_mfma_f32_16x16x32_bf16 v[72:75], v[154:157], v[208:211], v[72:75]
	s_setprio 0
	s_setprio 1
	v_mfma_f32_16x16x32_bf16 v[116:119], v[164:167], v[180:183], v[116:119]
	v_mfma_f32_16x16x32_bf16 v[112:115], v[172:175], v[180:183], v[112:115]
	v_mfma_f32_16x16x32_bf16 v[100:103], v[164:167], v[188:191], v[100:103]
	v_mfma_f32_16x16x32_bf16 v[96:99], v[172:175], v[188:191], v[96:99]
	v_mfma_f32_16x16x32_bf16 v[84:87], v[164:167], v[196:199], v[84:87]
	v_mfma_f32_16x16x32_bf16 v[80:83], v[172:175], v[196:199], v[80:83]
	v_mfma_f32_16x16x32_bf16 v[68:71], v[164:167], v[204:207], v[68:71]
	v_mfma_f32_16x16x32_bf16 v[64:67], v[172:175], v[204:207], v[64:67]
	v_mfma_f32_16x16x32_bf16 v[116:119], v[168:171], v[184:187], v[116:119]
	v_mfma_f32_16x16x32_bf16 v[112:115], v[176:179], v[184:187], v[112:115]
	v_mfma_f32_16x16x32_bf16 v[100:103], v[168:171], v[192:195], v[100:103]
	v_mfma_f32_16x16x32_bf16 v[96:99], v[176:179], v[192:195], v[96:99]
	v_mfma_f32_16x16x32_bf16 v[84:87], v[168:171], v[200:203], v[84:87]
	v_mfma_f32_16x16x32_bf16 v[80:83], v[176:179], v[200:203], v[80:83]
	v_mfma_f32_16x16x32_bf16 v[68:71], v[168:171], v[208:211], v[68:71]
	v_mfma_f32_16x16x32_bf16 v[64:67], v[176:179], v[208:211], v[64:67]
	s_setprio 0
	s_barrier
	s_add_i32 s64, s53, s44
	v_lshl_add_u64 v[212:213], s[34:35], 0, v[130:131]
	s_mov_b32 m0, s64
	ds_read_b128 v[180:183], v163 offset:16384
	ds_read_b128 v[184:187], v163 offset:17408
	ds_read_b128 v[188:191], v163 offset:18432
	ds_read_b128 v[192:195], v163 offset:19456
	ds_read_b128 v[196:199], v163 offset:20480
	ds_read_b128 v[200:203], v163 offset:21504
	ds_read_b128 v[204:207], v163 offset:22528
	ds_read_b128 v[208:211], v163 offset:23552
	global_load_lds_dwordx4 v[212:213], off
	s_add_i32 m0, s64, 0x2000
	s_add_u32 s64, s34, 0x40000
	v_lshl_add_u64 v[214:215], s[34:35], 0, v[134:135]
	s_addc_u32 s65, s35, 0
	s_add_i32 s66, s54, s44
	global_load_lds_dwordx4 v[214:215], off
	v_lshl_add_u64 v[216:217], s[64:65], 0, v[130:131]
	s_mov_b32 m0, s66
	v_lshl_add_u64 v[218:219], s[36:37], 0, v[132:133]
	global_load_lds_dwordx4 v[216:217], off
	v_lshl_add_u64 v[216:217], s[64:65], 0, v[134:135]
	s_add_i32 m0, s66, 0x2000
	s_nop 0
	global_load_lds_dwordx4 v[216:217], off
	v_lshl_add_u64 v[216:217], s[36:37], 0, v[128:129]
	s_mov_b32 m0, s29
	s_nop 0
	global_load_lds_dwordx4 v[216:217], off
	s_mov_b32 m0, s45
	s_nop 0
	global_load_lds_dwordx4 v[218:219], off
	s_waitcnt vmcnt(8)
	s_waitcnt lgkmcnt(0)
	s_barrier
; #define PG8_STAGE(bufoff, gbase, voff) do { _Pragma("unroll") for (int _i = 0; _i < 2; ++_i) \
;         __builtin_amdgcn_global_load_lds((const unsigned*)((const char*)(gbase) + (voff)[_i]), (LAS unsigned*)(lds + (bufoff) + ldsw + _i * 8192), 16, 0, 0); } while (0)
; #define PG8_LDA(dst, b, h) do { _Pragma("unroll") for (int m = 0; m < 4; ++m) _Pragma("unroll") for (int k = 0; k < 2; ++k) dst[m][k] = *(const LAS bf16x8*)(lds + PG8_SA(b, h) + aoff + m * 2048 + k * 1024); } while (0)
; #define PG8_LDB(dst, b, h) do { _Pragma("unroll") for (int n = 0; n < 2; ++n) _Pragma("unroll") for (int k = 0; k < 2; ++k) dst[n][k] = *(const LAS bf16x8*)(lds + PG8_SB(b, h) + boff + n * 2048 + k * 1024); } while (0)
; #define PG8_MMA(ai, bj, At, Bt) do { __builtin_amdgcn_s_setprio(1); _Pragma("unroll") for (int m = 0; m < 4; ++m) _Pragma("unroll") for (int n = 0; n < 2; ++n) _Pragma("unroll") for (int k = 0; k < 2; ++k) \
;         acc[ai][bj][m][n] = __builtin_amdgcn_mfma_f32_16x16x32_bf16(Bt[n][k], At[m][k], acc[ai][bj][m][n], 0, 0, 0); __builtin_amdgcn_s_setprio(0); } while (0)
; #define PG8_WAIT_V(n) asm volatile("s_waitcnt vmcnt(" #n ")" ::: "memory")
; #define PG8_WAIT_L(n) asm volatile("s_waitcnt lgkmcnt(" #n ")" ::: "memory")
; #define PG8_BAR __builtin_amdgcn_s_barrier()
; #define PG8_SCHED __builtin_amdgcn_sched_barrier(0)
; template <class Epi, class Sched>
; __device__ __forceinline__ void gemm_phase(LAS unsigned char* lds, const Gemm g, const Sched& S, const Epi& E, int wave_id) {
;     ...
;             PG8_WAIT_V(8); PG8_WAIT_L(0); PG8_BAR; PG8_MMA(1, 0, At, B0); PG8_MMA(1, 1, At, B1); PG8_BAR; PG8_SCHED;
;             PG8_LDB(B0, 1, 0); PG8_LDB(B1, 1, 1); PG8_SCHED; PG8_LDA(At, 1, 0); PG8_STAGE(PG8_SA(0, 1), a2 + hstepA, voffA);
;             PG8_WAIT_V(8); PG8_WAIT_L(0); PG8_BAR; PG8_MMA(0, 0, At, B0); PG8_MMA(0, 1, At, B1); PG8_BAR; PG8_SCHED;
	s_setprio 1
	s_waitcnt lgkmcnt(0)
	v_mfma_f32_16x16x32_bf16 v[60:63], v[142:145], v[180:183], v[60:63]
	v_mfma_f32_16x16x32_bf16 v[56:59], v[150:153], v[180:183], v[56:59]
	v_mfma_f32_16x16x32_bf16 v[44:47], v[142:145], v[188:191], v[44:47]
	v_mfma_f32_16x16x32_bf16 v[40:43], v[150:153], v[188:191], v[40:43]
	v_mfma_f32_16x16x32_bf16 v[28:31], v[142:145], v[196:199], v[28:31]
	v_mfma_f32_16x16x32_bf16 v[24:27], v[150:153], v[196:199], v[24:27]
	v_mfma_f32_16x16x32_bf16 v[12:15], v[142:145], v[204:207], v[12:15]
	v_mfma_f32_16x16x32_bf16 v[8:11], v[150:153], v[204:207], v[8:11]
	v_mfma_f32_16x16x32_bf16 v[60:63], v[146:149], v[184:187], v[60:63]
	v_mfma_f32_16x16x32_bf16 v[56:59], v[154:157], v[184:187], v[56:59]
	v_mfma_f32_16x16x32_bf16 v[44:47], v[146:149], v[192:195], v[44:47]
	v_mfma_f32_16x16x32_bf16 v[40:43], v[154:157], v[192:195], v[40:43]
	v_mfma_f32_16x16x32_bf16 v[28:31], v[146:149], v[200:203], v[28:31]
	v_mfma_f32_16x16x32_bf16 v[24:27], v[154:157], v[200:203], v[24:27]
	v_mfma_f32_16x16x32_bf16 v[12:15], v[146:149], v[208:211], v[12:15]
	v_mfma_f32_16x16x32_bf16 v[8:11], v[154:157], v[208:211], v[8:11]
	s_setprio 0
	s_setprio 1
	v_mfma_f32_16x16x32_bf16 v[52:55], v[164:167], v[180:183], v[52:55]
	v_mfma_f32_16x16x32_bf16 v[48:51], v[172:175], v[180:183], v[48:51]
	v_mfma_f32_16x16x32_bf16 v[36:39], v[164:167], v[188:191], v[36:39]
	v_mfma_f32_16x16x32_bf16 v[32:35], v[172:175], v[188:191], v[32:35]
	v_mfma_f32_16x16x32_bf16 v[20:23], v[164:167], v[196:199], v[20:23]
	v_mfma_f32_16x16x32_bf16 v[16:19], v[172:175], v[196:199], v[16:19]
	v_mfma_f32_16x16x32_bf16 v[4:7], v[164:167], v[204:207], v[4:7]
	v_mfma_f32_16x16x32_bf16 v[0:3], v[172:175], v[204:207], v[0:3]
	v_mfma_f32_16x16x32_bf16 v[52:55], v[168:171], v[184:187], v[52:55]
	v_mfma_f32_16x16x32_bf16 v[48:51], v[176:179], v[184:187], v[48:51]
	v_mfma_f32_16x16x32_bf16 v[36:39], v[168:171], v[192:195], v[36:39]
	v_mfma_f32_16x16x32_bf16 v[32:35], v[176:179], v[192:195], v[32:35]
	v_mfma_f32_16x16x32_bf16 v[20:23], v[168:171], v[200:203], v[20:23]
	v_mfma_f32_16x16x32_bf16 v[16:19], v[176:179], v[200:203], v[16:19]
	v_mfma_f32_16x16x32_bf16 v[4:7], v[168:171], v[208:211], v[4:7]
	v_mfma_f32_16x16x32_bf16 v[0:3], v[176:179], v[208:211], v[0:3]
	s_setprio 0
	s_barrier
	s_add_i32 s64, 0, 0x18000
	s_add_i32 s65, 0, 0x1c000
	v_add_u32_e32 v154, s64, v159
	v_add_u32_e32 v176, s65, v159
	ds_read_b128 v[142:145], v154
	ds_read_b128 v[146:149], v154 offset:1024
	ds_read_b128 v[150:153], v154 offset:2048
	ds_read_b128 v[154:157], v154 offset:3072
	ds_read_b128 v[164:167], v176
	ds_read_b128 v[168:171], v176 offset:1024
	ds_read_b128 v[172:175], v176 offset:2048
	ds_read_b128 v[176:179], v176 offset:3072
	s_add_u32 s36, s36, 0x40000
	s_addc_u32 s37, s37, 0
	s_mov_b32 m0, s46
	v_lshl_add_u64 v[220:221], s[36:37], 0, v[128:129]
	ds_read_b128 v[180:183], v163 offset:32768
	ds_read_b128 v[184:187], v163 offset:33792
	ds_read_b128 v[188:191], v163 offset:34816
	ds_read_b128 v[192:195], v163 offset:35840
	ds_read_b128 v[196:199], v163 offset:36864
	ds_read_b128 v[200:203], v163 offset:37888
	ds_read_b128 v[204:207], v163 offset:38912
	ds_read_b128 v[208:211], v163 offset:39936
	global_load_lds_dwordx4 v[220:221], off
	v_lshl_add_u64 v[220:221], s[36:37], 0, v[132:133]
	s_mov_b32 m0, s47
	s_nop 0
	global_load_lds_dwordx4 v[220:221], off
	s_waitcnt vmcnt(8)
	s_waitcnt lgkmcnt(0)
	s_barrier
	s_setprio 1
	s_waitcnt lgkmcnt(0)
	v_mfma_f32_16x16x32_bf16 v[124:127], v[142:145], v[180:183], v[124:127]
	v_mfma_f32_16x16x32_bf16 v[120:123], v[150:153], v[180:183], v[120:123]
	v_mfma_f32_16x16x32_bf16 v[108:111], v[142:145], v[188:191], v[108:111]
	v_mfma_f32_16x16x32_bf16 v[104:107], v[150:153], v[188:191], v[104:107]
	v_mfma_f32_16x16x32_bf16 v[92:95], v[142:145], v[196:199], v[92:95]
	v_mfma_f32_16x16x32_bf16 v[88:91], v[150:153], v[196:199], v[88:91]
	v_mfma_f32_16x16x32_bf16 v[76:79], v[142:145], v[204:207], v[76:79]
	v_mfma_f32_16x16x32_bf16 v[72:75], v[150:153], v[204:207], v[72:75]
	v_mfma_f32_16x16x32_bf16 v[124:127], v[146:149], v[184:187], v[124:127]
	v_mfma_f32_16x16x32_bf16 v[120:123], v[154:157], v[184:187], v[120:123]
	v_mfma_f32_16x16x32_bf16 v[108:111], v[146:149], v[192:195], v[108:111]
	v_mfma_f32_16x16x32_bf16 v[104:107], v[154:157], v[192:195], v[104:107]
	v_mfma_f32_16x16x32_bf16 v[92:95], v[146:149], v[200:203], v[92:95]
	v_mfma_f32_16x16x32_bf16 v[88:91], v[154:157], v[200:203], v[88:91]
	v_mfma_f32_16x16x32_bf16 v[76:79], v[146:149], v[208:211], v[76:79]
	v_mfma_f32_16x16x32_bf16 v[72:75], v[154:157], v[208:211], v[72:75]
	s_setprio 0
	s_setprio 1
	v_mfma_f32_16x16x32_bf16 v[116:119], v[164:167], v[180:183], v[116:119]
	v_mfma_f32_16x16x32_bf16 v[112:115], v[172:175], v[180:183], v[112:115]
	v_mfma_f32_16x16x32_bf16 v[100:103], v[164:167], v[188:191], v[100:103]
	v_mfma_f32_16x16x32_bf16 v[96:99], v[172:175], v[188:191], v[96:99]
	v_mfma_f32_16x16x32_bf16 v[84:87], v[164:167], v[196:199], v[84:87]
	v_mfma_f32_16x16x32_bf16 v[80:83], v[172:175], v[196:199], v[80:83]
	v_mfma_f32_16x16x32_bf16 v[68:71], v[164:167], v[204:207], v[68:71]
	v_mfma_f32_16x16x32_bf16 v[64:67], v[172:175], v[204:207], v[64:67]
	v_mfma_f32_16x16x32_bf16 v[116:119], v[168:171], v[184:187], v[116:119]
	v_mfma_f32_16x16x32_bf16 v[112:115], v[176:179], v[184:187], v[112:115]
	v_mfma_f32_16x16x32_bf16 v[100:103], v[168:171], v[192:195], v[100:103]
	v_mfma_f32_16x16x32_bf16 v[96:99], v[176:179], v[192:195], v[96:99]
	v_mfma_f32_16x16x32_bf16 v[84:87], v[168:171], v[200:203], v[84:87]
	v_mfma_f32_16x16x32_bf16 v[80:83], v[176:179], v[200:203], v[80:83]
	v_mfma_f32_16x16x32_bf16 v[68:71], v[168:171], v[208:211], v[68:71]
	v_mfma_f32_16x16x32_bf16 v[64:67], v[176:179], v[208:211], v[64:67]
	s_setprio 0
	s_barrier
; #define PG8_STAGE(bufoff, gbase, voff) do { _Pragma("unroll") for (int _i = 0; _i < 2; ++_i) \
;         __builtin_amdgcn_global_load_lds((const unsigned*)((const char*)(gbase) + (voff)[_i]), (LAS unsigned*)(lds + (bufoff) + ldsw + _i * 8192), 16, 0, 0); } while (0)
; #define PG8_LDA(dst, b, h) do { _Pragma("unroll") for (int m = 0; m < 4; ++m) _Pragma("unroll") for (int k = 0; k < 2; ++k) dst[m][k] = *(const LAS bf16x8*)(lds + PG8_SA(b, h) + aoff + m * 2048 + k * 1024); } while (0)
; #define PG8_MMA(ai, bj, At, Bt) do { __builtin_amdgcn_s_setprio(1); _Pragma("unroll") for (int m = 0; m < 4; ++m) _Pragma("unroll") for (int n = 0; n < 2; ++n) _Pragma("unroll") for (int k = 0; k < 2; ++k) \
;         acc[ai][bj][m][n] = __builtin_amdgcn_mfma_f32_16x16x32_bf16(Bt[n][k], At[m][k], acc[ai][bj][m][n], 0, 0, 0); __builtin_amdgcn_s_setprio(0); } while (0)
; #define PG8_WAIT_V(n) asm volatile("s_waitcnt vmcnt(" #n ")" ::: "memory")
; #define PG8_WAIT_L(n) asm volatile("s_waitcnt lgkmcnt(" #n ")" ::: "memory")
; #define PG8_BAR __builtin_amdgcn_s_barrier()
; #define PG8_SCHED __builtin_amdgcn_sched_barrier(0)
; template <class Epi, class Sched>
; __device__ __forceinline__ void gemm_phase(LAS unsigned char* lds, const Gemm g, const Sched& S, const Epi& E, int wave_id) {
;     ...
;             PG8_LDA(At, 1, 1); PG8_STAGE(PG8_SB(1, 0), b3, voffB); PG8_STAGE(PG8_SB(1, 1), b3 + hstepB, voffB); PG8_STAGE(PG8_SA(1, 0), a3, voffA);
;             PG8_WAIT_V(8); PG8_WAIT_L(0); PG8_BAR; PG8_MMA(1, 0, At, B0); PG8_MMA(1, 1, At, B1); PG8_BAR; PG8_SCHED;
;         }
	s_add_i32 s36, s64, s44
	v_lshl_add_u64 v[212:213], v[212:213], 0, s[6:7]
	s_mov_b32 m0, s36
	ds_read_b128 v[180:183], v163 offset:49152
	ds_read_b128 v[184:187], v163 offset:50176
	ds_read_b128 v[188:191], v163 offset:51200
	ds_read_b128 v[192:195], v163 offset:52224
	ds_read_b128 v[196:199], v163 offset:53248
	ds_read_b128 v[200:203], v163 offset:54272
	ds_read_b128 v[204:207], v163 offset:55296
	ds_read_b128 v[208:211], v163 offset:56320
	global_load_lds_dwordx4 v[212:213], off
	s_add_i32 m0, s36, 0x2000
	s_add_u32 s34, s34, 0x40080
	v_lshl_add_u64 v[212:213], v[214:215], 0, s[6:7]
	s_addc_u32 s35, s35, 0
	s_add_i32 s36, s65, s44
	global_load_lds_dwordx4 v[212:213], off
	v_lshl_add_u64 v[212:213], s[34:35], 0, v[130:131]
	s_mov_b32 m0, s36
	s_nop 0
	global_load_lds_dwordx4 v[212:213], off
	v_lshl_add_u64 v[212:213], s[34:35], 0, v[134:135]
	s_add_i32 m0, s36, 0x2000
	s_nop 0
	global_load_lds_dwordx4 v[212:213], off
	v_lshl_add_u64 v[212:213], v[216:217], 0, s[6:7]
	s_mov_b32 m0, s50
	s_nop 0
	global_load_lds_dwordx4 v[212:213], off
	v_lshl_add_u64 v[212:213], v[218:219], 0, s[6:7]
	s_mov_b32 m0, s51
	s_nop 0
	global_load_lds_dwordx4 v[212:213], off
	s_waitcnt vmcnt(8)
	s_waitcnt lgkmcnt(0)
	s_barrier
	s_setprio 1
	s_waitcnt lgkmcnt(0)
	v_mfma_f32_16x16x32_bf16 v[60:63], v[142:145], v[180:183], v[60:63]
	v_mfma_f32_16x16x32_bf16 v[56:59], v[150:153], v[180:183], v[56:59]
	v_mfma_f32_16x16x32_bf16 v[44:47], v[142:145], v[188:191], v[44:47]
	v_mfma_f32_16x16x32_bf16 v[40:43], v[150:153], v[188:191], v[40:43]
	v_mfma_f32_16x16x32_bf16 v[28:31], v[142:145], v[196:199], v[28:31]
	v_mfma_f32_16x16x32_bf16 v[24:27], v[150:153], v[196:199], v[24:27]
	v_mfma_f32_16x16x32_bf16 v[12:15], v[142:145], v[204:207], v[12:15]
	v_mfma_f32_16x16x32_bf16 v[8:11], v[150:153], v[204:207], v[8:11]
	v_mfma_f32_16x16x32_bf16 v[60:63], v[146:149], v[184:187], v[60:63]
	v_mfma_f32_16x16x32_bf16 v[56:59], v[154:157], v[184:187], v[56:59]
	v_mfma_f32_16x16x32_bf16 v[44:47], v[146:149], v[192:195], v[44:47]
	v_mfma_f32_16x16x32_bf16 v[40:43], v[154:157], v[192:195], v[40:43]
	v_mfma_f32_16x16x32_bf16 v[28:31], v[146:149], v[200:203], v[28:31]
	v_mfma_f32_16x16x32_bf16 v[24:27], v[154:157], v[200:203], v[24:27]
	v_mfma_f32_16x16x32_bf16 v[12:15], v[146:149], v[208:211], v[12:15]
	v_mfma_f32_16x16x32_bf16 v[8:11], v[154:157], v[208:211], v[8:11]
	s_setprio 0
	s_setprio 1
	v_mfma_f32_16x16x32_bf16 v[52:55], v[164:167], v[180:183], v[52:55]
	v_mfma_f32_16x16x32_bf16 v[48:51], v[172:175], v[180:183], v[48:51]
	v_mfma_f32_16x16x32_bf16 v[36:39], v[164:167], v[188:191], v[36:39]
	v_mfma_f32_16x16x32_bf16 v[32:35], v[172:175], v[188:191], v[32:35]
	v_mfma_f32_16x16x32_bf16 v[20:23], v[164:167], v[196:199], v[20:23]
	v_mfma_f32_16x16x32_bf16 v[16:19], v[172:175], v[196:199], v[16:19]
	v_mfma_f32_16x16x32_bf16 v[4:7], v[164:167], v[204:207], v[4:7]
	v_mfma_f32_16x16x32_bf16 v[0:3], v[172:175], v[204:207], v[0:3]
	v_mfma_f32_16x16x32_bf16 v[52:55], v[168:171], v[184:187], v[52:55]
	v_mfma_f32_16x16x32_bf16 v[48:51], v[176:179], v[184:187], v[48:51]
	v_mfma_f32_16x16x32_bf16 v[36:39], v[168:171], v[192:195], v[36:39]
	v_mfma_f32_16x16x32_bf16 v[32:35], v[176:179], v[192:195], v[32:35]
	v_mfma_f32_16x16x32_bf16 v[20:23], v[168:171], v[200:203], v[20:23]
	v_mfma_f32_16x16x32_bf16 v[16:19], v[176:179], v[200:203], v[16:19]
	v_mfma_f32_16x16x32_bf16 v[4:7], v[168:171], v[208:211], v[4:7]
	v_mfma_f32_16x16x32_bf16 v[0:3], v[176:179], v[208:211], v[0:3]
	s_setprio 0
	s_add_i32 s63, s63, 2
	s_add_u32 s30, s30, 0x100
	s_addc_u32 s31, s31, 0
	s_add_u32 s61, s61, 0x100
	s_addc_u32 s62, s62, 0
	s_cmp_gt_u32 s63, 13
	s_barrier
	s_cbranch_scc0 .LBB0_728
	s_and_b64 vcc, exec, s[8:9]
	s_cbranch_vccz .LBB0_731
	s_barrier

; #define PG8_STAGE(bufoff, gbase, voff) do { _Pragma("unroll") for (int _i = 0; _i < 2; ++_i) \
;         __builtin_amdgcn_global_load_lds((const unsigned*)((const char*)(gbase) + (voff)[_i]), (LAS unsigned*)(lds + (bufoff) + ldsw + _i * 8192), 16, 0, 0); } while (0)
; #define PG8_LDA(dst, b, h) do { _Pragma("unroll") for (int m = 0; m < 4; ++m) _Pragma("unroll") for (int k = 0; k < 2; ++k) dst[m][k] = *(const LAS bf16x8*)(lds + PG8_SA(b, h) + aoff + m * 2048 + k * 1024); } while (0)
; #define PG8_LDB(dst, b, h) do { _Pragma("unroll") for (int n = 0; n < 2; ++n) _Pragma("unroll") for (int k = 0; k < 2; ++k) dst[n][k] = *(const LAS bf16x8*)(lds + PG8_SB(b, h) + boff + n * 2048 + k * 1024); } while (0)
; #define PG8_MMA(ai, bj, At, Bt) do { __builtin_amdgcn_s_setprio(1); _Pragma("unroll") for (int m = 0; m < 4; ++m) _Pragma("unroll") for (int n = 0; n < 2; ++n) _Pragma("unroll") for (int k = 0; k < 2; ++k) \
;         acc[ai][bj][m][n] = __builtin_amdgcn_mfma_f32_16x16x32_bf16(Bt[n][k], At[m][k], acc[ai][bj][m][n], 0, 0, 0); __builtin_amdgcn_s_setprio(0); } while (0)
; #define PG8_WAIT_V(n) asm volatile("s_waitcnt vmcnt(" #n ")" ::: "memory")
; #define PG8_WAIT_L(n) asm volatile("s_waitcnt lgkmcnt(" #n ")" ::: "memory")
; #define PG8_BAR __builtin_amdgcn_s_barrier()
; #define PG8_SCHED __builtin_amdgcn_sched_barrier(0)
; template <class Epi, class Sched>
; __device__ __forceinline__ void gemm_phase(LAS unsigned char* lds, const Gemm g, const Sched& S, const Epi& E, int wave_id) {
;     ...
;         for (int t = 0; t < nt; t += 2) {
;             const bool last = (t == nt - 2);
;             const char* a1 = cA + (size_t)(t + 1) * kstep;
;             const char* a2 = last ? nA : cA + (size_t)(t + 2) * kstep; const char* b2 = last ? nB : cB + (size_t)(t + 2) * kstep;
;             const char* a3 = a2 + kstep; const char* b3 = b2 + kstep;
;             PG8_LDB(B0, 0, 0); PG8_LDB(B1, 0, 1); PG8_SCHED; PG8_LDA(At, 0, 0); PG8_STAGE(PG8_SA(1, 1), a1 + hstepA, voffA);
;             PG8_WAIT_V(8); PG8_WAIT_L(0); PG8_BAR; PG8_MMA(0, 0, At, B0); PG8_MMA(0, 1, At, B1); PG8_BAR; PG8_SCHED;
;             PG8_LDA(At, 0, 1); PG8_STAGE(PG8_SB(0, 0), b2, voffB); PG8_STAGE(PG8_SB(0, 1), b2 + hstepB, voffB); PG8_STAGE(PG8_SA(0, 0), a2, voffA);
;             PG8_WAIT_V(8); PG8_WAIT_L(0); PG8_BAR; PG8_MMA(1, 0, At, B0); PG8_MMA(1, 1, At, B1); PG8_BAR; PG8_SCHED;
.LBB0_804:
	ds_read_b128 v[140:143], v159
	ds_read_b128 v[144:147], v159 offset:1024
	ds_read_b128 v[148:151], v159 offset:2048
	ds_read_b128 v[152:155], v159 offset:3072
	ds_read_b128 v[162:165], v160
	ds_read_b128 v[166:169], v160 offset:1024
	ds_read_b128 v[170:173], v160 offset:2048
	ds_read_b128 v[174:177], v160 offset:3072
	s_add_u32 s34, s30, 0xfffc0080
	s_addc_u32 s35, s31, -1
	s_cmp_eq_u32 s55, 12
	s_cselect_b32 s37, s19, s35
	s_cselect_b32 s36, s51, s34
	s_cselect_b32 s35, s17, s54
	s_cselect_b32 s34, s52, s53
	v_lshl_add_u64 v[210:211], s[30:31], 0, v[136:137]
	s_add_i32 m0, s27, 0xc000
	ds_read_b128 v[178:181], v161
	ds_read_b128 v[182:185], v161 offset:1024
	ds_read_b128 v[186:189], v161 offset:2048
	ds_read_b128 v[190:193], v161 offset:3072
	ds_read_b128 v[194:197], v161 offset:4096
	ds_read_b128 v[198:201], v161 offset:5120
	ds_read_b128 v[202:205], v161 offset:6144
	ds_read_b128 v[206:209], v161 offset:7168
	global_load_lds_dwordx4 v[210:211], off
	v_lshl_add_u64 v[210:211], s[30:31], 0, v[138:139]
	s_add_i32 m0, s27, 0xe000
	s_nop 0
	global_load_lds_dwordx4 v[210:211], off
	s_waitcnt vmcnt(8)
	s_waitcnt lgkmcnt(0)
	s_barrier
	s_setprio 1
	s_waitcnt lgkmcnt(0)
	v_mfma_f32_16x16x32_bf16 v[124:127], v[140:143], v[178:181], v[124:127]
	v_mfma_f32_16x16x32_bf16 v[120:123], v[148:151], v[178:181], v[120:123]
	v_mfma_f32_16x16x32_bf16 v[108:111], v[140:143], v[186:189], v[108:111]
	v_mfma_f32_16x16x32_bf16 v[104:107], v[148:151], v[186:189], v[104:107]
	v_mfma_f32_16x16x32_bf16 v[92:95], v[140:143], v[194:197], v[92:95]
	v_mfma_f32_16x16x32_bf16 v[88:91], v[148:151], v[194:197], v[88:91]
	v_mfma_f32_16x16x32_bf16 v[76:79], v[140:143], v[202:205], v[76:79]
	v_mfma_f32_16x16x32_bf16 v[72:75], v[148:151], v[202:205], v[72:75]
	v_mfma_f32_16x16x32_bf16 v[124:127], v[144:147], v[182:185], v[124:127]
	v_mfma_f32_16x16x32_bf16 v[120:123], v[152:155], v[182:185], v[120:123]
	v_mfma_f32_16x16x32_bf16 v[108:111], v[144:147], v[190:193], v[108:111]
	v_mfma_f32_16x16x32_bf16 v[104:107], v[152:155], v[190:193], v[104:107]
	v_mfma_f32_16x16x32_bf16 v[92:95], v[144:147], v[198:201], v[92:95]
	v_mfma_f32_16x16x32_bf16 v[88:91], v[152:155], v[198:201], v[88:91]
	v_mfma_f32_16x16x32_bf16 v[76:79], v[144:147], v[206:209], v[76:79]
	v_mfma_f32_16x16x32_bf16 v[72:75], v[152:155], v[206:209], v[72:75]
	s_setprio 0
	s_setprio 1
	v_mfma_f32_16x16x32_bf16 v[116:119], v[162:165], v[178:181], v[116:119]
	v_mfma_f32_16x16x32_bf16 v[112:115], v[170:173], v[178:181], v[112:115]
	v_mfma_f32_16x16x32_bf16 v[100:103], v[162:165], v[186:189], v[100:103]
	v_mfma_f32_16x16x32_bf16 v[96:99], v[170:173], v[186:189], v[96:99]
	v_mfma_f32_16x16x32_bf16 v[84:87], v[162:165], v[194:197], v[84:87]
	v_mfma_f32_16x16x32_bf16 v[80:83], v[170:173], v[194:197], v[80:83]
	v_mfma_f32_16x16x32_bf16 v[68:71], v[162:165], v[202:205], v[68:71]
	v_mfma_f32_16x16x32_bf16 v[64:67], v[170:173], v[202:205], v[64:67]
	v_mfma_f32_16x16x32_bf16 v[116:119], v[166:169], v[182:185], v[116:119]
	v_mfma_f32_16x16x32_bf16 v[112:115], v[174:177], v[182:185], v[112:115]
	v_mfma_f32_16x16x32_bf16 v[100:103], v[166:169], v[190:193], v[100:103]
	v_mfma_f32_16x16x32_bf16 v[96:99], v[174:177], v[190:193], v[96:99]
	v_mfma_f32_16x16x32_bf16 v[84:87], v[166:169], v[198:201], v[84:87]
	v_mfma_f32_16x16x32_bf16 v[80:83], v[174:177], v[198:201], v[80:83]
	v_mfma_f32_16x16x32_bf16 v[68:71], v[166:169], v[206:209], v[68:71]
	v_mfma_f32_16x16x32_bf16 v[64:67], v[174:177], v[206:209], v[64:67]
	s_setprio 0
	s_barrier
	s_add_i32 s58, s48, s39
	v_lshl_add_u64 v[210:211], s[34:35], 0, v[130:131]
	s_mov_b32 m0, s58
	ds_read_b128 v[178:181], v161 offset:16384
	ds_read_b128 v[182:185], v161 offset:17408
	ds_read_b128 v[186:189], v161 offset:18432
	ds_read_b128 v[190:193], v161 offset:19456
	ds_read_b128 v[194:197], v161 offset:20480
	ds_read_b128 v[198:201], v161 offset:21504
	ds_read_b128 v[202:205], v161 offset:22528
	ds_read_b128 v[206:209], v161 offset:23552
	global_load_lds_dwordx4 v[210:211], off
	s_add_i32 m0, s58, 0x2000
	s_add_u32 s58, s34, 0x40000
	v_lshl_add_u64 v[212:213], s[34:35], 0, v[134:135]
	s_addc_u32 s59, s35, 0
	s_add_i32 s60, s49, s39
	global_load_lds_dwordx4 v[212:213], off
	v_lshl_add_u64 v[214:215], s[58:59], 0, v[130:131]
	s_mov_b32 m0, s60
	v_lshl_add_u64 v[216:217], s[36:37], 0, v[132:133]
	global_load_lds_dwordx4 v[214:215], off
	v_lshl_add_u64 v[214:215], s[58:59], 0, v[134:135]
	s_add_i32 m0, s60, 0x2000
	s_nop 0
	global_load_lds_dwordx4 v[214:215], off
	v_lshl_add_u64 v[214:215], s[36:37], 0, v[128:129]
	s_mov_b32 m0, s27
	s_nop 0
	global_load_lds_dwordx4 v[214:215], off
	s_mov_b32 m0, s29
	s_nop 0
	global_load_lds_dwordx4 v[216:217], off
	s_waitcnt vmcnt(8)
	s_waitcnt lgkmcnt(0)
	s_barrier
; #define PG8_STAGE(bufoff, gbase, voff) do { _Pragma("unroll") for (int _i = 0; _i < 2; ++_i) \
;         __builtin_amdgcn_global_load_lds((const unsigned*)((const char*)(gbase) + (voff)[_i]), (LAS unsigned*)(lds + (bufoff) + ldsw + _i * 8192), 16, 0, 0); } while (0)
; #define PG8_LDA(dst, b, h) do { _Pragma("unroll") for (int m = 0; m < 4; ++m) _Pragma("unroll") for (int k = 0; k < 2; ++k) dst[m][k] = *(const LAS bf16x8*)(lds + PG8_SA(b, h) + aoff + m * 2048 + k * 1024); } while (0)
; #define PG8_LDB(dst, b, h) do { _Pragma("unroll") for (int n = 0; n < 2; ++n) _Pragma("unroll") for (int k = 0; k < 2; ++k) dst[n][k] = *(const LAS bf16x8*)(lds + PG8_SB(b, h) + boff + n * 2048 + k * 1024); } while (0)
; #define PG8_MMA(ai, bj, At, Bt) do { __builtin_amdgcn_s_setprio(1); _Pragma("unroll") for (int m = 0; m < 4; ++m) _Pragma("unroll") for (int n = 0; n < 2; ++n) _Pragma("unroll") for (int k = 0; k < 2; ++k) \
;         acc[ai][bj][m][n] = __builtin_amdgcn_mfma_f32_16x16x32_bf16(Bt[n][k], At[m][k], acc[ai][bj][m][n], 0, 0, 0); __builtin_amdgcn_s_setprio(0); } while (0)
; #define PG8_WAIT_V(n) asm volatile("s_waitcnt vmcnt(" #n ")" ::: "memory")
; #define PG8_WAIT_L(n) asm volatile("s_waitcnt lgkmcnt(" #n ")" ::: "memory")
; #define PG8_BAR __builtin_amdgcn_s_barrier()
; #define PG8_SCHED __builtin_amdgcn_sched_barrier(0)
; template <class Epi, class Sched>
; __device__ __forceinline__ void gemm_phase(LAS unsigned char* lds, const Gemm g, const Sched& S, const Epi& E, int wave_id) {
;     ...
;             PG8_WAIT_V(8); PG8_WAIT_L(0); PG8_BAR; PG8_MMA(1, 0, At, B0); PG8_MMA(1, 1, At, B1); PG8_BAR; PG8_SCHED;
;             PG8_LDB(B0, 1, 0); PG8_LDB(B1, 1, 1); PG8_SCHED; PG8_LDA(At, 1, 0); PG8_STAGE(PG8_SA(0, 1), a2 + hstepA, voffA);
;             PG8_WAIT_V(8); PG8_WAIT_L(0); PG8_BAR; PG8_MMA(0, 0, At, B0); PG8_MMA(0, 1, At, B1); PG8_BAR; PG8_SCHED;
	s_setprio 1
	s_waitcnt lgkmcnt(0)
	v_mfma_f32_16x16x32_bf16 v[60:63], v[140:143], v[178:181], v[60:63]
	v_mfma_f32_16x16x32_bf16 v[56:59], v[148:151], v[178:181], v[56:59]
	v_mfma_f32_16x16x32_bf16 v[44:47], v[140:143], v[186:189], v[44:47]
	v_mfma_f32_16x16x32_bf16 v[40:43], v[148:151], v[186:189], v[40:43]
	v_mfma_f32_16x16x32_bf16 v[28:31], v[140:143], v[194:197], v[28:31]
	v_mfma_f32_16x16x32_bf16 v[24:27], v[148:151], v[194:197], v[24:27]
	v_mfma_f32_16x16x32_bf16 v[12:15], v[140:143], v[202:205], v[12:15]
	v_mfma_f32_16x16x32_bf16 v[8:11], v[148:151], v[202:205], v[8:11]
	v_mfma_f32_16x16x32_bf16 v[60:63], v[144:147], v[182:185], v[60:63]
	v_mfma_f32_16x16x32_bf16 v[56:59], v[152:155], v[182:185], v[56:59]
	v_mfma_f32_16x16x32_bf16 v[44:47], v[144:147], v[190:193], v[44:47]
	v_mfma_f32_16x16x32_bf16 v[40:43], v[152:155], v[190:193], v[40:43]
	v_mfma_f32_16x16x32_bf16 v[28:31], v[144:147], v[198:201], v[28:31]
	v_mfma_f32_16x16x32_bf16 v[24:27], v[152:155], v[198:201], v[24:27]
	v_mfma_f32_16x16x32_bf16 v[12:15], v[144:147], v[206:209], v[12:15]
	v_mfma_f32_16x16x32_bf16 v[8:11], v[152:155], v[206:209], v[8:11]
	s_setprio 0
	s_setprio 1
	v_mfma_f32_16x16x32_bf16 v[52:55], v[162:165], v[178:181], v[52:55]
	v_mfma_f32_16x16x32_bf16 v[48:51], v[170:173], v[178:181], v[48:51]
	v_mfma_f32_16x16x32_bf16 v[36:39], v[162:165], v[186:189], v[36:39]
	v_mfma_f32_16x16x32_bf16 v[32:35], v[170:173], v[186:189], v[32:35]
	v_mfma_f32_16x16x32_bf16 v[20:23], v[162:165], v[194:197], v[20:23]
	v_mfma_f32_16x16x32_bf16 v[16:19], v[170:173], v[194:197], v[16:19]
	v_mfma_f32_16x16x32_bf16 v[4:7], v[162:165], v[202:205], v[4:7]
	v_mfma_f32_16x16x32_bf16 v[0:3], v[170:173], v[202:205], v[0:3]
	v_mfma_f32_16x16x32_bf16 v[52:55], v[166:169], v[182:185], v[52:55]
	v_mfma_f32_16x16x32_bf16 v[48:51], v[174:177], v[182:185], v[48:51]
	v_mfma_f32_16x16x32_bf16 v[36:39], v[166:169], v[190:193], v[36:39]
	v_mfma_f32_16x16x32_bf16 v[32:35], v[174:177], v[190:193], v[32:35]
	v_mfma_f32_16x16x32_bf16 v[20:23], v[166:169], v[198:201], v[20:23]
	v_mfma_f32_16x16x32_bf16 v[16:19], v[174:177], v[198:201], v[16:19]
	v_mfma_f32_16x16x32_bf16 v[4:7], v[166:169], v[206:209], v[4:7]
	v_mfma_f32_16x16x32_bf16 v[0:3], v[174:177], v[206:209], v[0:3]
	s_setprio 0
	s_barrier
	s_add_i32 s58, 0, 0x18000
	s_add_i32 s59, 0, 0x1c000
	v_add_u32_e32 v152, s58, v157
	v_add_u32_e32 v174, s59, v157
	ds_read_b128 v[140:143], v152
	ds_read_b128 v[144:147], v152 offset:1024
	ds_read_b128 v[148:151], v152 offset:2048
	ds_read_b128 v[152:155], v152 offset:3072
	ds_read_b128 v[162:165], v174
	ds_read_b128 v[166:169], v174 offset:1024
	ds_read_b128 v[170:173], v174 offset:2048
	ds_read_b128 v[174:177], v174 offset:3072
	s_add_u32 s36, s36, 0x40000
	s_addc_u32 s37, s37, 0
	s_mov_b32 m0, s44
	v_lshl_add_u64 v[218:219], s[36:37], 0, v[128:129]
	ds_read_b128 v[178:181], v161 offset:32768
	ds_read_b128 v[182:185], v161 offset:33792
	ds_read_b128 v[186:189], v161 offset:34816
	ds_read_b128 v[190:193], v161 offset:35840
	ds_read_b128 v[194:197], v161 offset:36864
	ds_read_b128 v[198:201], v161 offset:37888
	ds_read_b128 v[202:205], v161 offset:38912
	ds_read_b128 v[206:209], v161 offset:39936
	global_load_lds_dwordx4 v[218:219], off
	v_lshl_add_u64 v[218:219], s[36:37], 0, v[132:133]
	s_mov_b32 m0, s45
	s_nop 0
	global_load_lds_dwordx4 v[218:219], off
	s_waitcnt vmcnt(8)
	s_waitcnt lgkmcnt(0)
	s_barrier
	s_setprio 1
	s_waitcnt lgkmcnt(0)
	v_mfma_f32_16x16x32_bf16 v[124:127], v[140:143], v[178:181], v[124:127]
	v_mfma_f32_16x16x32_bf16 v[120:123], v[148:151], v[178:181], v[120:123]
	v_mfma_f32_16x16x32_bf16 v[108:111], v[140:143], v[186:189], v[108:111]
	v_mfma_f32_16x16x32_bf16 v[104:107], v[148:151], v[186:189], v[104:107]
	v_mfma_f32_16x16x32_bf16 v[92:95], v[140:143], v[194:197], v[92:95]
	v_mfma_f32_16x16x32_bf16 v[88:91], v[148:151], v[194:197], v[88:91]
	v_mfma_f32_16x16x32_bf16 v[76:79], v[140:143], v[202:205], v[76:79]
	v_mfma_f32_16x16x32_bf16 v[72:75], v[148:151], v[202:205], v[72:75]
	v_mfma_f32_16x16x32_bf16 v[124:127], v[144:147], v[182:185], v[124:127]
	v_mfma_f32_16x16x32_bf16 v[120:123], v[152:155], v[182:185], v[120:123]
	v_mfma_f32_16x16x32_bf16 v[108:111], v[144:147], v[190:193], v[108:111]
	v_mfma_f32_16x16x32_bf16 v[104:107], v[152:155], v[190:193], v[104:107]
	v_mfma_f32_16x16x32_bf16 v[92:95], v[144:147], v[198:201], v[92:95]
	v_mfma_f32_16x16x32_bf16 v[88:91], v[152:155], v[198:201], v[88:91]
	v_mfma_f32_16x16x32_bf16 v[76:79], v[144:147], v[206:209], v[76:79]
	v_mfma_f32_16x16x32_bf16 v[72:75], v[152:155], v[206:209], v[72:75]
	s_setprio 0
	s_setprio 1
	v_mfma_f32_16x16x32_bf16 v[116:119], v[162:165], v[178:181], v[116:119]
	v_mfma_f32_16x16x32_bf16 v[112:115], v[170:173], v[178:181], v[112:115]
	v_mfma_f32_16x16x32_bf16 v[100:103], v[162:165], v[186:189], v[100:103]
	v_mfma_f32_16x16x32_bf16 v[96:99], v[170:173], v[186:189], v[96:99]
	v_mfma_f32_16x16x32_bf16 v[84:87], v[162:165], v[194:197], v[84:87]
	v_mfma_f32_16x16x32_bf16 v[80:83], v[170:173], v[194:197], v[80:83]
	v_mfma_f32_16x16x32_bf16 v[68:71], v[162:165], v[202:205], v[68:71]
	v_mfma_f32_16x16x32_bf16 v[64:67], v[170:173], v[202:205], v[64:67]
	v_mfma_f32_16x16x32_bf16 v[116:119], v[166:169], v[182:185], v[116:119]
	v_mfma_f32_16x16x32_bf16 v[112:115], v[174:177], v[182:185], v[112:115]
	v_mfma_f32_16x16x32_bf16 v[100:103], v[166:169], v[190:193], v[100:103]
	v_mfma_f32_16x16x32_bf16 v[96:99], v[174:177], v[190:193], v[96:99]
	v_mfma_f32_16x16x32_bf16 v[84:87], v[166:169], v[198:201], v[84:87]
	v_mfma_f32_16x16x32_bf16 v[80:83], v[174:177], v[198:201], v[80:83]
	v_mfma_f32_16x16x32_bf16 v[68:71], v[166:169], v[206:209], v[68:71]
	v_mfma_f32_16x16x32_bf16 v[64:67], v[174:177], v[206:209], v[64:67]
	s_setprio 0
	s_barrier
; #define PG8_STAGE(bufoff, gbase, voff) do { _Pragma("unroll") for (int _i = 0; _i < 2; ++_i) \
;         __builtin_amdgcn_global_load_lds((const unsigned*)((const char*)(gbase) + (voff)[_i]), (LAS unsigned*)(lds + (bufoff) + ldsw + _i * 8192), 16, 0, 0); } while (0)
; #define PG8_LDA(dst, b, h) do { _Pragma("unroll") for (int m = 0; m < 4; ++m) _Pragma("unroll") for (int k = 0; k < 2; ++k) dst[m][k] = *(const LAS bf16x8*)(lds + PG8_SA(b, h) + aoff + m * 2048 + k * 1024); } while (0)
; #define PG8_MMA(ai, bj, At, Bt) do { __builtin_amdgcn_s_setprio(1); _Pragma("unroll") for (int m = 0; m < 4; ++m) _Pragma("unroll") for (int n = 0; n < 2; ++n) _Pragma("unroll") for (int k = 0; k < 2; ++k) \
;         acc[ai][bj][m][n] = __builtin_amdgcn_mfma_f32_16x16x32_bf16(Bt[n][k], At[m][k], acc[ai][bj][m][n], 0, 0, 0); __builtin_amdgcn_s_setprio(0); } while (0)
; #define PG8_WAIT_V(n) asm volatile("s_waitcnt vmcnt(" #n ")" ::: "memory")
; #define PG8_WAIT_L(n) asm volatile("s_waitcnt lgkmcnt(" #n ")" ::: "memory")
; #define PG8_BAR __builtin_amdgcn_s_barrier()
; #define PG8_SCHED __builtin_amdgcn_sched_barrier(0)
; template <class Epi, class Sched>
; __device__ __forceinline__ void gemm_phase(LAS unsigned char* lds, const Gemm g, const Sched& S, const Epi& E, int wave_id) {
;     ...
;             PG8_LDA(At, 1, 1); PG8_STAGE(PG8_SB(1, 0), b3, voffB); PG8_STAGE(PG8_SB(1, 1), b3 + hstepB, voffB); PG8_STAGE(PG8_SA(1, 0), a3, voffA);
;             PG8_WAIT_V(8); PG8_WAIT_L(0); PG8_BAR; PG8_MMA(1, 0, At, B0); PG8_MMA(1, 1, At, B1); PG8_BAR; PG8_SCHED;
;         }
	s_add_i32 s36, s58, s39
	v_lshl_add_u64 v[210:211], v[210:211], 0, s[8:9]
	s_mov_b32 m0, s36
	ds_read_b128 v[178:181], v161 offset:49152
	ds_read_b128 v[182:185], v161 offset:50176
	ds_read_b128 v[186:189], v161 offset:51200
	ds_read_b128 v[190:193], v161 offset:52224
	ds_read_b128 v[194:197], v161 offset:53248
	ds_read_b128 v[198:201], v161 offset:54272
	ds_read_b128 v[202:205], v161 offset:55296
	ds_read_b128 v[206:209], v161 offset:56320
	global_load_lds_dwordx4 v[210:211], off
	s_add_i32 m0, s36, 0x2000
	s_add_u32 s34, s34, 0x40080
	v_lshl_add_u64 v[210:211], v[212:213], 0, s[8:9]
	s_addc_u32 s35, s35, 0
	s_add_i32 s36, s59, s39
	global_load_lds_dwordx4 v[210:211], off
	v_lshl_add_u64 v[210:211], s[34:35], 0, v[130:131]
	s_mov_b32 m0, s36
	s_nop 0
	global_load_lds_dwordx4 v[210:211], off
	v_lshl_add_u64 v[210:211], s[34:35], 0, v[134:135]
	s_add_i32 m0, s36, 0x2000
	s_nop 0
	global_load_lds_dwordx4 v[210:211], off
	v_lshl_add_u64 v[210:211], v[214:215], 0, s[8:9]
	s_mov_b32 m0, s46
	s_nop 0
	global_load_lds_dwordx4 v[210:211], off
	v_lshl_add_u64 v[210:211], v[216:217], 0, s[8:9]
	s_mov_b32 m0, s47
	s_nop 0
	global_load_lds_dwordx4 v[210:211], off
	s_waitcnt vmcnt(8)
	s_waitcnt lgkmcnt(0)
	s_barrier
	s_setprio 1
	s_waitcnt lgkmcnt(0)
	v_mfma_f32_16x16x32_bf16 v[60:63], v[140:143], v[178:181], v[60:63]
	v_mfma_f32_16x16x32_bf16 v[56:59], v[148:151], v[178:181], v[56:59]
	v_mfma_f32_16x16x32_bf16 v[44:47], v[140:143], v[186:189], v[44:47]
	v_mfma_f32_16x16x32_bf16 v[40:43], v[148:151], v[186:189], v[40:43]
	v_mfma_f32_16x16x32_bf16 v[28:31], v[140:143], v[194:197], v[28:31]
	v_mfma_f32_16x16x32_bf16 v[24:27], v[148:151], v[194:197], v[24:27]
	v_mfma_f32_16x16x32_bf16 v[12:15], v[140:143], v[202:205], v[12:15]
	v_mfma_f32_16x16x32_bf16 v[8:11], v[148:151], v[202:205], v[8:11]
	v_mfma_f32_16x16x32_bf16 v[60:63], v[144:147], v[182:185], v[60:63]
	v_mfma_f32_16x16x32_bf16 v[56:59], v[152:155], v[182:185], v[56:59]
	v_mfma_f32_16x16x32_bf16 v[44:47], v[144:147], v[190:193], v[44:47]
	v_mfma_f32_16x16x32_bf16 v[40:43], v[152:155], v[190:193], v[40:43]
	v_mfma_f32_16x16x32_bf16 v[28:31], v[144:147], v[198:201], v[28:31]
	v_mfma_f32_16x16x32_bf16 v[24:27], v[152:155], v[198:201], v[24:27]
	v_mfma_f32_16x16x32_bf16 v[12:15], v[144:147], v[206:209], v[12:15]
	v_mfma_f32_16x16x32_bf16 v[8:11], v[152:155], v[206:209], v[8:11]
	s_setprio 0
	s_setprio 1
	v_mfma_f32_16x16x32_bf16 v[52:55], v[162:165], v[178:181], v[52:55]
	v_mfma_f32_16x16x32_bf16 v[48:51], v[170:173], v[178:181], v[48:51]
	v_mfma_f32_16x16x32_bf16 v[36:39], v[162:165], v[186:189], v[36:39]
	v_mfma_f32_16x16x32_bf16 v[32:35], v[170:173], v[186:189], v[32:35]
	v_mfma_f32_16x16x32_bf16 v[20:23], v[162:165], v[194:197], v[20:23]
	v_mfma_f32_16x16x32_bf16 v[16:19], v[170:173], v[194:197], v[16:19]
	v_mfma_f32_16x16x32_bf16 v[4:7], v[162:165], v[202:205], v[4:7]
	v_mfma_f32_16x16x32_bf16 v[0:3], v[170:173], v[202:205], v[0:3]
	v_mfma_f32_16x16x32_bf16 v[52:55], v[166:169], v[182:185], v[52:55]
	v_mfma_f32_16x16x32_bf16 v[48:51], v[174:177], v[182:185], v[48:51]
	v_mfma_f32_16x16x32_bf16 v[36:39], v[166:169], v[190:193], v[36:39]
	v_mfma_f32_16x16x32_bf16 v[32:35], v[174:177], v[190:193], v[32:35]
	v_mfma_f32_16x16x32_bf16 v[20:23], v[166:169], v[198:201], v[20:23]
	v_mfma_f32_16x16x32_bf16 v[16:19], v[174:177], v[198:201], v[16:19]
	v_mfma_f32_16x16x32_bf16 v[4:7], v[166:169], v[206:209], v[4:7]
	v_mfma_f32_16x16x32_bf16 v[0:3], v[174:177], v[206:209], v[0:3]
	s_setprio 0
	s_add_i32 s55, s55, 2
	s_add_u32 s30, s30, 0x100
	s_addc_u32 s31, s31, 0
	s_add_u32 s53, s53, 0x100
	s_addc_u32 s54, s54, 0
	s_cmp_gt_u32 s55, 13
	s_barrier
	s_cbranch_scc0 .LBB0_804
	s_and_b64 vcc, exec, s[10:11]
	s_cbranch_vccz .LBB0_807
	s_barrier

; #define PG8_STAGE(bufoff, gbase, voff) do { _Pragma("unroll") for (int _i = 0; _i < 2; ++_i) \
;         __builtin_amdgcn_global_load_lds((const unsigned*)((const char*)(gbase) + (voff)[_i]), (LAS unsigned*)(lds + (bufoff) + ldsw + _i * 8192), 16, 0, 0); } while (0)
; #define PG8_LDA(dst, b, h) do { _Pragma("unroll") for (int m = 0; m < 4; ++m) _Pragma("unroll") for (int k = 0; k < 2; ++k) dst[m][k] = *(const LAS bf16x8*)(lds + PG8_SA(b, h) + aoff + m * 2048 + k * 1024); } while (0)
; #define PG8_LDB(dst, b, h) do { _Pragma("unroll") for (int n = 0; n < 2; ++n) _Pragma("unroll") for (int k = 0; k < 2; ++k) dst[n][k] = *(const LAS bf16x8*)(lds + PG8_SB(b, h) + boff + n * 2048 + k * 1024); } while (0)
; #define PG8_MMA(ai, bj, At, Bt) do { __builtin_amdgcn_s_setprio(1); _Pragma("unroll") for (int m = 0; m < 4; ++m) _Pragma("unroll") for (int n = 0; n < 2; ++n) _Pragma("unroll") for (int k = 0; k < 2; ++k) \
;         acc[ai][bj][m][n] = __builtin_amdgcn_mfma_f32_16x16x32_bf16(Bt[n][k], At[m][k], acc[ai][bj][m][n], 0, 0, 0); __builtin_amdgcn_s_setprio(0); } while (0)
; #define PG8_WAIT_V(n) asm volatile("s_waitcnt vmcnt(" #n ")" ::: "memory")
; #define PG8_WAIT_L(n) asm volatile("s_waitcnt lgkmcnt(" #n ")" ::: "memory")
; #define PG8_BAR __builtin_amdgcn_s_barrier()
; #define PG8_SCHED __builtin_amdgcn_sched_barrier(0)
; template <class Epi, class Sched>
; __device__ __forceinline__ void gemm_phase(LAS unsigned char* lds, const Gemm g, const Sched& S, const Epi& E, int wave_id) {
;     ...
;         for (int t = 0; t < nt; t += 2) {
;             const bool last = (t == nt - 2);
;             const char* a1 = cA + (size_t)(t + 1) * kstep;
;             const char* a2 = last ? nA : cA + (size_t)(t + 2) * kstep; const char* b2 = last ? nB : cB + (size_t)(t + 2) * kstep;
;             const char* a3 = a2 + kstep; const char* b3 = b2 + kstep;
;             PG8_LDB(B0, 0, 0); PG8_LDB(B1, 0, 1); PG8_SCHED; PG8_LDA(At, 0, 0); PG8_STAGE(PG8_SA(1, 1), a1 + hstepA, voffA);
;             PG8_WAIT_V(8); PG8_WAIT_L(0); PG8_BAR; PG8_MMA(0, 0, At, B0); PG8_MMA(0, 1, At, B1); PG8_BAR; PG8_SCHED;
;             PG8_LDA(At, 0, 1); PG8_STAGE(PG8_SB(0, 0), b2, voffB); PG8_STAGE(PG8_SB(0, 1), b2 + hstepB, voffB); PG8_STAGE(PG8_SA(0, 0), a2, voffA);
;             PG8_WAIT_V(8); PG8_WAIT_L(0); PG8_BAR; PG8_MMA(1, 0, At, B0); PG8_MMA(1, 1, At, B1); PG8_BAR; PG8_SCHED;
.LBB0_863:
	ds_read_b128 v[140:143], v159
	ds_read_b128 v[144:147], v159 offset:1024
	ds_read_b128 v[148:151], v159 offset:2048
	ds_read_b128 v[152:155], v159 offset:3072
	ds_read_b128 v[162:165], v160
	ds_read_b128 v[166:169], v160 offset:1024
	ds_read_b128 v[170:173], v160 offset:2048
	ds_read_b128 v[174:177], v160 offset:3072
	s_add_u32 s34, s30, 0xfffc0080
	s_addc_u32 s35, s31, -1
	s_cmp_eq_u32 s50, 12
	s_cselect_b32 s37, s19, s35
	s_cselect_b32 s36, s46, s34
	s_cselect_b32 s35, s17, s49
	s_cselect_b32 s34, s47, s48
	v_lshl_add_u64 v[210:211], s[30:31], 0, v[136:137]
	s_add_i32 m0, s27, 0xc000
	ds_read_b128 v[178:181], v161
	ds_read_b128 v[182:185], v161 offset:1024
	ds_read_b128 v[186:189], v161 offset:2048
	ds_read_b128 v[190:193], v161 offset:3072
	ds_read_b128 v[194:197], v161 offset:4096
	ds_read_b128 v[198:201], v161 offset:5120
	ds_read_b128 v[202:205], v161 offset:6144
	ds_read_b128 v[206:209], v161 offset:7168
	global_load_lds_dwordx4 v[210:211], off
	v_lshl_add_u64 v[210:211], s[30:31], 0, v[138:139]
	s_add_i32 m0, s27, 0xe000
	s_nop 0
	global_load_lds_dwordx4 v[210:211], off
	s_waitcnt vmcnt(8)
	s_waitcnt lgkmcnt(0)
	s_barrier
	s_setprio 1
	s_waitcnt lgkmcnt(0)
	v_mfma_f32_16x16x32_bf16 v[124:127], v[140:143], v[178:181], v[124:127]
	v_mfma_f32_16x16x32_bf16 v[120:123], v[148:151], v[178:181], v[120:123]
	v_mfma_f32_16x16x32_bf16 v[108:111], v[140:143], v[186:189], v[108:111]
	v_mfma_f32_16x16x32_bf16 v[104:107], v[148:151], v[186:189], v[104:107]
	v_mfma_f32_16x16x32_bf16 v[92:95], v[140:143], v[194:197], v[92:95]
	v_mfma_f32_16x16x32_bf16 v[88:91], v[148:151], v[194:197], v[88:91]
	v_mfma_f32_16x16x32_bf16 v[76:79], v[140:143], v[202:205], v[76:79]
	v_mfma_f32_16x16x32_bf16 v[72:75], v[148:151], v[202:205], v[72:75]
	v_mfma_f32_16x16x32_bf16 v[124:127], v[144:147], v[182:185], v[124:127]
	v_mfma_f32_16x16x32_bf16 v[120:123], v[152:155], v[182:185], v[120:123]
	v_mfma_f32_16x16x32_bf16 v[108:111], v[144:147], v[190:193], v[108:111]
	v_mfma_f32_16x16x32_bf16 v[104:107], v[152:155], v[190:193], v[104:107]
	v_mfma_f32_16x16x32_bf16 v[92:95], v[144:147], v[198:201], v[92:95]
	v_mfma_f32_16x16x32_bf16 v[88:91], v[152:155], v[198:201], v[88:91]
	v_mfma_f32_16x16x32_bf16 v[76:79], v[144:147], v[206:209], v[76:79]
	v_mfma_f32_16x16x32_bf16 v[72:75], v[152:155], v[206:209], v[72:75]
	s_setprio 0
	s_setprio 1
	v_mfma_f32_16x16x32_bf16 v[116:119], v[162:165], v[178:181], v[116:119]
	v_mfma_f32_16x16x32_bf16 v[112:115], v[170:173], v[178:181], v[112:115]
	v_mfma_f32_16x16x32_bf16 v[100:103], v[162:165], v[186:189], v[100:103]
	v_mfma_f32_16x16x32_bf16 v[96:99], v[170:173], v[186:189], v[96:99]
	v_mfma_f32_16x16x32_bf16 v[84:87], v[162:165], v[194:197], v[84:87]
	v_mfma_f32_16x16x32_bf16 v[80:83], v[170:173], v[194:197], v[80:83]
	v_mfma_f32_16x16x32_bf16 v[68:71], v[162:165], v[202:205], v[68:71]
	v_mfma_f32_16x16x32_bf16 v[64:67], v[170:173], v[202:205], v[64:67]
	v_mfma_f32_16x16x32_bf16 v[116:119], v[166:169], v[182:185], v[116:119]
	v_mfma_f32_16x16x32_bf16 v[112:115], v[174:177], v[182:185], v[112:115]
	v_mfma_f32_16x16x32_bf16 v[100:103], v[166:169], v[190:193], v[100:103]
	v_mfma_f32_16x16x32_bf16 v[96:99], v[174:177], v[190:193], v[96:99]
	v_mfma_f32_16x16x32_bf16 v[84:87], v[166:169], v[198:201], v[84:87]
	v_mfma_f32_16x16x32_bf16 v[80:83], v[174:177], v[198:201], v[80:83]
	v_mfma_f32_16x16x32_bf16 v[68:71], v[166:169], v[206:209], v[68:71]
	v_mfma_f32_16x16x32_bf16 v[64:67], v[174:177], v[206:209], v[64:67]
	s_setprio 0
	s_barrier
	s_add_i32 s51, s43, s38
	v_lshl_add_u64 v[210:211], s[34:35], 0, v[130:131]
	s_mov_b32 m0, s51
	ds_read_b128 v[178:181], v161 offset:16384
	ds_read_b128 v[182:185], v161 offset:17408
	ds_read_b128 v[186:189], v161 offset:18432
	ds_read_b128 v[190:193], v161 offset:19456
	ds_read_b128 v[194:197], v161 offset:20480
	ds_read_b128 v[198:201], v161 offset:21504
	ds_read_b128 v[202:205], v161 offset:22528
	ds_read_b128 v[206:209], v161 offset:23552
	global_load_lds_dwordx4 v[210:211], off
	s_add_i32 m0, s51, 0x2000
	s_add_u32 s52, s34, 0x40000
	v_lshl_add_u64 v[212:213], s[34:35], 0, v[134:135]
	s_addc_u32 s53, s35, 0
	s_add_i32 s51, s44, s38
	global_load_lds_dwordx4 v[212:213], off
	v_lshl_add_u64 v[214:215], s[52:53], 0, v[130:131]
	s_mov_b32 m0, s51
	v_lshl_add_u64 v[216:217], s[36:37], 0, v[132:133]
	global_load_lds_dwordx4 v[214:215], off
	v_lshl_add_u64 v[214:215], s[52:53], 0, v[134:135]
	s_add_i32 m0, s51, 0x2000
	s_nop 0
	global_load_lds_dwordx4 v[214:215], off
	v_lshl_add_u64 v[214:215], s[36:37], 0, v[128:129]
	s_mov_b32 m0, s27
	s_nop 0
	global_load_lds_dwordx4 v[214:215], off
	s_mov_b32 m0, s29
	s_nop 0
	global_load_lds_dwordx4 v[216:217], off
	s_waitcnt vmcnt(8)
	s_waitcnt lgkmcnt(0)
	s_barrier
; #define PG8_STAGE(bufoff, gbase, voff) do { _Pragma("unroll") for (int _i = 0; _i < 2; ++_i) \
;         __builtin_amdgcn_global_load_lds((const unsigned*)((const char*)(gbase) + (voff)[_i]), (LAS unsigned*)(lds + (bufoff) + ldsw + _i * 8192), 16, 0, 0); } while (0)
; #define PG8_LDA(dst, b, h) do { _Pragma("unroll") for (int m = 0; m < 4; ++m) _Pragma("unroll") for (int k = 0; k < 2; ++k) dst[m][k] = *(const LAS bf16x8*)(lds + PG8_SA(b, h) + aoff + m * 2048 + k * 1024); } while (0)
; #define PG8_LDB(dst, b, h) do { _Pragma("unroll") for (int n = 0; n < 2; ++n) _Pragma("unroll") for (int k = 0; k < 2; ++k) dst[n][k] = *(const LAS bf16x8*)(lds + PG8_SB(b, h) + boff + n * 2048 + k * 1024); } while (0)
; #define PG8_MMA(ai, bj, At, Bt) do { __builtin_amdgcn_s_setprio(1); _Pragma("unroll") for (int m = 0; m < 4; ++m) _Pragma("unroll") for (int n = 0; n < 2; ++n) _Pragma("unroll") for (int k = 0; k < 2; ++k) \
;         acc[ai][bj][m][n] = __builtin_amdgcn_mfma_f32_16x16x32_bf16(Bt[n][k], At[m][k], acc[ai][bj][m][n], 0, 0, 0); __builtin_amdgcn_s_setprio(0); } while (0)
; #define PG8_WAIT_V(n) asm volatile("s_waitcnt vmcnt(" #n ")" ::: "memory")
; #define PG8_WAIT_L(n) asm volatile("s_waitcnt lgkmcnt(" #n ")" ::: "memory")
; #define PG8_BAR __builtin_amdgcn_s_barrier()
; #define PG8_SCHED __builtin_amdgcn_sched_barrier(0)
; template <class Epi, class Sched>
; __device__ __forceinline__ void gemm_phase(LAS unsigned char* lds, const Gemm g, const Sched& S, const Epi& E, int wave_id) {
;     ...
;             PG8_WAIT_V(8); PG8_WAIT_L(0); PG8_BAR; PG8_MMA(1, 0, At, B0); PG8_MMA(1, 1, At, B1); PG8_BAR; PG8_SCHED;
;             PG8_LDB(B0, 1, 0); PG8_LDB(B1, 1, 1); PG8_SCHED; PG8_LDA(At, 1, 0); PG8_STAGE(PG8_SA(0, 1), a2 + hstepA, voffA);
;             PG8_WAIT_V(8); PG8_WAIT_L(0); PG8_BAR; PG8_MMA(0, 0, At, B0); PG8_MMA(0, 1, At, B1); PG8_BAR; PG8_SCHED;
	s_setprio 1
	s_waitcnt lgkmcnt(0)
	v_mfma_f32_16x16x32_bf16 v[60:63], v[140:143], v[178:181], v[60:63]
	v_mfma_f32_16x16x32_bf16 v[56:59], v[148:151], v[178:181], v[56:59]
	v_mfma_f32_16x16x32_bf16 v[44:47], v[140:143], v[186:189], v[44:47]
	v_mfma_f32_16x16x32_bf16 v[40:43], v[148:151], v[186:189], v[40:43]
	v_mfma_f32_16x16x32_bf16 v[28:31], v[140:143], v[194:197], v[28:31]
	v_mfma_f32_16x16x32_bf16 v[24:27], v[148:151], v[194:197], v[24:27]
	v_mfma_f32_16x16x32_bf16 v[12:15], v[140:143], v[202:205], v[12:15]
	v_mfma_f32_16x16x32_bf16 v[8:11], v[148:151], v[202:205], v[8:11]
	v_mfma_f32_16x16x32_bf16 v[60:63], v[144:147], v[182:185], v[60:63]
	v_mfma_f32_16x16x32_bf16 v[56:59], v[152:155], v[182:185], v[56:59]
	v_mfma_f32_16x16x32_bf16 v[44:47], v[144:147], v[190:193], v[44:47]
	v_mfma_f32_16x16x32_bf16 v[40:43], v[152:155], v[190:193], v[40:43]
	v_mfma_f32_16x16x32_bf16 v[28:31], v[144:147], v[198:201], v[28:31]
	v_mfma_f32_16x16x32_bf16 v[24:27], v[152:155], v[198:201], v[24:27]
	v_mfma_f32_16x16x32_bf16 v[12:15], v[144:147], v[206:209], v[12:15]
	v_mfma_f32_16x16x32_bf16 v[8:11], v[152:155], v[206:209], v[8:11]
	s_setprio 0
	s_setprio 1
	v_mfma_f32_16x16x32_bf16 v[52:55], v[162:165], v[178:181], v[52:55]
	v_mfma_f32_16x16x32_bf16 v[48:51], v[170:173], v[178:181], v[48:51]
	v_mfma_f32_16x16x32_bf16 v[36:39], v[162:165], v[186:189], v[36:39]
	v_mfma_f32_16x16x32_bf16 v[32:35], v[170:173], v[186:189], v[32:35]
	v_mfma_f32_16x16x32_bf16 v[20:23], v[162:165], v[194:197], v[20:23]
	v_mfma_f32_16x16x32_bf16 v[16:19], v[170:173], v[194:197], v[16:19]
	v_mfma_f32_16x16x32_bf16 v[4:7], v[162:165], v[202:205], v[4:7]
	v_mfma_f32_16x16x32_bf16 v[0:3], v[170:173], v[202:205], v[0:3]
	v_mfma_f32_16x16x32_bf16 v[52:55], v[166:169], v[182:185], v[52:55]
	v_mfma_f32_16x16x32_bf16 v[48:51], v[174:177], v[182:185], v[48:51]
	v_mfma_f32_16x16x32_bf16 v[36:39], v[166:169], v[190:193], v[36:39]
	v_mfma_f32_16x16x32_bf16 v[32:35], v[174:177], v[190:193], v[32:35]
	v_mfma_f32_16x16x32_bf16 v[20:23], v[166:169], v[198:201], v[20:23]
	v_mfma_f32_16x16x32_bf16 v[16:19], v[174:177], v[198:201], v[16:19]
	v_mfma_f32_16x16x32_bf16 v[4:7], v[166:169], v[206:209], v[4:7]
	v_mfma_f32_16x16x32_bf16 v[0:3], v[174:177], v[206:209], v[0:3]
	s_setprio 0
	s_barrier
	s_add_i32 s51, 0, 0x18000
	s_add_i32 s52, 0, 0x1c000
	v_add_u32_e32 v152, s51, v157
	v_add_u32_e32 v174, s52, v157
	ds_read_b128 v[140:143], v152
	ds_read_b128 v[144:147], v152 offset:1024
	ds_read_b128 v[148:151], v152 offset:2048
	ds_read_b128 v[152:155], v152 offset:3072
	ds_read_b128 v[162:165], v174
	ds_read_b128 v[166:169], v174 offset:1024
	ds_read_b128 v[170:173], v174 offset:2048
	ds_read_b128 v[174:177], v174 offset:3072
	s_add_u32 s36, s36, 0x40000
	s_addc_u32 s37, s37, 0
	s_mov_b32 m0, s39
	v_lshl_add_u64 v[218:219], s[36:37], 0, v[128:129]
	ds_read_b128 v[178:181], v161 offset:32768
	ds_read_b128 v[182:185], v161 offset:33792
	ds_read_b128 v[186:189], v161 offset:34816
	ds_read_b128 v[190:193], v161 offset:35840
	ds_read_b128 v[194:197], v161 offset:36864
	ds_read_b128 v[198:201], v161 offset:37888
	ds_read_b128 v[202:205], v161 offset:38912
	ds_read_b128 v[206:209], v161 offset:39936
	global_load_lds_dwordx4 v[218:219], off
	v_lshl_add_u64 v[218:219], s[36:37], 0, v[132:133]
	s_mov_b32 m0, s40
	s_nop 0
	global_load_lds_dwordx4 v[218:219], off
	s_waitcnt vmcnt(8)
	s_waitcnt lgkmcnt(0)
	s_barrier
	s_setprio 1
	s_waitcnt lgkmcnt(0)
	v_mfma_f32_16x16x32_bf16 v[124:127], v[140:143], v[178:181], v[124:127]
	v_mfma_f32_16x16x32_bf16 v[120:123], v[148:151], v[178:181], v[120:123]
	v_mfma_f32_16x16x32_bf16 v[108:111], v[140:143], v[186:189], v[108:111]
	v_mfma_f32_16x16x32_bf16 v[104:107], v[148:151], v[186:189], v[104:107]
	v_mfma_f32_16x16x32_bf16 v[92:95], v[140:143], v[194:197], v[92:95]
	v_mfma_f32_16x16x32_bf16 v[88:91], v[148:151], v[194:197], v[88:91]
	v_mfma_f32_16x16x32_bf16 v[76:79], v[140:143], v[202:205], v[76:79]
	v_mfma_f32_16x16x32_bf16 v[72:75], v[148:151], v[202:205], v[72:75]
	v_mfma_f32_16x16x32_bf16 v[124:127], v[144:147], v[182:185], v[124:127]
	v_mfma_f32_16x16x32_bf16 v[120:123], v[152:155], v[182:185], v[120:123]
	v_mfma_f32_16x16x32_bf16 v[108:111], v[144:147], v[190:193], v[108:111]
	v_mfma_f32_16x16x32_bf16 v[104:107], v[152:155], v[190:193], v[104:107]
	v_mfma_f32_16x16x32_bf16 v[92:95], v[144:147], v[198:201], v[92:95]
	v_mfma_f32_16x16x32_bf16 v[88:91], v[152:155], v[198:201], v[88:91]
	v_mfma_f32_16x16x32_bf16 v[76:79], v[144:147], v[206:209], v[76:79]
	v_mfma_f32_16x16x32_bf16 v[72:75], v[152:155], v[206:209], v[72:75]
	s_setprio 0
	s_setprio 1
	v_mfma_f32_16x16x32_bf16 v[116:119], v[162:165], v[178:181], v[116:119]
	v_mfma_f32_16x16x32_bf16 v[112:115], v[170:173], v[178:181], v[112:115]
	v_mfma_f32_16x16x32_bf16 v[100:103], v[162:165], v[186:189], v[100:103]
	v_mfma_f32_16x16x32_bf16 v[96:99], v[170:173], v[186:189], v[96:99]
	v_mfma_f32_16x16x32_bf16 v[84:87], v[162:165], v[194:197], v[84:87]
	v_mfma_f32_16x16x32_bf16 v[80:83], v[170:173], v[194:197], v[80:83]
	v_mfma_f32_16x16x32_bf16 v[68:71], v[162:165], v[202:205], v[68:71]
	v_mfma_f32_16x16x32_bf16 v[64:67], v[170:173], v[202:205], v[64:67]
	v_mfma_f32_16x16x32_bf16 v[116:119], v[166:169], v[182:185], v[116:119]
	v_mfma_f32_16x16x32_bf16 v[112:115], v[174:177], v[182:185], v[112:115]
	v_mfma_f32_16x16x32_bf16 v[100:103], v[166:169], v[190:193], v[100:103]
	v_mfma_f32_16x16x32_bf16 v[96:99], v[174:177], v[190:193], v[96:99]
	v_mfma_f32_16x16x32_bf16 v[84:87], v[166:169], v[198:201], v[84:87]
	v_mfma_f32_16x16x32_bf16 v[80:83], v[174:177], v[198:201], v[80:83]
	v_mfma_f32_16x16x32_bf16 v[68:71], v[166:169], v[206:209], v[68:71]
	v_mfma_f32_16x16x32_bf16 v[64:67], v[174:177], v[206:209], v[64:67]
	s_setprio 0
	s_barrier
; #define PG8_STAGE(bufoff, gbase, voff) do { _Pragma("unroll") for (int _i = 0; _i < 2; ++_i) \
;         __builtin_amdgcn_global_load_lds((const unsigned*)((const char*)(gbase) + (voff)[_i]), (LAS unsigned*)(lds + (bufoff) + ldsw + _i * 8192), 16, 0, 0); } while (0)
; #define PG8_LDA(dst, b, h) do { _Pragma("unroll") for (int m = 0; m < 4; ++m) _Pragma("unroll") for (int k = 0; k < 2; ++k) dst[m][k] = *(const LAS bf16x8*)(lds + PG8_SA(b, h) + aoff + m * 2048 + k * 1024); } while (0)
; #define PG8_MMA(ai, bj, At, Bt) do { __builtin_amdgcn_s_setprio(1); _Pragma("unroll") for (int m = 0; m < 4; ++m) _Pragma("unroll") for (int n = 0; n < 2; ++n) _Pragma("unroll") for (int k = 0; k < 2; ++k) \
;         acc[ai][bj][m][n] = __builtin_amdgcn_mfma_f32_16x16x32_bf16(Bt[n][k], At[m][k], acc[ai][bj][m][n], 0, 0, 0); __builtin_amdgcn_s_setprio(0); } while (0)
; #define PG8_WAIT_V(n) asm volatile("s_waitcnt vmcnt(" #n ")" ::: "memory")
; #define PG8_WAIT_L(n) asm volatile("s_waitcnt lgkmcnt(" #n ")" ::: "memory")
; #define PG8_BAR __builtin_amdgcn_s_barrier()
; #define PG8_SCHED __builtin_amdgcn_sched_barrier(0)
; template <class Epi, class Sched>
; __device__ __forceinline__ void gemm_phase(LAS unsigned char* lds, const Gemm g, const Sched& S, const Epi& E, int wave_id) {
;     ...
;             PG8_LDA(At, 1, 1); PG8_STAGE(PG8_SB(1, 0), b3, voffB); PG8_STAGE(PG8_SB(1, 1), b3 + hstepB, voffB); PG8_STAGE(PG8_SA(1, 0), a3, voffA);
;             PG8_WAIT_V(8); PG8_WAIT_L(0); PG8_BAR; PG8_MMA(1, 0, At, B0); PG8_MMA(1, 1, At, B1); PG8_BAR; PG8_SCHED;
;         }
	s_add_i32 s36, s51, s38
	v_lshl_add_u64 v[210:211], v[210:211], 0, s[8:9]
	s_mov_b32 m0, s36
	ds_read_b128 v[178:181], v161 offset:49152
	ds_read_b128 v[182:185], v161 offset:50176
	ds_read_b128 v[186:189], v161 offset:51200
	ds_read_b128 v[190:193], v161 offset:52224
	ds_read_b128 v[194:197], v161 offset:53248
	ds_read_b128 v[198:201], v161 offset:54272
	ds_read_b128 v[202:205], v161 offset:55296
	ds_read_b128 v[206:209], v161 offset:56320
	global_load_lds_dwordx4 v[210:211], off
	s_add_i32 m0, s36, 0x2000
	s_add_u32 s34, s34, 0x40080
	v_lshl_add_u64 v[210:211], v[212:213], 0, s[8:9]
	s_addc_u32 s35, s35, 0
	s_add_i32 s36, s52, s38
	global_load_lds_dwordx4 v[210:211], off
	v_lshl_add_u64 v[210:211], s[34:35], 0, v[130:131]
	s_mov_b32 m0, s36
	s_nop 0
	global_load_lds_dwordx4 v[210:211], off
	v_lshl_add_u64 v[210:211], s[34:35], 0, v[134:135]
	s_add_i32 m0, s36, 0x2000
	s_nop 0
	global_load_lds_dwordx4 v[210:211], off
	v_lshl_add_u64 v[210:211], v[214:215], 0, s[8:9]
	s_mov_b32 m0, s41
	s_nop 0
	global_load_lds_dwordx4 v[210:211], off
	v_lshl_add_u64 v[210:211], v[216:217], 0, s[8:9]
	s_mov_b32 m0, s42
	s_nop 0
	global_load_lds_dwordx4 v[210:211], off
	s_waitcnt vmcnt(8)
	s_waitcnt lgkmcnt(0)
	s_barrier
	s_setprio 1
	s_waitcnt lgkmcnt(0)
	v_mfma_f32_16x16x32_bf16 v[60:63], v[140:143], v[178:181], v[60:63]
	v_mfma_f32_16x16x32_bf16 v[56:59], v[148:151], v[178:181], v[56:59]
	v_mfma_f32_16x16x32_bf16 v[44:47], v[140:143], v[186:189], v[44:47]
	v_mfma_f32_16x16x32_bf16 v[40:43], v[148:151], v[186:189], v[40:43]
	v_mfma_f32_16x16x32_bf16 v[28:31], v[140:143], v[194:197], v[28:31]
	v_mfma_f32_16x16x32_bf16 v[24:27], v[148:151], v[194:197], v[24:27]
	v_mfma_f32_16x16x32_bf16 v[12:15], v[140:143], v[202:205], v[12:15]
	v_mfma_f32_16x16x32_bf16 v[8:11], v[148:151], v[202:205], v[8:11]
	v_mfma_f32_16x16x32_bf16 v[60:63], v[144:147], v[182:185], v[60:63]
	v_mfma_f32_16x16x32_bf16 v[56:59], v[152:155], v[182:185], v[56:59]
	v_mfma_f32_16x16x32_bf16 v[44:47], v[144:147], v[190:193], v[44:47]
	v_mfma_f32_16x16x32_bf16 v[40:43], v[152:155], v[190:193], v[40:43]
	v_mfma_f32_16x16x32_bf16 v[28:31], v[144:147], v[198:201], v[28:31]
	v_mfma_f32_16x16x32_bf16 v[24:27], v[152:155], v[198:201], v[24:27]
	v_mfma_f32_16x16x32_bf16 v[12:15], v[144:147], v[206:209], v[12:15]
	v_mfma_f32_16x16x32_bf16 v[8:11], v[152:155], v[206:209], v[8:11]
	s_setprio 0
	s_setprio 1
	v_mfma_f32_16x16x32_bf16 v[52:55], v[162:165], v[178:181], v[52:55]
	v_mfma_f32_16x16x32_bf16 v[48:51], v[170:173], v[178:181], v[48:51]
	v_mfma_f32_16x16x32_bf16 v[36:39], v[162:165], v[186:189], v[36:39]
	v_mfma_f32_16x16x32_bf16 v[32:35], v[170:173], v[186:189], v[32:35]
	v_mfma_f32_16x16x32_bf16 v[20:23], v[162:165], v[194:197], v[20:23]
	v_mfma_f32_16x16x32_bf16 v[16:19], v[170:173], v[194:197], v[16:19]
	v_mfma_f32_16x16x32_bf16 v[4:7], v[162:165], v[202:205], v[4:7]
	v_mfma_f32_16x16x32_bf16 v[0:3], v[170:173], v[202:205], v[0:3]
	v_mfma_f32_16x16x32_bf16 v[52:55], v[166:169], v[182:185], v[52:55]
	v_mfma_f32_16x16x32_bf16 v[48:51], v[174:177], v[182:185], v[48:51]
	v_mfma_f32_16x16x32_bf16 v[36:39], v[166:169], v[190:193], v[36:39]
	v_mfma_f32_16x16x32_bf16 v[32:35], v[174:177], v[190:193], v[32:35]
	v_mfma_f32_16x16x32_bf16 v[20:23], v[166:169], v[198:201], v[20:23]
	v_mfma_f32_16x16x32_bf16 v[16:19], v[174:177], v[198:201], v[16:19]
	v_mfma_f32_16x16x32_bf16 v[4:7], v[166:169], v[206:209], v[4:7]
	v_mfma_f32_16x16x32_bf16 v[0:3], v[174:177], v[206:209], v[0:3]
	s_setprio 0
	s_add_i32 s50, s50, 2
	s_add_u32 s30, s30, 0x100
	s_addc_u32 s31, s31, 0
	s_add_u32 s48, s48, 0x100
	s_addc_u32 s49, s49, 0
	s_cmp_gt_u32 s50, 13
	s_barrier
	s_cbranch_scc0 .LBB0_863
	s_and_b64 vcc, exec, s[10:11]
	s_cbranch_vccz .LBB0_866
	s_barrier

; #define PG8_STAGE(bufoff, gbase, voff) do { _Pragma("unroll") for (int _i = 0; _i < 2; ++_i) \
;         __builtin_amdgcn_global_load_lds((const unsigned*)((const char*)(gbase) + (voff)[_i]), (LAS unsigned*)(lds + (bufoff) + ldsw + _i * 8192), 16, 0, 0); } while (0)
; #define PG8_LDA(dst, b, h) do { _Pragma("unroll") for (int m = 0; m < 4; ++m) _Pragma("unroll") for (int k = 0; k < 2; ++k) dst[m][k] = *(const LAS bf16x8*)(lds + PG8_SA(b, h) + aoff + m * 2048 + k * 1024); } while (0)
; #define PG8_LDB(dst, b, h) do { _Pragma("unroll") for (int n = 0; n < 2; ++n) _Pragma("unroll") for (int k = 0; k < 2; ++k) dst[n][k] = *(const LAS bf16x8*)(lds + PG8_SB(b, h) + boff + n * 2048 + k * 1024); } while (0)
; #define PG8_MMA(ai, bj, At, Bt) do { __builtin_amdgcn_s_setprio(1); _Pragma("unroll") for (int m = 0; m < 4; ++m) _Pragma("unroll") for (int n = 0; n < 2; ++n) _Pragma("unroll") for (int k = 0; k < 2; ++k) \
;         acc[ai][bj][m][n] = __builtin_amdgcn_mfma_f32_16x16x32_bf16(Bt[n][k], At[m][k], acc[ai][bj][m][n], 0, 0, 0); __builtin_amdgcn_s_setprio(0); } while (0)
; #define PG8_WAIT_V(n) asm volatile("s_waitcnt vmcnt(" #n ")" ::: "memory")
; #define PG8_WAIT_L(n) asm volatile("s_waitcnt lgkmcnt(" #n ")" ::: "memory")
; #define PG8_BAR __builtin_amdgcn_s_barrier()
; #define PG8_SCHED __builtin_amdgcn_sched_barrier(0)
; template <class Epi, class Sched>
; __device__ __forceinline__ void gemm_phase(LAS unsigned char* lds, const Gemm g, const Sched& S, const Epi& E, int wave_id) {
;     ...
;         for (int t = 0; t < nt; t += 2) {
;             const bool last = (t == nt - 2);
;             const char* a1 = cA + (size_t)(t + 1) * kstep;
;             const char* a2 = last ? nA : cA + (size_t)(t + 2) * kstep; const char* b2 = last ? nB : cB + (size_t)(t + 2) * kstep;
;             const char* a3 = a2 + kstep; const char* b3 = b2 + kstep;
;             PG8_LDB(B0, 0, 0); PG8_LDB(B1, 0, 1); PG8_SCHED; PG8_LDA(At, 0, 0); PG8_STAGE(PG8_SA(1, 1), a1 + hstepA, voffA);
;             PG8_WAIT_V(8); PG8_WAIT_L(0); PG8_BAR; PG8_MMA(0, 0, At, B0); PG8_MMA(0, 1, At, B1); PG8_BAR; PG8_SCHED;
;             PG8_LDA(At, 0, 1); PG8_STAGE(PG8_SB(0, 0), b2, voffB); PG8_STAGE(PG8_SB(0, 1), b2 + hstepB, voffB); PG8_STAGE(PG8_SA(0, 0), a2, voffA);
;             PG8_WAIT_V(8); PG8_WAIT_L(0); PG8_BAR; PG8_MMA(1, 0, At, B0); PG8_MMA(1, 1, At, B1); PG8_BAR; PG8_SCHED;
.LBB0_960:
	ds_read_b128 v[156:159], v151
	ds_read_b128 v[160:163], v151 offset:1024
	ds_read_b128 v[164:167], v151 offset:2048
	ds_read_b128 v[168:171], v151 offset:3072
	ds_read_b128 v[172:175], v152
	ds_read_b128 v[176:179], v152 offset:1024
	ds_read_b128 v[180:183], v152 offset:2048
	ds_read_b128 v[184:187], v152 offset:3072
	s_add_u32 s26, s24, 0xfffc0080
	s_addc_u32 s27, s25, -1
	s_cmp_eq_u32 s53, 12
	s_cselect_b32 s29, s17, s27
	s_cselect_b32 s28, s49, s26
	s_cselect_b32 s27, s15, s52
	s_cselect_b32 s26, s50, s51
	v_lshl_add_u64 v[220:221], s[24:25], 0, v[142:143]
	s_add_i32 m0, s37, 0xc000
	ds_read_b128 v[188:191], v153
	ds_read_b128 v[192:195], v153 offset:1024
	ds_read_b128 v[196:199], v153 offset:2048
	ds_read_b128 v[200:203], v153 offset:3072
	ds_read_b128 v[204:207], v153 offset:4096
	ds_read_b128 v[208:211], v153 offset:5120
	ds_read_b128 v[212:215], v153 offset:6144
	ds_read_b128 v[216:219], v153 offset:7168
	global_load_lds_dwordx4 v[220:221], off
	v_lshl_add_u64 v[220:221], s[24:25], 0, v[144:145]
	s_add_i32 m0, s37, 0xe000
	s_nop 0
	global_load_lds_dwordx4 v[220:221], off
	s_waitcnt vmcnt(8)
	s_waitcnt lgkmcnt(0)
	s_barrier
	s_setprio 1
	s_waitcnt lgkmcnt(0)
	v_mfma_f32_16x16x32_bf16 v[124:127], v[156:159], v[188:191], v[124:127]
	v_mfma_f32_16x16x32_bf16 v[120:123], v[164:167], v[188:191], v[120:123]
	v_mfma_f32_16x16x32_bf16 v[108:111], v[156:159], v[196:199], v[108:111]
	v_mfma_f32_16x16x32_bf16 v[104:107], v[164:167], v[196:199], v[104:107]
	v_mfma_f32_16x16x32_bf16 v[92:95], v[156:159], v[204:207], v[92:95]
	v_mfma_f32_16x16x32_bf16 v[88:91], v[164:167], v[204:207], v[88:91]
	v_mfma_f32_16x16x32_bf16 v[76:79], v[156:159], v[212:215], v[76:79]
	v_mfma_f32_16x16x32_bf16 v[72:75], v[164:167], v[212:215], v[72:75]
	v_mfma_f32_16x16x32_bf16 v[124:127], v[160:163], v[192:195], v[124:127]
	v_mfma_f32_16x16x32_bf16 v[120:123], v[168:171], v[192:195], v[120:123]
	v_mfma_f32_16x16x32_bf16 v[108:111], v[160:163], v[200:203], v[108:111]
	v_mfma_f32_16x16x32_bf16 v[104:107], v[168:171], v[200:203], v[104:107]
	v_mfma_f32_16x16x32_bf16 v[92:95], v[160:163], v[208:211], v[92:95]
	v_mfma_f32_16x16x32_bf16 v[88:91], v[168:171], v[208:211], v[88:91]
	v_mfma_f32_16x16x32_bf16 v[76:79], v[160:163], v[216:219], v[76:79]
	v_mfma_f32_16x16x32_bf16 v[72:75], v[168:171], v[216:219], v[72:75]
	s_setprio 0
	s_setprio 1
	v_mfma_f32_16x16x32_bf16 v[116:119], v[172:175], v[188:191], v[116:119]
	v_mfma_f32_16x16x32_bf16 v[112:115], v[180:183], v[188:191], v[112:115]
	v_mfma_f32_16x16x32_bf16 v[100:103], v[172:175], v[196:199], v[100:103]
	v_mfma_f32_16x16x32_bf16 v[96:99], v[180:183], v[196:199], v[96:99]
	v_mfma_f32_16x16x32_bf16 v[84:87], v[172:175], v[204:207], v[84:87]
	v_mfma_f32_16x16x32_bf16 v[80:83], v[180:183], v[204:207], v[80:83]
	v_mfma_f32_16x16x32_bf16 v[68:71], v[172:175], v[212:215], v[68:71]
	v_mfma_f32_16x16x32_bf16 v[64:67], v[180:183], v[212:215], v[64:67]
	v_mfma_f32_16x16x32_bf16 v[116:119], v[176:179], v[192:195], v[116:119]
	v_mfma_f32_16x16x32_bf16 v[112:115], v[184:187], v[192:195], v[112:115]
	v_mfma_f32_16x16x32_bf16 v[100:103], v[176:179], v[200:203], v[100:103]
	v_mfma_f32_16x16x32_bf16 v[96:99], v[184:187], v[200:203], v[96:99]
	v_mfma_f32_16x16x32_bf16 v[84:87], v[176:179], v[208:211], v[84:87]
	v_mfma_f32_16x16x32_bf16 v[80:83], v[184:187], v[208:211], v[80:83]
	v_mfma_f32_16x16x32_bf16 v[68:71], v[176:179], v[216:219], v[68:71]
	v_mfma_f32_16x16x32_bf16 v[64:67], v[184:187], v[216:219], v[64:67]
	s_setprio 0
	s_barrier
	s_add_i32 s54, s47, s2
	v_lshl_add_u64 v[220:221], s[26:27], 0, v[130:131]
	s_mov_b32 m0, s54
	ds_read_b128 v[188:191], v153 offset:16384
	ds_read_b128 v[192:195], v153 offset:17408
	ds_read_b128 v[196:199], v153 offset:18432
	ds_read_b128 v[200:203], v153 offset:19456
	ds_read_b128 v[204:207], v153 offset:20480
	ds_read_b128 v[208:211], v153 offset:21504
	ds_read_b128 v[212:215], v153 offset:22528
	ds_read_b128 v[216:219], v153 offset:23552
	global_load_lds_dwordx4 v[220:221], off
	s_add_i32 m0, s54, 0x2000
	s_add_u32 s54, s26, 0x40000
	v_lshl_add_u64 v[222:223], s[26:27], 0, v[134:135]
	s_addc_u32 s55, s27, 0
	s_add_i32 s58, s48, s2
	global_load_lds_dwordx4 v[222:223], off
	v_lshl_add_u64 v[224:225], s[54:55], 0, v[130:131]
	s_mov_b32 m0, s58
	v_lshl_add_u64 v[226:227], s[28:29], 0, v[132:133]
	global_load_lds_dwordx4 v[224:225], off
	v_lshl_add_u64 v[224:225], s[54:55], 0, v[134:135]
	s_add_i32 m0, s58, 0x2000
	s_nop 0
	global_load_lds_dwordx4 v[224:225], off
	v_lshl_add_u64 v[224:225], s[28:29], 0, v[128:129]
	s_mov_b32 m0, s37
	s_nop 0
	global_load_lds_dwordx4 v[224:225], off
	s_mov_b32 m0, s38
	s_nop 0
	global_load_lds_dwordx4 v[226:227], off
	s_waitcnt vmcnt(8)
	s_waitcnt lgkmcnt(0)
	s_barrier
; #define PG8_STAGE(bufoff, gbase, voff) do { _Pragma("unroll") for (int _i = 0; _i < 2; ++_i) \
;         __builtin_amdgcn_global_load_lds((const unsigned*)((const char*)(gbase) + (voff)[_i]), (LAS unsigned*)(lds + (bufoff) + ldsw + _i * 8192), 16, 0, 0); } while (0)
; #define PG8_LDA(dst, b, h) do { _Pragma("unroll") for (int m = 0; m < 4; ++m) _Pragma("unroll") for (int k = 0; k < 2; ++k) dst[m][k] = *(const LAS bf16x8*)(lds + PG8_SA(b, h) + aoff + m * 2048 + k * 1024); } while (0)
; #define PG8_LDB(dst, b, h) do { _Pragma("unroll") for (int n = 0; n < 2; ++n) _Pragma("unroll") for (int k = 0; k < 2; ++k) dst[n][k] = *(const LAS bf16x8*)(lds + PG8_SB(b, h) + boff + n * 2048 + k * 1024); } while (0)
; #define PG8_MMA(ai, bj, At, Bt) do { __builtin_amdgcn_s_setprio(1); _Pragma("unroll") for (int m = 0; m < 4; ++m) _Pragma("unroll") for (int n = 0; n < 2; ++n) _Pragma("unroll") for (int k = 0; k < 2; ++k) \
;         acc[ai][bj][m][n] = __builtin_amdgcn_mfma_f32_16x16x32_bf16(Bt[n][k], At[m][k], acc[ai][bj][m][n], 0, 0, 0); __builtin_amdgcn_s_setprio(0); } while (0)
; #define PG8_WAIT_V(n) asm volatile("s_waitcnt vmcnt(" #n ")" ::: "memory")
; #define PG8_WAIT_L(n) asm volatile("s_waitcnt lgkmcnt(" #n ")" ::: "memory")
; #define PG8_BAR __builtin_amdgcn_s_barrier()
; #define PG8_SCHED __builtin_amdgcn_sched_barrier(0)
; template <class Epi, class Sched>
; __device__ __forceinline__ void gemm_phase(LAS unsigned char* lds, const Gemm g, const Sched& S, const Epi& E, int wave_id) {
;     ...
;             PG8_WAIT_V(8); PG8_WAIT_L(0); PG8_BAR; PG8_MMA(1, 0, At, B0); PG8_MMA(1, 1, At, B1); PG8_BAR; PG8_SCHED;
;             PG8_LDB(B0, 1, 0); PG8_LDB(B1, 1, 1); PG8_SCHED; PG8_LDA(At, 1, 0); PG8_STAGE(PG8_SA(0, 1), a2 + hstepA, voffA);
;             PG8_WAIT_V(8); PG8_WAIT_L(0); PG8_BAR; PG8_MMA(0, 0, At, B0); PG8_MMA(0, 1, At, B1); PG8_BAR; PG8_SCHED;
	s_setprio 1
	s_waitcnt lgkmcnt(0)
	v_mfma_f32_16x16x32_bf16 v[60:63], v[156:159], v[188:191], v[60:63]
	v_mfma_f32_16x16x32_bf16 v[56:59], v[164:167], v[188:191], v[56:59]
	v_mfma_f32_16x16x32_bf16 v[44:47], v[156:159], v[196:199], v[44:47]
	v_mfma_f32_16x16x32_bf16 v[40:43], v[164:167], v[196:199], v[40:43]
	v_mfma_f32_16x16x32_bf16 v[28:31], v[156:159], v[204:207], v[28:31]
	v_mfma_f32_16x16x32_bf16 v[24:27], v[164:167], v[204:207], v[24:27]
	v_mfma_f32_16x16x32_bf16 v[12:15], v[156:159], v[212:215], v[12:15]
	v_mfma_f32_16x16x32_bf16 v[8:11], v[164:167], v[212:215], v[8:11]
	v_mfma_f32_16x16x32_bf16 v[60:63], v[160:163], v[192:195], v[60:63]
	v_mfma_f32_16x16x32_bf16 v[56:59], v[168:171], v[192:195], v[56:59]
	v_mfma_f32_16x16x32_bf16 v[44:47], v[160:163], v[200:203], v[44:47]
	v_mfma_f32_16x16x32_bf16 v[40:43], v[168:171], v[200:203], v[40:43]
	v_mfma_f32_16x16x32_bf16 v[28:31], v[160:163], v[208:211], v[28:31]
	v_mfma_f32_16x16x32_bf16 v[24:27], v[168:171], v[208:211], v[24:27]
	v_mfma_f32_16x16x32_bf16 v[12:15], v[160:163], v[216:219], v[12:15]
	v_mfma_f32_16x16x32_bf16 v[8:11], v[168:171], v[216:219], v[8:11]
	s_setprio 0
	s_setprio 1
	v_mfma_f32_16x16x32_bf16 v[52:55], v[172:175], v[188:191], v[52:55]
	v_mfma_f32_16x16x32_bf16 v[48:51], v[180:183], v[188:191], v[48:51]
	v_mfma_f32_16x16x32_bf16 v[36:39], v[172:175], v[196:199], v[36:39]
	v_mfma_f32_16x16x32_bf16 v[32:35], v[180:183], v[196:199], v[32:35]
	v_mfma_f32_16x16x32_bf16 v[20:23], v[172:175], v[204:207], v[20:23]
	v_mfma_f32_16x16x32_bf16 v[16:19], v[180:183], v[204:207], v[16:19]
	v_mfma_f32_16x16x32_bf16 v[4:7], v[172:175], v[212:215], v[4:7]
	v_mfma_f32_16x16x32_bf16 v[0:3], v[180:183], v[212:215], v[0:3]
	v_mfma_f32_16x16x32_bf16 v[52:55], v[176:179], v[192:195], v[52:55]
	v_mfma_f32_16x16x32_bf16 v[48:51], v[184:187], v[192:195], v[48:51]
	v_mfma_f32_16x16x32_bf16 v[36:39], v[176:179], v[200:203], v[36:39]
	v_mfma_f32_16x16x32_bf16 v[32:35], v[184:187], v[200:203], v[32:35]
	v_mfma_f32_16x16x32_bf16 v[20:23], v[176:179], v[208:211], v[20:23]
	v_mfma_f32_16x16x32_bf16 v[16:19], v[184:187], v[208:211], v[16:19]
	v_mfma_f32_16x16x32_bf16 v[4:7], v[176:179], v[216:219], v[4:7]
	v_mfma_f32_16x16x32_bf16 v[0:3], v[184:187], v[216:219], v[0:3]
	s_setprio 0
	s_barrier
	s_add_i32 s54, 0, 0x18000
	s_add_i32 s55, 0, 0x1c000
	v_add_u32_e32 v168, s54, v150
	v_add_u32_e32 v184, s55, v150
	ds_read_b128 v[156:159], v168
	ds_read_b128 v[160:163], v168 offset:1024
	ds_read_b128 v[164:167], v168 offset:2048
	ds_read_b128 v[168:171], v168 offset:3072
	ds_read_b128 v[172:175], v184
	ds_read_b128 v[176:179], v184 offset:1024
	ds_read_b128 v[180:183], v184 offset:2048
	ds_read_b128 v[184:187], v184 offset:3072
	s_add_u32 s28, s28, 0x40000
	s_addc_u32 s29, s29, 0
	s_mov_b32 m0, s39
	v_lshl_add_u64 v[228:229], s[28:29], 0, v[128:129]
	ds_read_b128 v[188:191], v153 offset:32768
	ds_read_b128 v[192:195], v153 offset:33792
	ds_read_b128 v[196:199], v153 offset:34816
	ds_read_b128 v[200:203], v153 offset:35840
	ds_read_b128 v[204:207], v153 offset:36864
	ds_read_b128 v[208:211], v153 offset:37888
	ds_read_b128 v[212:215], v153 offset:38912
	ds_read_b128 v[216:219], v153 offset:39936
	global_load_lds_dwordx4 v[228:229], off
	v_lshl_add_u64 v[228:229], s[28:29], 0, v[132:133]
	s_mov_b32 m0, s40
	s_nop 0
	global_load_lds_dwordx4 v[228:229], off
	s_waitcnt vmcnt(8)
	s_waitcnt lgkmcnt(0)
	s_barrier
	s_setprio 1
	s_waitcnt lgkmcnt(0)
	v_mfma_f32_16x16x32_bf16 v[124:127], v[156:159], v[188:191], v[124:127]
	v_mfma_f32_16x16x32_bf16 v[120:123], v[164:167], v[188:191], v[120:123]
	v_mfma_f32_16x16x32_bf16 v[108:111], v[156:159], v[196:199], v[108:111]
	v_mfma_f32_16x16x32_bf16 v[104:107], v[164:167], v[196:199], v[104:107]
	v_mfma_f32_16x16x32_bf16 v[92:95], v[156:159], v[204:207], v[92:95]
	v_mfma_f32_16x16x32_bf16 v[88:91], v[164:167], v[204:207], v[88:91]
	v_mfma_f32_16x16x32_bf16 v[76:79], v[156:159], v[212:215], v[76:79]
	v_mfma_f32_16x16x32_bf16 v[72:75], v[164:167], v[212:215], v[72:75]
	v_mfma_f32_16x16x32_bf16 v[124:127], v[160:163], v[192:195], v[124:127]
	v_mfma_f32_16x16x32_bf16 v[120:123], v[168:171], v[192:195], v[120:123]
	v_mfma_f32_16x16x32_bf16 v[108:111], v[160:163], v[200:203], v[108:111]
	v_mfma_f32_16x16x32_bf16 v[104:107], v[168:171], v[200:203], v[104:107]
	v_mfma_f32_16x16x32_bf16 v[92:95], v[160:163], v[208:211], v[92:95]
	v_mfma_f32_16x16x32_bf16 v[88:91], v[168:171], v[208:211], v[88:91]
	v_mfma_f32_16x16x32_bf16 v[76:79], v[160:163], v[216:219], v[76:79]
	v_mfma_f32_16x16x32_bf16 v[72:75], v[168:171], v[216:219], v[72:75]
	s_setprio 0
	s_setprio 1
	v_mfma_f32_16x16x32_bf16 v[116:119], v[172:175], v[188:191], v[116:119]
	v_mfma_f32_16x16x32_bf16 v[112:115], v[180:183], v[188:191], v[112:115]
	v_mfma_f32_16x16x32_bf16 v[100:103], v[172:175], v[196:199], v[100:103]
	v_mfma_f32_16x16x32_bf16 v[96:99], v[180:183], v[196:199], v[96:99]
	v_mfma_f32_16x16x32_bf16 v[84:87], v[172:175], v[204:207], v[84:87]
	v_mfma_f32_16x16x32_bf16 v[80:83], v[180:183], v[204:207], v[80:83]
	v_mfma_f32_16x16x32_bf16 v[68:71], v[172:175], v[212:215], v[68:71]
	v_mfma_f32_16x16x32_bf16 v[64:67], v[180:183], v[212:215], v[64:67]
	v_mfma_f32_16x16x32_bf16 v[116:119], v[176:179], v[192:195], v[116:119]
	v_mfma_f32_16x16x32_bf16 v[112:115], v[184:187], v[192:195], v[112:115]
	v_mfma_f32_16x16x32_bf16 v[100:103], v[176:179], v[200:203], v[100:103]
	v_mfma_f32_16x16x32_bf16 v[96:99], v[184:187], v[200:203], v[96:99]
	v_mfma_f32_16x16x32_bf16 v[84:87], v[176:179], v[208:211], v[84:87]
	v_mfma_f32_16x16x32_bf16 v[80:83], v[184:187], v[208:211], v[80:83]
	v_mfma_f32_16x16x32_bf16 v[68:71], v[176:179], v[216:219], v[68:71]
	v_mfma_f32_16x16x32_bf16 v[64:67], v[184:187], v[216:219], v[64:67]
	s_setprio 0
	s_barrier
; #define PG8_STAGE(bufoff, gbase, voff) do { _Pragma("unroll") for (int _i = 0; _i < 2; ++_i) \
;         __builtin_amdgcn_global_load_lds((const unsigned*)((const char*)(gbase) + (voff)[_i]), (LAS unsigned*)(lds + (bufoff) + ldsw + _i * 8192), 16, 0, 0); } while (0)
; #define PG8_LDA(dst, b, h) do { _Pragma("unroll") for (int m = 0; m < 4; ++m) _Pragma("unroll") for (int k = 0; k < 2; ++k) dst[m][k] = *(const LAS bf16x8*)(lds + PG8_SA(b, h) + aoff + m * 2048 + k * 1024); } while (0)
; #define PG8_MMA(ai, bj, At, Bt) do { __builtin_amdgcn_s_setprio(1); _Pragma("unroll") for (int m = 0; m < 4; ++m) _Pragma("unroll") for (int n = 0; n < 2; ++n) _Pragma("unroll") for (int k = 0; k < 2; ++k) \
;         acc[ai][bj][m][n] = __builtin_amdgcn_mfma_f32_16x16x32_bf16(Bt[n][k], At[m][k], acc[ai][bj][m][n], 0, 0, 0); __builtin_amdgcn_s_setprio(0); } while (0)
; #define PG8_WAIT_V(n) asm volatile("s_waitcnt vmcnt(" #n ")" ::: "memory")
; #define PG8_WAIT_L(n) asm volatile("s_waitcnt lgkmcnt(" #n ")" ::: "memory")
; #define PG8_BAR __builtin_amdgcn_s_barrier()
; #define PG8_SCHED __builtin_amdgcn_sched_barrier(0)
; template <class Epi, class Sched>
; __device__ __forceinline__ void gemm_phase(LAS unsigned char* lds, const Gemm g, const Sched& S, const Epi& E, int wave_id) {
;     ...
;             PG8_LDA(At, 1, 1); PG8_STAGE(PG8_SB(1, 0), b3, voffB); PG8_STAGE(PG8_SB(1, 1), b3 + hstepB, voffB); PG8_STAGE(PG8_SA(1, 0), a3, voffA);
;             PG8_WAIT_V(8); PG8_WAIT_L(0); PG8_BAR; PG8_MMA(1, 0, At, B0); PG8_MMA(1, 1, At, B1); PG8_BAR; PG8_SCHED;
;         }
	s_add_i32 s28, s54, s2
	v_lshl_add_u64 v[220:221], v[220:221], 0, s[10:11]
	s_mov_b32 m0, s28
	ds_read_b128 v[188:191], v153 offset:49152
	ds_read_b128 v[192:195], v153 offset:50176
	ds_read_b128 v[196:199], v153 offset:51200
	ds_read_b128 v[200:203], v153 offset:52224
	ds_read_b128 v[204:207], v153 offset:53248
	ds_read_b128 v[208:211], v153 offset:54272
	ds_read_b128 v[212:215], v153 offset:55296
	ds_read_b128 v[216:219], v153 offset:56320
	global_load_lds_dwordx4 v[220:221], off
	s_add_i32 m0, s28, 0x2000
	s_add_u32 s26, s26, 0x40080
	v_lshl_add_u64 v[220:221], v[222:223], 0, s[10:11]
	s_addc_u32 s27, s27, 0
	s_add_i32 s28, s55, s2
	global_load_lds_dwordx4 v[220:221], off
	v_lshl_add_u64 v[220:221], s[26:27], 0, v[130:131]
	s_mov_b32 m0, s28
	s_nop 0
	global_load_lds_dwordx4 v[220:221], off
	v_lshl_add_u64 v[220:221], s[26:27], 0, v[134:135]
	s_add_i32 m0, s28, 0x2000
	s_nop 0
	global_load_lds_dwordx4 v[220:221], off
	v_lshl_add_u64 v[220:221], v[224:225], 0, s[10:11]
	s_mov_b32 m0, s45
	s_nop 0
	global_load_lds_dwordx4 v[220:221], off
	v_lshl_add_u64 v[220:221], v[226:227], 0, s[10:11]
	s_mov_b32 m0, s46
	s_nop 0
	global_load_lds_dwordx4 v[220:221], off
	s_waitcnt vmcnt(8)
	s_waitcnt lgkmcnt(0)
	s_barrier
	s_setprio 1
	s_waitcnt lgkmcnt(0)
	v_mfma_f32_16x16x32_bf16 v[60:63], v[156:159], v[188:191], v[60:63]
	v_mfma_f32_16x16x32_bf16 v[56:59], v[164:167], v[188:191], v[56:59]
	v_mfma_f32_16x16x32_bf16 v[44:47], v[156:159], v[196:199], v[44:47]
	v_mfma_f32_16x16x32_bf16 v[40:43], v[164:167], v[196:199], v[40:43]
	v_mfma_f32_16x16x32_bf16 v[28:31], v[156:159], v[204:207], v[28:31]
	v_mfma_f32_16x16x32_bf16 v[24:27], v[164:167], v[204:207], v[24:27]
	v_mfma_f32_16x16x32_bf16 v[12:15], v[156:159], v[212:215], v[12:15]
	v_mfma_f32_16x16x32_bf16 v[8:11], v[164:167], v[212:215], v[8:11]
	v_mfma_f32_16x16x32_bf16 v[60:63], v[160:163], v[192:195], v[60:63]
	v_mfma_f32_16x16x32_bf16 v[56:59], v[168:171], v[192:195], v[56:59]
	v_mfma_f32_16x16x32_bf16 v[44:47], v[160:163], v[200:203], v[44:47]
	v_mfma_f32_16x16x32_bf16 v[40:43], v[168:171], v[200:203], v[40:43]
	v_mfma_f32_16x16x32_bf16 v[28:31], v[160:163], v[208:211], v[28:31]
	v_mfma_f32_16x16x32_bf16 v[24:27], v[168:171], v[208:211], v[24:27]
	v_mfma_f32_16x16x32_bf16 v[12:15], v[160:163], v[216:219], v[12:15]
	v_mfma_f32_16x16x32_bf16 v[8:11], v[168:171], v[216:219], v[8:11]
	s_setprio 0
	s_setprio 1
	v_mfma_f32_16x16x32_bf16 v[52:55], v[172:175], v[188:191], v[52:55]
	v_mfma_f32_16x16x32_bf16 v[48:51], v[180:183], v[188:191], v[48:51]
	v_mfma_f32_16x16x32_bf16 v[36:39], v[172:175], v[196:199], v[36:39]
	v_mfma_f32_16x16x32_bf16 v[32:35], v[180:183], v[196:199], v[32:35]
	v_mfma_f32_16x16x32_bf16 v[20:23], v[172:175], v[204:207], v[20:23]
	v_mfma_f32_16x16x32_bf16 v[16:19], v[180:183], v[204:207], v[16:19]
	v_mfma_f32_16x16x32_bf16 v[4:7], v[172:175], v[212:215], v[4:7]
	v_mfma_f32_16x16x32_bf16 v[0:3], v[180:183], v[212:215], v[0:3]
	v_mfma_f32_16x16x32_bf16 v[52:55], v[176:179], v[192:195], v[52:55]
	v_mfma_f32_16x16x32_bf16 v[48:51], v[184:187], v[192:195], v[48:51]
	v_mfma_f32_16x16x32_bf16 v[36:39], v[176:179], v[200:203], v[36:39]
	v_mfma_f32_16x16x32_bf16 v[32:35], v[184:187], v[200:203], v[32:35]
	v_mfma_f32_16x16x32_bf16 v[20:23], v[176:179], v[208:211], v[20:23]
	v_mfma_f32_16x16x32_bf16 v[16:19], v[184:187], v[208:211], v[16:19]
	v_mfma_f32_16x16x32_bf16 v[4:7], v[176:179], v[216:219], v[4:7]
	v_mfma_f32_16x16x32_bf16 v[0:3], v[184:187], v[216:219], v[0:3]
	s_setprio 0
	s_add_i32 s53, s53, 2
	s_add_u32 s24, s24, 0x100
	s_addc_u32 s25, s25, 0
	s_add_u32 s51, s51, 0x100
	s_addc_u32 s52, s52, 0
	s_cmp_gt_u32 s53, 13
	s_barrier
	s_cbranch_scc0 .LBB0_960
	s_and_b64 vcc, exec, s[12:13]
	s_cbranch_vccz .LBB0_963
	s_barrier

; #define PG8_STAGE(bufoff, gbase, voff) do { _Pragma("unroll") for (int _i = 0; _i < 2; ++_i) \
;         __builtin_amdgcn_global_load_lds((const unsigned*)((const char*)(gbase) + (voff)[_i]), (LAS unsigned*)(lds + (bufoff) + ldsw + _i * 8192), 16, 0, 0); } while (0)
; #define PG8_LDA(dst, b, h) do { _Pragma("unroll") for (int m = 0; m < 4; ++m) _Pragma("unroll") for (int k = 0; k < 2; ++k) dst[m][k] = *(const LAS bf16x8*)(lds + PG8_SA(b, h) + aoff + m * 2048 + k * 1024); } while (0)
; #define PG8_LDB(dst, b, h) do { _Pragma("unroll") for (int n = 0; n < 2; ++n) _Pragma("unroll") for (int k = 0; k < 2; ++k) dst[n][k] = *(const LAS bf16x8*)(lds + PG8_SB(b, h) + boff + n * 2048 + k * 1024); } while (0)
; #define PG8_MMA(ai, bj, At, Bt) do { __builtin_amdgcn_s_setprio(1); _Pragma("unroll") for (int m = 0; m < 4; ++m) _Pragma("unroll") for (int n = 0; n < 2; ++n) _Pragma("unroll") for (int k = 0; k < 2; ++k) \
;         acc[ai][bj][m][n] = __builtin_amdgcn_mfma_f32_16x16x32_bf16(Bt[n][k], At[m][k], acc[ai][bj][m][n], 0, 0, 0); __builtin_amdgcn_s_setprio(0); } while (0)
; #define PG8_WAIT_V(n) asm volatile("s_waitcnt vmcnt(" #n ")" ::: "memory")
; #define PG8_WAIT_L(n) asm volatile("s_waitcnt lgkmcnt(" #n ")" ::: "memory")
; #define PG8_BAR __builtin_amdgcn_s_barrier()
; #define PG8_SCHED __builtin_amdgcn_sched_barrier(0)
; template <class Epi, class Sched>
; __device__ __forceinline__ void gemm_phase(LAS unsigned char* lds, const Gemm g, const Sched& S, const Epi& E, int wave_id) {
;     ...
;         for (int t = 0; t < nt; t += 2) {
;             const bool last = (t == nt - 2);
;             const char* a1 = cA + (size_t)(t + 1) * kstep;
;             const char* a2 = last ? nA : cA + (size_t)(t + 2) * kstep; const char* b2 = last ? nB : cB + (size_t)(t + 2) * kstep;
;             const char* a3 = a2 + kstep; const char* b3 = b2 + kstep;
;             PG8_LDB(B0, 0, 0); PG8_LDB(B1, 0, 1); PG8_SCHED; PG8_LDA(At, 0, 0); PG8_STAGE(PG8_SA(1, 1), a1 + hstepA, voffA);
;             PG8_WAIT_V(8); PG8_WAIT_L(0); PG8_BAR; PG8_MMA(0, 0, At, B0); PG8_MMA(0, 1, At, B1); PG8_BAR; PG8_SCHED;
;             PG8_LDA(At, 0, 1); PG8_STAGE(PG8_SB(0, 0), b2, voffB); PG8_STAGE(PG8_SB(0, 1), b2 + hstepB, voffB); PG8_STAGE(PG8_SA(0, 0), a2, voffA);
;             PG8_WAIT_V(8); PG8_WAIT_L(0); PG8_BAR; PG8_MMA(1, 0, At, B0); PG8_MMA(1, 1, At, B1); PG8_BAR; PG8_SCHED;
.LBB0_1041:
	ds_read_b128 v[116:119], v201
	ds_read_b128 v[120:123], v201 offset:1024
	ds_read_b128 v[124:127], v201 offset:2048
	ds_read_b128 v[136:139], v201 offset:3072
	ds_read_b128 v[140:143], v202
	ds_read_b128 v[148:151], v202 offset:1024
	ds_read_b128 v[152:155], v202 offset:2048
	ds_read_b128 v[156:159], v202 offset:3072
	s_add_u32 s28, s26, 0xfffe0080
	s_addc_u32 s29, s27, -1
	s_cmp_eq_u32 s52, 4
	s_cselect_b32 s31, s19, s29
	s_cselect_b32 s30, s48, s28
	s_cselect_b32 s29, s17, s51
	s_cselect_b32 s28, s49, s50
	v_lshl_add_u64 v[216:217], s[26:27], 0, v[178:179]
	s_add_i32 m0, s25, 0xc000
	ds_read_b128 v[160:163], v203
	ds_read_b128 v[164:167], v203 offset:1024
	ds_read_b128 v[186:189], v203 offset:2048
	ds_read_b128 v[190:193], v203 offset:3072
	ds_read_b128 v[194:197], v203 offset:4096
	ds_read_b128 v[204:207], v203 offset:5120
	ds_read_b128 v[208:211], v203 offset:6144
	ds_read_b128 v[212:215], v203 offset:7168
	global_load_lds_dwordx4 v[216:217], off
	v_lshl_add_u64 v[216:217], s[26:27], 0, v[180:181]
	s_add_i32 m0, s25, 0xe000
	s_nop 0
	global_load_lds_dwordx4 v[216:217], off
	s_waitcnt vmcnt(8)
	s_waitcnt lgkmcnt(0)
	s_barrier
	s_setprio 1
	s_waitcnt lgkmcnt(0)
	v_mfma_f32_16x16x32_bf16 v[144:147], v[116:119], v[160:163], v[144:147]
	v_mfma_f32_16x16x32_bf16 v[128:131], v[124:127], v[160:163], v[128:131]
	v_mfma_f32_16x16x32_bf16 v[108:111], v[116:119], v[186:189], v[108:111]
	v_mfma_f32_16x16x32_bf16 v[100:103], v[124:127], v[186:189], v[100:103]
	v_mfma_f32_16x16x32_bf16 v[92:95], v[116:119], v[194:197], v[92:95]
	v_mfma_f32_16x16x32_bf16 v[84:87], v[124:127], v[194:197], v[84:87]
	v_mfma_f32_16x16x32_bf16 v[76:79], v[116:119], v[208:211], v[76:79]
	v_mfma_f32_16x16x32_bf16 v[68:71], v[124:127], v[208:211], v[68:71]
	v_mfma_f32_16x16x32_bf16 v[144:147], v[120:123], v[164:167], v[144:147]
	v_mfma_f32_16x16x32_bf16 v[128:131], v[136:139], v[164:167], v[128:131]
	v_mfma_f32_16x16x32_bf16 v[108:111], v[120:123], v[190:193], v[108:111]
	v_mfma_f32_16x16x32_bf16 v[100:103], v[136:139], v[190:193], v[100:103]
	v_mfma_f32_16x16x32_bf16 v[92:95], v[120:123], v[204:207], v[92:95]
	v_mfma_f32_16x16x32_bf16 v[84:87], v[136:139], v[204:207], v[84:87]
	v_mfma_f32_16x16x32_bf16 v[76:79], v[120:123], v[212:215], v[76:79]
	v_mfma_f32_16x16x32_bf16 v[68:71], v[136:139], v[212:215], v[68:71]
	s_setprio 0
	s_setprio 1
	v_mfma_f32_16x16x32_bf16 v[132:135], v[140:143], v[160:163], v[132:135]
	v_mfma_f32_16x16x32_bf16 v[112:115], v[152:155], v[160:163], v[112:115]
	v_mfma_f32_16x16x32_bf16 v[104:107], v[140:143], v[186:189], v[104:107]
	v_mfma_f32_16x16x32_bf16 v[96:99], v[152:155], v[186:189], v[96:99]
	v_mfma_f32_16x16x32_bf16 v[88:91], v[140:143], v[194:197], v[88:91]
	v_mfma_f32_16x16x32_bf16 v[80:83], v[152:155], v[194:197], v[80:83]
	v_mfma_f32_16x16x32_bf16 v[72:75], v[140:143], v[208:211], v[72:75]
	v_mfma_f32_16x16x32_bf16 v[64:67], v[152:155], v[208:211], v[64:67]
	v_mfma_f32_16x16x32_bf16 v[132:135], v[148:151], v[164:167], v[132:135]
	v_mfma_f32_16x16x32_bf16 v[112:115], v[156:159], v[164:167], v[112:115]
	v_mfma_f32_16x16x32_bf16 v[104:107], v[148:151], v[190:193], v[104:107]
	v_mfma_f32_16x16x32_bf16 v[96:99], v[156:159], v[190:193], v[96:99]
	v_mfma_f32_16x16x32_bf16 v[88:91], v[148:151], v[204:207], v[88:91]
	v_mfma_f32_16x16x32_bf16 v[80:83], v[156:159], v[204:207], v[80:83]
	v_mfma_f32_16x16x32_bf16 v[72:75], v[148:151], v[212:215], v[72:75]
	v_mfma_f32_16x16x32_bf16 v[64:67], v[156:159], v[212:215], v[64:67]
	s_setprio 0
	s_barrier
	s_add_i32 s53, s45, s36
	v_lshl_add_u64 v[216:217], s[28:29], 0, v[170:171]
	s_mov_b32 m0, s53
	ds_read_b128 v[160:163], v203 offset:16384
	ds_read_b128 v[164:167], v203 offset:17408
	ds_read_b128 v[186:189], v203 offset:18432
	ds_read_b128 v[190:193], v203 offset:19456
	ds_read_b128 v[194:197], v203 offset:20480
	ds_read_b128 v[204:207], v203 offset:21504
	ds_read_b128 v[208:211], v203 offset:22528
	ds_read_b128 v[212:215], v203 offset:23552
	global_load_lds_dwordx4 v[216:217], off
	s_add_i32 m0, s53, 0x2000
	s_add_u32 s54, s28, 0x20000
	v_lshl_add_u64 v[218:219], s[28:29], 0, v[174:175]
	s_addc_u32 s55, s29, 0
	s_add_i32 s53, s46, s36
	global_load_lds_dwordx4 v[218:219], off
	v_lshl_add_u64 v[220:221], s[54:55], 0, v[170:171]
	s_mov_b32 m0, s53
	v_lshl_add_u64 v[222:223], s[30:31], 0, v[172:173]
	global_load_lds_dwordx4 v[220:221], off
	v_lshl_add_u64 v[220:221], s[54:55], 0, v[174:175]
	s_add_i32 m0, s53, 0x2000
	s_nop 0
	global_load_lds_dwordx4 v[220:221], off
	v_lshl_add_u64 v[220:221], s[30:31], 0, v[168:169]
	s_mov_b32 m0, s25
	s_nop 0
	global_load_lds_dwordx4 v[220:221], off
	s_mov_b32 m0, s37
	s_nop 0
	global_load_lds_dwordx4 v[222:223], off
	s_waitcnt vmcnt(8)
	s_waitcnt lgkmcnt(0)
	s_barrier
; #define PG8_STAGE(bufoff, gbase, voff) do { _Pragma("unroll") for (int _i = 0; _i < 2; ++_i) \
;         __builtin_amdgcn_global_load_lds((const unsigned*)((const char*)(gbase) + (voff)[_i]), (LAS unsigned*)(lds + (bufoff) + ldsw + _i * 8192), 16, 0, 0); } while (0)
; #define PG8_LDA(dst, b, h) do { _Pragma("unroll") for (int m = 0; m < 4; ++m) _Pragma("unroll") for (int k = 0; k < 2; ++k) dst[m][k] = *(const LAS bf16x8*)(lds + PG8_SA(b, h) + aoff + m * 2048 + k * 1024); } while (0)
; #define PG8_LDB(dst, b, h) do { _Pragma("unroll") for (int n = 0; n < 2; ++n) _Pragma("unroll") for (int k = 0; k < 2; ++k) dst[n][k] = *(const LAS bf16x8*)(lds + PG8_SB(b, h) + boff + n * 2048 + k * 1024); } while (0)
; #define PG8_MMA(ai, bj, At, Bt) do { __builtin_amdgcn_s_setprio(1); _Pragma("unroll") for (int m = 0; m < 4; ++m) _Pragma("unroll") for (int n = 0; n < 2; ++n) _Pragma("unroll") for (int k = 0; k < 2; ++k) \
;         acc[ai][bj][m][n] = __builtin_amdgcn_mfma_f32_16x16x32_bf16(Bt[n][k], At[m][k], acc[ai][bj][m][n], 0, 0, 0); __builtin_amdgcn_s_setprio(0); } while (0)
; #define PG8_WAIT_V(n) asm volatile("s_waitcnt vmcnt(" #n ")" ::: "memory")
; #define PG8_WAIT_L(n) asm volatile("s_waitcnt lgkmcnt(" #n ")" ::: "memory")
; #define PG8_BAR __builtin_amdgcn_s_barrier()
; #define PG8_SCHED __builtin_amdgcn_sched_barrier(0)
; template <class Epi, class Sched>
; __device__ __forceinline__ void gemm_phase(LAS unsigned char* lds, const Gemm g, const Sched& S, const Epi& E, int wave_id) {
;     ...
;             PG8_WAIT_V(8); PG8_WAIT_L(0); PG8_BAR; PG8_MMA(1, 0, At, B0); PG8_MMA(1, 1, At, B1); PG8_BAR; PG8_SCHED;
;             PG8_LDB(B0, 1, 0); PG8_LDB(B1, 1, 1); PG8_SCHED; PG8_LDA(At, 1, 0); PG8_STAGE(PG8_SA(0, 1), a2 + hstepA, voffA);
;             PG8_WAIT_V(8); PG8_WAIT_L(0); PG8_BAR; PG8_MMA(0, 0, At, B0); PG8_MMA(0, 1, At, B1); PG8_BAR; PG8_SCHED;
	s_setprio 1
	s_waitcnt lgkmcnt(0)
	v_mfma_f32_16x16x32_bf16 v[60:63], v[116:119], v[160:163], v[60:63]
	v_mfma_f32_16x16x32_bf16 v[52:55], v[124:127], v[160:163], v[52:55]
	v_mfma_f32_16x16x32_bf16 v[44:47], v[116:119], v[186:189], v[44:47]
	v_mfma_f32_16x16x32_bf16 v[36:39], v[124:127], v[186:189], v[36:39]
	v_mfma_f32_16x16x32_bf16 v[28:31], v[116:119], v[194:197], v[28:31]
	v_mfma_f32_16x16x32_bf16 v[20:23], v[124:127], v[194:197], v[20:23]
	v_mfma_f32_16x16x32_bf16 v[12:15], v[116:119], v[208:211], v[12:15]
	v_mfma_f32_16x16x32_bf16 v[4:7], v[124:127], v[208:211], v[4:7]
	v_mfma_f32_16x16x32_bf16 v[60:63], v[120:123], v[164:167], v[60:63]
	v_mfma_f32_16x16x32_bf16 v[52:55], v[136:139], v[164:167], v[52:55]
	v_mfma_f32_16x16x32_bf16 v[44:47], v[120:123], v[190:193], v[44:47]
	v_mfma_f32_16x16x32_bf16 v[36:39], v[136:139], v[190:193], v[36:39]
	v_mfma_f32_16x16x32_bf16 v[28:31], v[120:123], v[204:207], v[28:31]
	v_mfma_f32_16x16x32_bf16 v[20:23], v[136:139], v[204:207], v[20:23]
	v_mfma_f32_16x16x32_bf16 v[12:15], v[120:123], v[212:215], v[12:15]
	v_mfma_f32_16x16x32_bf16 v[4:7], v[136:139], v[212:215], v[4:7]
	s_setprio 0
	s_setprio 1
	v_mfma_f32_16x16x32_bf16 v[56:59], v[140:143], v[160:163], v[56:59]
	v_mfma_f32_16x16x32_bf16 v[48:51], v[152:155], v[160:163], v[48:51]
	v_mfma_f32_16x16x32_bf16 v[40:43], v[140:143], v[186:189], v[40:43]
	v_mfma_f32_16x16x32_bf16 v[32:35], v[152:155], v[186:189], v[32:35]
	v_mfma_f32_16x16x32_bf16 v[24:27], v[140:143], v[194:197], v[24:27]
	v_mfma_f32_16x16x32_bf16 v[16:19], v[152:155], v[194:197], v[16:19]
	v_mfma_f32_16x16x32_bf16 v[8:11], v[140:143], v[208:211], v[8:11]
	v_mfma_f32_16x16x32_bf16 v[0:3], v[152:155], v[208:211], v[0:3]
	v_mfma_f32_16x16x32_bf16 v[56:59], v[148:151], v[164:167], v[56:59]
	v_mfma_f32_16x16x32_bf16 v[48:51], v[156:159], v[164:167], v[48:51]
	v_mfma_f32_16x16x32_bf16 v[40:43], v[148:151], v[190:193], v[40:43]
	v_mfma_f32_16x16x32_bf16 v[32:35], v[156:159], v[190:193], v[32:35]
	v_mfma_f32_16x16x32_bf16 v[24:27], v[148:151], v[204:207], v[24:27]
	v_mfma_f32_16x16x32_bf16 v[16:19], v[156:159], v[204:207], v[16:19]
	v_mfma_f32_16x16x32_bf16 v[8:11], v[148:151], v[212:215], v[8:11]
	v_mfma_f32_16x16x32_bf16 v[0:3], v[156:159], v[212:215], v[0:3]
	s_setprio 0
	s_barrier
	s_add_i32 s53, 0, 0x18000
	s_add_i32 s54, 0, 0x1c000
	v_add_u32_e32 v136, s53, v199
	v_add_u32_e32 v156, s54, v199
	ds_read_b128 v[116:119], v136
	ds_read_b128 v[120:123], v136 offset:1024
	ds_read_b128 v[124:127], v136 offset:2048
	ds_read_b128 v[136:139], v136 offset:3072
	ds_read_b128 v[140:143], v156
	ds_read_b128 v[148:151], v156 offset:1024
	ds_read_b128 v[152:155], v156 offset:2048
	ds_read_b128 v[156:159], v156 offset:3072
	s_add_u32 s30, s30, 0x20000
	s_addc_u32 s31, s31, 0
	s_mov_b32 m0, s38
	v_lshl_add_u64 v[224:225], s[30:31], 0, v[168:169]
	ds_read_b128 v[160:163], v203 offset:32768
	ds_read_b128 v[164:167], v203 offset:33792
	ds_read_b128 v[186:189], v203 offset:34816
	ds_read_b128 v[190:193], v203 offset:35840
	ds_read_b128 v[194:197], v203 offset:36864
	ds_read_b128 v[204:207], v203 offset:37888
	ds_read_b128 v[208:211], v203 offset:38912
	ds_read_b128 v[212:215], v203 offset:39936
	global_load_lds_dwordx4 v[224:225], off
	v_lshl_add_u64 v[224:225], s[30:31], 0, v[172:173]
	s_mov_b32 m0, s39
	s_nop 0
	global_load_lds_dwordx4 v[224:225], off
	s_waitcnt vmcnt(8)
	s_waitcnt lgkmcnt(0)
	s_barrier
	s_setprio 1
	s_waitcnt lgkmcnt(0)
	v_mfma_f32_16x16x32_bf16 v[144:147], v[116:119], v[160:163], v[144:147]
	v_mfma_f32_16x16x32_bf16 v[128:131], v[124:127], v[160:163], v[128:131]
	v_mfma_f32_16x16x32_bf16 v[108:111], v[116:119], v[186:189], v[108:111]
	v_mfma_f32_16x16x32_bf16 v[100:103], v[124:127], v[186:189], v[100:103]
	v_mfma_f32_16x16x32_bf16 v[92:95], v[116:119], v[194:197], v[92:95]
	v_mfma_f32_16x16x32_bf16 v[84:87], v[124:127], v[194:197], v[84:87]
	v_mfma_f32_16x16x32_bf16 v[76:79], v[116:119], v[208:211], v[76:79]
	v_mfma_f32_16x16x32_bf16 v[68:71], v[124:127], v[208:211], v[68:71]
	v_mfma_f32_16x16x32_bf16 v[144:147], v[120:123], v[164:167], v[144:147]
	v_mfma_f32_16x16x32_bf16 v[128:131], v[136:139], v[164:167], v[128:131]
	v_mfma_f32_16x16x32_bf16 v[108:111], v[120:123], v[190:193], v[108:111]
	v_mfma_f32_16x16x32_bf16 v[100:103], v[136:139], v[190:193], v[100:103]
	v_mfma_f32_16x16x32_bf16 v[92:95], v[120:123], v[204:207], v[92:95]
	v_mfma_f32_16x16x32_bf16 v[84:87], v[136:139], v[204:207], v[84:87]
	v_mfma_f32_16x16x32_bf16 v[76:79], v[120:123], v[212:215], v[76:79]
	v_mfma_f32_16x16x32_bf16 v[68:71], v[136:139], v[212:215], v[68:71]
	s_setprio 0
	s_setprio 1
	v_mfma_f32_16x16x32_bf16 v[132:135], v[140:143], v[160:163], v[132:135]
	v_mfma_f32_16x16x32_bf16 v[112:115], v[152:155], v[160:163], v[112:115]
	v_mfma_f32_16x16x32_bf16 v[104:107], v[140:143], v[186:189], v[104:107]
	v_mfma_f32_16x16x32_bf16 v[96:99], v[152:155], v[186:189], v[96:99]
	v_mfma_f32_16x16x32_bf16 v[88:91], v[140:143], v[194:197], v[88:91]
	v_mfma_f32_16x16x32_bf16 v[80:83], v[152:155], v[194:197], v[80:83]
	v_mfma_f32_16x16x32_bf16 v[72:75], v[140:143], v[208:211], v[72:75]
	v_mfma_f32_16x16x32_bf16 v[64:67], v[152:155], v[208:211], v[64:67]
	v_mfma_f32_16x16x32_bf16 v[132:135], v[148:151], v[164:167], v[132:135]
	v_mfma_f32_16x16x32_bf16 v[112:115], v[156:159], v[164:167], v[112:115]
	v_mfma_f32_16x16x32_bf16 v[104:107], v[148:151], v[190:193], v[104:107]
	v_mfma_f32_16x16x32_bf16 v[96:99], v[156:159], v[190:193], v[96:99]
	v_mfma_f32_16x16x32_bf16 v[88:91], v[148:151], v[204:207], v[88:91]
	v_mfma_f32_16x16x32_bf16 v[80:83], v[156:159], v[204:207], v[80:83]
	v_mfma_f32_16x16x32_bf16 v[72:75], v[148:151], v[212:215], v[72:75]
	v_mfma_f32_16x16x32_bf16 v[64:67], v[156:159], v[212:215], v[64:67]
	s_setprio 0
	s_barrier
; #define PG8_STAGE(bufoff, gbase, voff) do { _Pragma("unroll") for (int _i = 0; _i < 2; ++_i) \
;         __builtin_amdgcn_global_load_lds((const unsigned*)((const char*)(gbase) + (voff)[_i]), (LAS unsigned*)(lds + (bufoff) + ldsw + _i * 8192), 16, 0, 0); } while (0)
; #define PG8_LDA(dst, b, h) do { _Pragma("unroll") for (int m = 0; m < 4; ++m) _Pragma("unroll") for (int k = 0; k < 2; ++k) dst[m][k] = *(const LAS bf16x8*)(lds + PG8_SA(b, h) + aoff + m * 2048 + k * 1024); } while (0)
; #define PG8_MMA(ai, bj, At, Bt) do { __builtin_amdgcn_s_setprio(1); _Pragma("unroll") for (int m = 0; m < 4; ++m) _Pragma("unroll") for (int n = 0; n < 2; ++n) _Pragma("unroll") for (int k = 0; k < 2; ++k) \
;         acc[ai][bj][m][n] = __builtin_amdgcn_mfma_f32_16x16x32_bf16(Bt[n][k], At[m][k], acc[ai][bj][m][n], 0, 0, 0); __builtin_amdgcn_s_setprio(0); } while (0)
; #define PG8_WAIT_V(n) asm volatile("s_waitcnt vmcnt(" #n ")" ::: "memory")
; #define PG8_WAIT_L(n) asm volatile("s_waitcnt lgkmcnt(" #n ")" ::: "memory")
; #define PG8_BAR __builtin_amdgcn_s_barrier()
; #define PG8_SCHED __builtin_amdgcn_sched_barrier(0)
; template <class Epi, class Sched>
; __device__ __forceinline__ void gemm_phase(LAS unsigned char* lds, const Gemm g, const Sched& S, const Epi& E, int wave_id) {
;     ...
;             PG8_LDA(At, 1, 1); PG8_STAGE(PG8_SB(1, 0), b3, voffB); PG8_STAGE(PG8_SB(1, 1), b3 + hstepB, voffB); PG8_STAGE(PG8_SA(1, 0), a3, voffA);
;             PG8_WAIT_V(8); PG8_WAIT_L(0); PG8_BAR; PG8_MMA(1, 0, At, B0); PG8_MMA(1, 1, At, B1); PG8_BAR; PG8_SCHED;
;         }
	s_add_i32 s30, s53, s36
	v_lshl_add_u64 v[216:217], v[216:217], 0, s[10:11]
	s_mov_b32 m0, s30
	ds_read_b128 v[160:163], v203 offset:49152
	ds_read_b128 v[164:167], v203 offset:50176
	ds_read_b128 v[186:189], v203 offset:51200
	ds_read_b128 v[190:193], v203 offset:52224
	ds_read_b128 v[194:197], v203 offset:53248
	ds_read_b128 v[204:207], v203 offset:54272
	ds_read_b128 v[208:211], v203 offset:55296
	ds_read_b128 v[212:215], v203 offset:56320
	global_load_lds_dwordx4 v[216:217], off
	s_add_i32 m0, s30, 0x2000
	s_add_u32 s28, s28, 0x20080
	v_lshl_add_u64 v[216:217], v[218:219], 0, s[10:11]
	s_addc_u32 s29, s29, 0
	s_add_i32 s30, s54, s36
	global_load_lds_dwordx4 v[216:217], off
	v_lshl_add_u64 v[216:217], s[28:29], 0, v[170:171]
	s_mov_b32 m0, s30
	s_nop 0
	global_load_lds_dwordx4 v[216:217], off
	v_lshl_add_u64 v[216:217], s[28:29], 0, v[174:175]
	s_add_i32 m0, s30, 0x2000
	s_nop 0
	global_load_lds_dwordx4 v[216:217], off
	v_lshl_add_u64 v[216:217], v[220:221], 0, s[10:11]
	s_mov_b32 m0, s41
	s_nop 0
	global_load_lds_dwordx4 v[216:217], off
	v_lshl_add_u64 v[216:217], v[222:223], 0, s[10:11]
	s_mov_b32 m0, s42
	s_nop 0
	global_load_lds_dwordx4 v[216:217], off
	s_waitcnt vmcnt(8)
	s_waitcnt lgkmcnt(0)
	s_barrier
	s_setprio 1
	s_waitcnt lgkmcnt(0)
	v_mfma_f32_16x16x32_bf16 v[60:63], v[116:119], v[160:163], v[60:63]
	v_mfma_f32_16x16x32_bf16 v[52:55], v[124:127], v[160:163], v[52:55]
	v_mfma_f32_16x16x32_bf16 v[44:47], v[116:119], v[186:189], v[44:47]
	v_mfma_f32_16x16x32_bf16 v[36:39], v[124:127], v[186:189], v[36:39]
	v_mfma_f32_16x16x32_bf16 v[28:31], v[116:119], v[194:197], v[28:31]
	v_mfma_f32_16x16x32_bf16 v[20:23], v[124:127], v[194:197], v[20:23]
	v_mfma_f32_16x16x32_bf16 v[12:15], v[116:119], v[208:211], v[12:15]
	v_mfma_f32_16x16x32_bf16 v[4:7], v[124:127], v[208:211], v[4:7]
	v_mfma_f32_16x16x32_bf16 v[60:63], v[120:123], v[164:167], v[60:63]
	v_mfma_f32_16x16x32_bf16 v[52:55], v[136:139], v[164:167], v[52:55]
	v_mfma_f32_16x16x32_bf16 v[44:47], v[120:123], v[190:193], v[44:47]
	v_mfma_f32_16x16x32_bf16 v[36:39], v[136:139], v[190:193], v[36:39]
	v_mfma_f32_16x16x32_bf16 v[28:31], v[120:123], v[204:207], v[28:31]
	v_mfma_f32_16x16x32_bf16 v[20:23], v[136:139], v[204:207], v[20:23]
	v_mfma_f32_16x16x32_bf16 v[12:15], v[120:123], v[212:215], v[12:15]
	v_mfma_f32_16x16x32_bf16 v[4:7], v[136:139], v[212:215], v[4:7]
	s_setprio 0
	s_setprio 1
	v_mfma_f32_16x16x32_bf16 v[56:59], v[140:143], v[160:163], v[56:59]
	v_mfma_f32_16x16x32_bf16 v[48:51], v[152:155], v[160:163], v[48:51]
	v_mfma_f32_16x16x32_bf16 v[40:43], v[140:143], v[186:189], v[40:43]
	v_mfma_f32_16x16x32_bf16 v[32:35], v[152:155], v[186:189], v[32:35]
	v_mfma_f32_16x16x32_bf16 v[24:27], v[140:143], v[194:197], v[24:27]
	v_mfma_f32_16x16x32_bf16 v[16:19], v[152:155], v[194:197], v[16:19]
	v_mfma_f32_16x16x32_bf16 v[8:11], v[140:143], v[208:211], v[8:11]
	v_mfma_f32_16x16x32_bf16 v[0:3], v[152:155], v[208:211], v[0:3]
	v_mfma_f32_16x16x32_bf16 v[56:59], v[148:151], v[164:167], v[56:59]
	v_mfma_f32_16x16x32_bf16 v[48:51], v[156:159], v[164:167], v[48:51]
	v_mfma_f32_16x16x32_bf16 v[40:43], v[148:151], v[190:193], v[40:43]
	v_mfma_f32_16x16x32_bf16 v[32:35], v[156:159], v[190:193], v[32:35]
	v_mfma_f32_16x16x32_bf16 v[24:27], v[148:151], v[204:207], v[24:27]
	v_mfma_f32_16x16x32_bf16 v[16:19], v[156:159], v[204:207], v[16:19]
	v_mfma_f32_16x16x32_bf16 v[8:11], v[148:151], v[212:215], v[8:11]
	v_mfma_f32_16x16x32_bf16 v[0:3], v[156:159], v[212:215], v[0:3]
	s_setprio 0
	s_add_i32 s52, s52, 2
	s_add_u32 s26, s26, 0x100
	s_addc_u32 s27, s27, 0
	s_add_u32 s50, s50, 0x100
	s_addc_u32 s51, s51, 0
	s_cmp_gt_u32 s52, 5
	s_barrier
	s_cbranch_scc0 .LBB0_1041
	s_and_b64 vcc, exec, s[12:13]
	s_cbranch_vccz .LBB0_1044
	s_barrier

; #define PG8_STAGE(bufoff, gbase, voff) do { _Pragma("unroll") for (int _i = 0; _i < 2; ++_i) \
;         __builtin_amdgcn_global_load_lds((const unsigned*)((const char*)(gbase) + (voff)[_i]), (LAS unsigned*)(lds + (bufoff) + ldsw + _i * 8192), 16, 0, 0); } while (0)
; #define PG8_LDA(dst, b, h) do { _Pragma("unroll") for (int m = 0; m < 4; ++m) _Pragma("unroll") for (int k = 0; k < 2; ++k) dst[m][k] = *(const LAS bf16x8*)(lds + PG8_SA(b, h) + aoff + m * 2048 + k * 1024); } while (0)
; #define PG8_LDB(dst, b, h) do { _Pragma("unroll") for (int n = 0; n < 2; ++n) _Pragma("unroll") for (int k = 0; k < 2; ++k) dst[n][k] = *(const LAS bf16x8*)(lds + PG8_SB(b, h) + boff + n * 2048 + k * 1024); } while (0)
; #define PG8_MMA(ai, bj, At, Bt) do { __builtin_amdgcn_s_setprio(1); _Pragma("unroll") for (int m = 0; m < 4; ++m) _Pragma("unroll") for (int n = 0; n < 2; ++n) _Pragma("unroll") for (int k = 0; k < 2; ++k) \
;         acc[ai][bj][m][n] = __builtin_amdgcn_mfma_f32_16x16x32_bf16(Bt[n][k], At[m][k], acc[ai][bj][m][n], 0, 0, 0); __builtin_amdgcn_s_setprio(0); } while (0)
; #define PG8_WAIT_V(n) asm volatile("s_waitcnt vmcnt(" #n ")" ::: "memory")
; #define PG8_WAIT_L(n) asm volatile("s_waitcnt lgkmcnt(" #n ")" ::: "memory")
; #define PG8_BAR __builtin_amdgcn_s_barrier()
; #define PG8_SCHED __builtin_amdgcn_sched_barrier(0)
; template <class Epi, class Sched>
; __device__ __forceinline__ void gemm_phase(LAS unsigned char* lds, const Gemm g, const Sched& S, const Epi& E, int wave_id) {
;     ...
;         for (int t = 0; t < nt; t += 2) {
;             const bool last = (t == nt - 2);
;             const char* a1 = cA + (size_t)(t + 1) * kstep;
;             const char* a2 = last ? nA : cA + (size_t)(t + 2) * kstep; const char* b2 = last ? nB : cB + (size_t)(t + 2) * kstep;
;             const char* a3 = a2 + kstep; const char* b3 = b2 + kstep;
;             PG8_LDB(B0, 0, 0); PG8_LDB(B1, 0, 1); PG8_SCHED; PG8_LDA(At, 0, 0); PG8_STAGE(PG8_SA(1, 1), a1 + hstepA, voffA);
;             PG8_WAIT_V(8); PG8_WAIT_L(0); PG8_BAR; PG8_MMA(0, 0, At, B0); PG8_MMA(0, 1, At, B1); PG8_BAR; PG8_SCHED;
;             PG8_LDA(At, 0, 1); PG8_STAGE(PG8_SB(0, 0), b2, voffB); PG8_STAGE(PG8_SB(0, 1), b2 + hstepB, voffB); PG8_STAGE(PG8_SA(0, 0), a2, voffA);
;             PG8_WAIT_V(8); PG8_WAIT_L(0); PG8_BAR; PG8_MMA(1, 0, At, B0); PG8_MMA(1, 1, At, B1); PG8_BAR; PG8_SCHED;
.LBB0_1146:
	ds_read_b128 v[128:131], v206
	ds_read_b128 v[132:135], v206 offset:1024
	ds_read_b128 v[136:139], v206 offset:2048
	ds_read_b128 v[140:143], v206 offset:3072
	ds_read_b128 v[144:147], v207
	ds_read_b128 v[148:151], v207 offset:1024
	ds_read_b128 v[178:181], v207 offset:2048
	ds_read_b128 v[182:185], v207 offset:3072
	s_add_u32 s30, s28, 0xfffe0080
	s_addc_u32 s31, s29, -1
	s_cmp_eq_u32 s60, 4
	s_cselect_b32 s35, s21, s31
	s_cselect_b32 s34, s56, s30
	s_cselect_b32 s31, s19, s59
	s_cselect_b32 s30, s57, s58
	v_lshl_add_u64 v[202:203], s[28:29], 0, v[170:171]
	s_add_i32 m0, s38, 0xc000
	ds_read_b128 v[186:189], v208
	ds_read_b128 v[190:193], v208 offset:1024
	ds_read_b128 v[194:197], v208 offset:2048
	ds_read_b128 v[198:201], v208 offset:3072
	ds_read_b128 v[212:215], v208 offset:4096
	ds_read_b128 v[216:219], v208 offset:5120
	ds_read_b128 v[220:223], v208 offset:6144
	ds_read_b128 v[224:227], v208 offset:7168
	global_load_lds_dwordx4 v[202:203], off
	v_lshl_add_u64 v[202:203], s[28:29], 0, v[172:173]
	s_add_i32 m0, s38, 0xe000
	s_nop 0
	global_load_lds_dwordx4 v[202:203], off
	s_waitcnt vmcnt(8)
	s_waitcnt lgkmcnt(0)
	s_barrier
	s_setprio 1
	s_waitcnt lgkmcnt(0)
	v_mfma_f32_16x16x32_bf16 v[124:127], v[128:131], v[186:189], v[124:127]
	v_mfma_f32_16x16x32_bf16 v[120:123], v[136:139], v[186:189], v[120:123]
	v_mfma_f32_16x16x32_bf16 v[108:111], v[128:131], v[194:197], v[108:111]
	v_mfma_f32_16x16x32_bf16 v[104:107], v[136:139], v[194:197], v[104:107]
	v_mfma_f32_16x16x32_bf16 v[92:95], v[128:131], v[212:215], v[92:95]
	v_mfma_f32_16x16x32_bf16 v[88:91], v[136:139], v[212:215], v[88:91]
	v_mfma_f32_16x16x32_bf16 v[76:79], v[128:131], v[220:223], v[76:79]
	v_mfma_f32_16x16x32_bf16 v[72:75], v[136:139], v[220:223], v[72:75]
	v_mfma_f32_16x16x32_bf16 v[124:127], v[132:135], v[190:193], v[124:127]
	v_mfma_f32_16x16x32_bf16 v[120:123], v[140:143], v[190:193], v[120:123]
	v_mfma_f32_16x16x32_bf16 v[108:111], v[132:135], v[198:201], v[108:111]
	v_mfma_f32_16x16x32_bf16 v[104:107], v[140:143], v[198:201], v[104:107]
	v_mfma_f32_16x16x32_bf16 v[92:95], v[132:135], v[216:219], v[92:95]
	v_mfma_f32_16x16x32_bf16 v[88:91], v[140:143], v[216:219], v[88:91]
	v_mfma_f32_16x16x32_bf16 v[76:79], v[132:135], v[224:227], v[76:79]
	v_mfma_f32_16x16x32_bf16 v[72:75], v[140:143], v[224:227], v[72:75]
	s_setprio 0
	s_setprio 1
	v_mfma_f32_16x16x32_bf16 v[116:119], v[144:147], v[186:189], v[116:119]
	v_mfma_f32_16x16x32_bf16 v[112:115], v[178:181], v[186:189], v[112:115]
	v_mfma_f32_16x16x32_bf16 v[100:103], v[144:147], v[194:197], v[100:103]
	v_mfma_f32_16x16x32_bf16 v[96:99], v[178:181], v[194:197], v[96:99]
	v_mfma_f32_16x16x32_bf16 v[84:87], v[144:147], v[212:215], v[84:87]
	v_mfma_f32_16x16x32_bf16 v[80:83], v[178:181], v[212:215], v[80:83]
	v_mfma_f32_16x16x32_bf16 v[68:71], v[144:147], v[220:223], v[68:71]
	v_mfma_f32_16x16x32_bf16 v[64:67], v[178:181], v[220:223], v[64:67]
	v_mfma_f32_16x16x32_bf16 v[116:119], v[148:151], v[190:193], v[116:119]
	v_mfma_f32_16x16x32_bf16 v[112:115], v[182:185], v[190:193], v[112:115]
	v_mfma_f32_16x16x32_bf16 v[100:103], v[148:151], v[198:201], v[100:103]
	v_mfma_f32_16x16x32_bf16 v[96:99], v[182:185], v[198:201], v[96:99]
	v_mfma_f32_16x16x32_bf16 v[84:87], v[148:151], v[216:219], v[84:87]
	v_mfma_f32_16x16x32_bf16 v[80:83], v[182:185], v[216:219], v[80:83]
	v_mfma_f32_16x16x32_bf16 v[68:71], v[148:151], v[224:227], v[68:71]
	v_mfma_f32_16x16x32_bf16 v[64:67], v[182:185], v[224:227], v[64:67]
	s_setprio 0
	s_barrier
	s_add_i32 s61, s54, s37
	v_lshl_add_u64 v[202:203], s[30:31], 0, v[154:155]
	s_mov_b32 m0, s61
	ds_read_b128 v[186:189], v208 offset:16384
	ds_read_b128 v[190:193], v208 offset:17408
	ds_read_b128 v[194:197], v208 offset:18432
	ds_read_b128 v[198:201], v208 offset:19456
	ds_read_b128 v[212:215], v208 offset:20480
	ds_read_b128 v[216:219], v208 offset:21504
	ds_read_b128 v[220:223], v208 offset:22528
	ds_read_b128 v[224:227], v208 offset:23552
	global_load_lds_dwordx4 v[202:203], off
	s_add_i32 m0, s61, 0x2000
	s_add_u32 s62, s30, 0x20000
	v_lshl_add_u64 v[228:229], s[30:31], 0, v[158:159]
	s_addc_u32 s63, s31, 0
	s_add_i32 s61, s55, s37
	global_load_lds_dwordx4 v[228:229], off
	v_lshl_add_u64 v[230:231], s[62:63], 0, v[154:155]
	s_mov_b32 m0, s61
	v_lshl_add_u64 v[232:233], s[34:35], 0, v[156:157]
	global_load_lds_dwordx4 v[230:231], off
	v_lshl_add_u64 v[230:231], s[62:63], 0, v[158:159]
	s_add_i32 m0, s61, 0x2000
	s_nop 0
	global_load_lds_dwordx4 v[230:231], off
	v_lshl_add_u64 v[230:231], s[34:35], 0, v[152:153]
	s_mov_b32 m0, s38
	s_nop 0
	global_load_lds_dwordx4 v[230:231], off
	s_mov_b32 m0, s39
	s_nop 0
	global_load_lds_dwordx4 v[232:233], off
	s_waitcnt vmcnt(8)
	s_waitcnt lgkmcnt(0)
	s_barrier
; #define PG8_STAGE(bufoff, gbase, voff) do { _Pragma("unroll") for (int _i = 0; _i < 2; ++_i) \
;         __builtin_amdgcn_global_load_lds((const unsigned*)((const char*)(gbase) + (voff)[_i]), (LAS unsigned*)(lds + (bufoff) + ldsw + _i * 8192), 16, 0, 0); } while (0)
; #define PG8_LDA(dst, b, h) do { _Pragma("unroll") for (int m = 0; m < 4; ++m) _Pragma("unroll") for (int k = 0; k < 2; ++k) dst[m][k] = *(const LAS bf16x8*)(lds + PG8_SA(b, h) + aoff + m * 2048 + k * 1024); } while (0)
; #define PG8_LDB(dst, b, h) do { _Pragma("unroll") for (int n = 0; n < 2; ++n) _Pragma("unroll") for (int k = 0; k < 2; ++k) dst[n][k] = *(const LAS bf16x8*)(lds + PG8_SB(b, h) + boff + n * 2048 + k * 1024); } while (0)
; #define PG8_MMA(ai, bj, At, Bt) do { __builtin_amdgcn_s_setprio(1); _Pragma("unroll") for (int m = 0; m < 4; ++m) _Pragma("unroll") for (int n = 0; n < 2; ++n) _Pragma("unroll") for (int k = 0; k < 2; ++k) \
;         acc[ai][bj][m][n] = __builtin_amdgcn_mfma_f32_16x16x32_bf16(Bt[n][k], At[m][k], acc[ai][bj][m][n], 0, 0, 0); __builtin_amdgcn_s_setprio(0); } while (0)
; #define PG8_WAIT_V(n) asm volatile("s_waitcnt vmcnt(" #n ")" ::: "memory")
; #define PG8_WAIT_L(n) asm volatile("s_waitcnt lgkmcnt(" #n ")" ::: "memory")
; #define PG8_BAR __builtin_amdgcn_s_barrier()
; #define PG8_SCHED __builtin_amdgcn_sched_barrier(0)
; template <class Epi, class Sched>
; __device__ __forceinline__ void gemm_phase(LAS unsigned char* lds, const Gemm g, const Sched& S, const Epi& E, int wave_id) {
;     ...
;             PG8_WAIT_V(8); PG8_WAIT_L(0); PG8_BAR; PG8_MMA(1, 0, At, B0); PG8_MMA(1, 1, At, B1); PG8_BAR; PG8_SCHED;
;             PG8_LDB(B0, 1, 0); PG8_LDB(B1, 1, 1); PG8_SCHED; PG8_LDA(At, 1, 0); PG8_STAGE(PG8_SA(0, 1), a2 + hstepA, voffA);
;             PG8_WAIT_V(8); PG8_WAIT_L(0); PG8_BAR; PG8_MMA(0, 0, At, B0); PG8_MMA(0, 1, At, B1); PG8_BAR; PG8_SCHED;
	s_setprio 1
	s_waitcnt lgkmcnt(0)
	v_mfma_f32_16x16x32_bf16 v[60:63], v[128:131], v[186:189], v[60:63]
	v_mfma_f32_16x16x32_bf16 v[56:59], v[136:139], v[186:189], v[56:59]
	v_mfma_f32_16x16x32_bf16 v[44:47], v[128:131], v[194:197], v[44:47]
	v_mfma_f32_16x16x32_bf16 v[40:43], v[136:139], v[194:197], v[40:43]
	v_mfma_f32_16x16x32_bf16 v[28:31], v[128:131], v[212:215], v[28:31]
	v_mfma_f32_16x16x32_bf16 v[24:27], v[136:139], v[212:215], v[24:27]
	v_mfma_f32_16x16x32_bf16 v[12:15], v[128:131], v[220:223], v[12:15]
	v_mfma_f32_16x16x32_bf16 v[8:11], v[136:139], v[220:223], v[8:11]
	v_mfma_f32_16x16x32_bf16 v[60:63], v[132:135], v[190:193], v[60:63]
	v_mfma_f32_16x16x32_bf16 v[56:59], v[140:143], v[190:193], v[56:59]
	v_mfma_f32_16x16x32_bf16 v[44:47], v[132:135], v[198:201], v[44:47]
	v_mfma_f32_16x16x32_bf16 v[40:43], v[140:143], v[198:201], v[40:43]
	v_mfma_f32_16x16x32_bf16 v[28:31], v[132:135], v[216:219], v[28:31]
	v_mfma_f32_16x16x32_bf16 v[24:27], v[140:143], v[216:219], v[24:27]
	v_mfma_f32_16x16x32_bf16 v[12:15], v[132:135], v[224:227], v[12:15]
	v_mfma_f32_16x16x32_bf16 v[8:11], v[140:143], v[224:227], v[8:11]
	s_setprio 0
	s_setprio 1
	v_mfma_f32_16x16x32_bf16 v[52:55], v[144:147], v[186:189], v[52:55]
	v_mfma_f32_16x16x32_bf16 v[48:51], v[178:181], v[186:189], v[48:51]
	v_mfma_f32_16x16x32_bf16 v[36:39], v[144:147], v[194:197], v[36:39]
	v_mfma_f32_16x16x32_bf16 v[32:35], v[178:181], v[194:197], v[32:35]
	v_mfma_f32_16x16x32_bf16 v[20:23], v[144:147], v[212:215], v[20:23]
	v_mfma_f32_16x16x32_bf16 v[16:19], v[178:181], v[212:215], v[16:19]
	v_mfma_f32_16x16x32_bf16 v[4:7], v[144:147], v[220:223], v[4:7]
	v_mfma_f32_16x16x32_bf16 v[0:3], v[178:181], v[220:223], v[0:3]
	v_mfma_f32_16x16x32_bf16 v[52:55], v[148:151], v[190:193], v[52:55]
	v_mfma_f32_16x16x32_bf16 v[48:51], v[182:185], v[190:193], v[48:51]
	v_mfma_f32_16x16x32_bf16 v[36:39], v[148:151], v[198:201], v[36:39]
	v_mfma_f32_16x16x32_bf16 v[32:35], v[182:185], v[198:201], v[32:35]
	v_mfma_f32_16x16x32_bf16 v[20:23], v[148:151], v[216:219], v[20:23]
	v_mfma_f32_16x16x32_bf16 v[16:19], v[182:185], v[216:219], v[16:19]
	v_mfma_f32_16x16x32_bf16 v[4:7], v[148:151], v[224:227], v[4:7]
	v_mfma_f32_16x16x32_bf16 v[0:3], v[182:185], v[224:227], v[0:3]
	s_setprio 0
	s_barrier
	s_add_i32 s61, 0, 0x18000
	s_add_i32 s62, 0, 0x1c000
	v_add_u32_e32 v140, s61, v205
	v_add_u32_e32 v182, s62, v205
	ds_read_b128 v[128:131], v140
	ds_read_b128 v[132:135], v140 offset:1024
	ds_read_b128 v[136:139], v140 offset:2048
	ds_read_b128 v[140:143], v140 offset:3072
	ds_read_b128 v[144:147], v182
	ds_read_b128 v[148:151], v182 offset:1024
	ds_read_b128 v[178:181], v182 offset:2048
	ds_read_b128 v[182:185], v182 offset:3072
	s_add_u32 s34, s34, 0x20000
	s_addc_u32 s35, s35, 0
	s_mov_b32 m0, s40
	v_lshl_add_u64 v[234:235], s[34:35], 0, v[152:153]
	ds_read_b128 v[186:189], v208 offset:32768
	ds_read_b128 v[190:193], v208 offset:33792
	ds_read_b128 v[194:197], v208 offset:34816
	ds_read_b128 v[198:201], v208 offset:35840
	ds_read_b128 v[212:215], v208 offset:36864
	ds_read_b128 v[216:219], v208 offset:37888
	ds_read_b128 v[220:223], v208 offset:38912
	ds_read_b128 v[224:227], v208 offset:39936
	global_load_lds_dwordx4 v[234:235], off
	v_lshl_add_u64 v[234:235], s[34:35], 0, v[156:157]
	s_mov_b32 m0, s41
	s_nop 0
	global_load_lds_dwordx4 v[234:235], off
	s_waitcnt vmcnt(8)
	s_waitcnt lgkmcnt(0)
	s_barrier
	s_setprio 1
	s_waitcnt lgkmcnt(0)
	v_mfma_f32_16x16x32_bf16 v[124:127], v[128:131], v[186:189], v[124:127]
	v_mfma_f32_16x16x32_bf16 v[120:123], v[136:139], v[186:189], v[120:123]
	v_mfma_f32_16x16x32_bf16 v[108:111], v[128:131], v[194:197], v[108:111]
	v_mfma_f32_16x16x32_bf16 v[104:107], v[136:139], v[194:197], v[104:107]
	v_mfma_f32_16x16x32_bf16 v[92:95], v[128:131], v[212:215], v[92:95]
	v_mfma_f32_16x16x32_bf16 v[88:91], v[136:139], v[212:215], v[88:91]
	v_mfma_f32_16x16x32_bf16 v[76:79], v[128:131], v[220:223], v[76:79]
	v_mfma_f32_16x16x32_bf16 v[72:75], v[136:139], v[220:223], v[72:75]
	v_mfma_f32_16x16x32_bf16 v[124:127], v[132:135], v[190:193], v[124:127]
	v_mfma_f32_16x16x32_bf16 v[120:123], v[140:143], v[190:193], v[120:123]
	v_mfma_f32_16x16x32_bf16 v[108:111], v[132:135], v[198:201], v[108:111]
	v_mfma_f32_16x16x32_bf16 v[104:107], v[140:143], v[198:201], v[104:107]
	v_mfma_f32_16x16x32_bf16 v[92:95], v[132:135], v[216:219], v[92:95]
	v_mfma_f32_16x16x32_bf16 v[88:91], v[140:143], v[216:219], v[88:91]
	v_mfma_f32_16x16x32_bf16 v[76:79], v[132:135], v[224:227], v[76:79]
	v_mfma_f32_16x16x32_bf16 v[72:75], v[140:143], v[224:227], v[72:75]
	s_setprio 0
	s_setprio 1
	v_mfma_f32_16x16x32_bf16 v[116:119], v[144:147], v[186:189], v[116:119]
	v_mfma_f32_16x16x32_bf16 v[112:115], v[178:181], v[186:189], v[112:115]
	v_mfma_f32_16x16x32_bf16 v[100:103], v[144:147], v[194:197], v[100:103]
	v_mfma_f32_16x16x32_bf16 v[96:99], v[178:181], v[194:197], v[96:99]
	v_mfma_f32_16x16x32_bf16 v[84:87], v[144:147], v[212:215], v[84:87]
	v_mfma_f32_16x16x32_bf16 v[80:83], v[178:181], v[212:215], v[80:83]
	v_mfma_f32_16x16x32_bf16 v[68:71], v[144:147], v[220:223], v[68:71]
	v_mfma_f32_16x16x32_bf16 v[64:67], v[178:181], v[220:223], v[64:67]
	v_mfma_f32_16x16x32_bf16 v[116:119], v[148:151], v[190:193], v[116:119]
	v_mfma_f32_16x16x32_bf16 v[112:115], v[182:185], v[190:193], v[112:115]
	v_mfma_f32_16x16x32_bf16 v[100:103], v[148:151], v[198:201], v[100:103]
	v_mfma_f32_16x16x32_bf16 v[96:99], v[182:185], v[198:201], v[96:99]
	v_mfma_f32_16x16x32_bf16 v[84:87], v[148:151], v[216:219], v[84:87]
	v_mfma_f32_16x16x32_bf16 v[80:83], v[182:185], v[216:219], v[80:83]
	v_mfma_f32_16x16x32_bf16 v[68:71], v[148:151], v[224:227], v[68:71]
	v_mfma_f32_16x16x32_bf16 v[64:67], v[182:185], v[224:227], v[64:67]
	s_setprio 0
	s_barrier
; #define PG8_STAGE(bufoff, gbase, voff) do { _Pragma("unroll") for (int _i = 0; _i < 2; ++_i) \
;         __builtin_amdgcn_global_load_lds((const unsigned*)((const char*)(gbase) + (voff)[_i]), (LAS unsigned*)(lds + (bufoff) + ldsw + _i * 8192), 16, 0, 0); } while (0)
; #define PG8_LDA(dst, b, h) do { _Pragma("unroll") for (int m = 0; m < 4; ++m) _Pragma("unroll") for (int k = 0; k < 2; ++k) dst[m][k] = *(const LAS bf16x8*)(lds + PG8_SA(b, h) + aoff + m * 2048 + k * 1024); } while (0)
; #define PG8_MMA(ai, bj, At, Bt) do { __builtin_amdgcn_s_setprio(1); _Pragma("unroll") for (int m = 0; m < 4; ++m) _Pragma("unroll") for (int n = 0; n < 2; ++n) _Pragma("unroll") for (int k = 0; k < 2; ++k) \
;         acc[ai][bj][m][n] = __builtin_amdgcn_mfma_f32_16x16x32_bf16(Bt[n][k], At[m][k], acc[ai][bj][m][n], 0, 0, 0); __builtin_amdgcn_s_setprio(0); } while (0)
; #define PG8_WAIT_V(n) asm volatile("s_waitcnt vmcnt(" #n ")" ::: "memory")
; #define PG8_WAIT_L(n) asm volatile("s_waitcnt lgkmcnt(" #n ")" ::: "memory")
; #define PG8_BAR __builtin_amdgcn_s_barrier()
; #define PG8_SCHED __builtin_amdgcn_sched_barrier(0)
; template <class Epi, class Sched>
; __device__ __forceinline__ void gemm_phase(LAS unsigned char* lds, const Gemm g, const Sched& S, const Epi& E, int wave_id) {
;     ...
;             PG8_LDA(At, 1, 1); PG8_STAGE(PG8_SB(1, 0), b3, voffB); PG8_STAGE(PG8_SB(1, 1), b3 + hstepB, voffB); PG8_STAGE(PG8_SA(1, 0), a3, voffA);
;             PG8_WAIT_V(8); PG8_WAIT_L(0); PG8_BAR; PG8_MMA(1, 0, At, B0); PG8_MMA(1, 1, At, B1); PG8_BAR; PG8_SCHED;
;         }
	s_add_i32 s34, s61, s37
	v_lshl_add_u64 v[202:203], v[202:203], 0, s[12:13]
	s_mov_b32 m0, s34
	ds_read_b128 v[186:189], v208 offset:49152
	ds_read_b128 v[190:193], v208 offset:50176
	ds_read_b128 v[194:197], v208 offset:51200
	ds_read_b128 v[198:201], v208 offset:52224
	ds_read_b128 v[212:215], v208 offset:53248
	ds_read_b128 v[216:219], v208 offset:54272
	ds_read_b128 v[220:223], v208 offset:55296
	ds_read_b128 v[224:227], v208 offset:56320
	global_load_lds_dwordx4 v[202:203], off
	s_add_i32 m0, s34, 0x2000
	s_add_u32 s30, s30, 0x20080
	v_lshl_add_u64 v[202:203], v[228:229], 0, s[12:13]
	s_addc_u32 s31, s31, 0
	s_add_i32 s34, s62, s37
	global_load_lds_dwordx4 v[202:203], off
	v_lshl_add_u64 v[202:203], s[30:31], 0, v[154:155]
	s_mov_b32 m0, s34
	s_nop 0
	global_load_lds_dwordx4 v[202:203], off
	v_lshl_add_u64 v[202:203], s[30:31], 0, v[158:159]
	s_add_i32 m0, s34, 0x2000
	s_nop 0
	global_load_lds_dwordx4 v[202:203], off
	v_lshl_add_u64 v[202:203], v[230:231], 0, s[12:13]
	s_mov_b32 m0, s44
	s_nop 0
	global_load_lds_dwordx4 v[202:203], off
	v_lshl_add_u64 v[202:203], v[232:233], 0, s[12:13]
	s_mov_b32 m0, s45
	s_nop 0
	global_load_lds_dwordx4 v[202:203], off
	s_waitcnt vmcnt(8)
	s_waitcnt lgkmcnt(0)
	s_barrier
	s_setprio 1
	s_waitcnt lgkmcnt(0)
	v_mfma_f32_16x16x32_bf16 v[60:63], v[128:131], v[186:189], v[60:63]
	v_mfma_f32_16x16x32_bf16 v[56:59], v[136:139], v[186:189], v[56:59]
	v_mfma_f32_16x16x32_bf16 v[44:47], v[128:131], v[194:197], v[44:47]
	v_mfma_f32_16x16x32_bf16 v[40:43], v[136:139], v[194:197], v[40:43]
	v_mfma_f32_16x16x32_bf16 v[28:31], v[128:131], v[212:215], v[28:31]
	v_mfma_f32_16x16x32_bf16 v[24:27], v[136:139], v[212:215], v[24:27]
	v_mfma_f32_16x16x32_bf16 v[12:15], v[128:131], v[220:223], v[12:15]
	v_mfma_f32_16x16x32_bf16 v[8:11], v[136:139], v[220:223], v[8:11]
	v_mfma_f32_16x16x32_bf16 v[60:63], v[132:135], v[190:193], v[60:63]
	v_mfma_f32_16x16x32_bf16 v[56:59], v[140:143], v[190:193], v[56:59]
	v_mfma_f32_16x16x32_bf16 v[44:47], v[132:135], v[198:201], v[44:47]
	v_mfma_f32_16x16x32_bf16 v[40:43], v[140:143], v[198:201], v[40:43]
	v_mfma_f32_16x16x32_bf16 v[28:31], v[132:135], v[216:219], v[28:31]
	v_mfma_f32_16x16x32_bf16 v[24:27], v[140:143], v[216:219], v[24:27]
	v_mfma_f32_16x16x32_bf16 v[12:15], v[132:135], v[224:227], v[12:15]
	v_mfma_f32_16x16x32_bf16 v[8:11], v[140:143], v[224:227], v[8:11]
	s_setprio 0
	s_setprio 1
	v_mfma_f32_16x16x32_bf16 v[52:55], v[144:147], v[186:189], v[52:55]
	v_mfma_f32_16x16x32_bf16 v[48:51], v[178:181], v[186:189], v[48:51]
	v_mfma_f32_16x16x32_bf16 v[36:39], v[144:147], v[194:197], v[36:39]
	v_mfma_f32_16x16x32_bf16 v[32:35], v[178:181], v[194:197], v[32:35]
	v_mfma_f32_16x16x32_bf16 v[20:23], v[144:147], v[212:215], v[20:23]
	v_mfma_f32_16x16x32_bf16 v[16:19], v[178:181], v[212:215], v[16:19]
	v_mfma_f32_16x16x32_bf16 v[4:7], v[144:147], v[220:223], v[4:7]
	v_mfma_f32_16x16x32_bf16 v[0:3], v[178:181], v[220:223], v[0:3]
	v_mfma_f32_16x16x32_bf16 v[52:55], v[148:151], v[190:193], v[52:55]
	v_mfma_f32_16x16x32_bf16 v[48:51], v[182:185], v[190:193], v[48:51]
	v_mfma_f32_16x16x32_bf16 v[36:39], v[148:151], v[198:201], v[36:39]
	v_mfma_f32_16x16x32_bf16 v[32:35], v[182:185], v[198:201], v[32:35]
	v_mfma_f32_16x16x32_bf16 v[20:23], v[148:151], v[216:219], v[20:23]
	v_mfma_f32_16x16x32_bf16 v[16:19], v[182:185], v[216:219], v[16:19]
	v_mfma_f32_16x16x32_bf16 v[4:7], v[148:151], v[224:227], v[4:7]
	v_mfma_f32_16x16x32_bf16 v[0:3], v[182:185], v[224:227], v[0:3]
	s_setprio 0
	s_add_i32 s60, s60, 2
	s_add_u32 s28, s28, 0x100
	s_addc_u32 s29, s29, 0
	s_add_u32 s58, s58, 0x100
	s_addc_u32 s59, s59, 0
	s_cmp_gt_u32 s60, 5
	s_barrier
	s_cbranch_scc0 .LBB0_1146
	s_and_b64 vcc, exec, s[14:15]
	s_cbranch_vccz .LBB0_1149
	s_barrier

; #define PG8_STAGE(bufoff, gbase, voff) do { _Pragma("unroll") for (int _i = 0; _i < 2; ++_i) \
;         __builtin_amdgcn_global_load_lds((const unsigned*)((const char*)(gbase) + (voff)[_i]), (LAS unsigned*)(lds + (bufoff) + ldsw + _i * 8192), 16, 0, 0); } while (0)
; #define PG8_LDA(dst, b, h) do { _Pragma("unroll") for (int m = 0; m < 4; ++m) _Pragma("unroll") for (int k = 0; k < 2; ++k) dst[m][k] = *(const LAS bf16x8*)(lds + PG8_SA(b, h) + aoff + m * 2048 + k * 1024); } while (0)
; #define PG8_LDB(dst, b, h) do { _Pragma("unroll") for (int n = 0; n < 2; ++n) _Pragma("unroll") for (int k = 0; k < 2; ++k) dst[n][k] = *(const LAS bf16x8*)(lds + PG8_SB(b, h) + boff + n * 2048 + k * 1024); } while (0)
; #define PG8_MMA(ai, bj, At, Bt) do { __builtin_amdgcn_s_setprio(1); _Pragma("unroll") for (int m = 0; m < 4; ++m) _Pragma("unroll") for (int n = 0; n < 2; ++n) _Pragma("unroll") for (int k = 0; k < 2; ++k) \
;         acc[ai][bj][m][n] = __builtin_amdgcn_mfma_f32_16x16x32_bf16(Bt[n][k], At[m][k], acc[ai][bj][m][n], 0, 0, 0); __builtin_amdgcn_s_setprio(0); } while (0)
; #define PG8_WAIT_V(n) asm volatile("s_waitcnt vmcnt(" #n ")" ::: "memory")
; #define PG8_WAIT_L(n) asm volatile("s_waitcnt lgkmcnt(" #n ")" ::: "memory")
; #define PG8_BAR __builtin_amdgcn_s_barrier()
; #define PG8_SCHED __builtin_amdgcn_sched_barrier(0)
; template <class Epi, class Sched>
; __device__ __forceinline__ void gemm_phase(LAS unsigned char* lds, const Gemm g, const Sched& S, const Epi& E, int wave_id) {
;     ...
;         for (int t = 0; t < nt; t += 2) {
;             const bool last = (t == nt - 2);
;             const char* a1 = cA + (size_t)(t + 1) * kstep;
;             const char* a2 = last ? nA : cA + (size_t)(t + 2) * kstep; const char* b2 = last ? nB : cB + (size_t)(t + 2) * kstep;
;             const char* a3 = a2 + kstep; const char* b3 = b2 + kstep;
;             PG8_LDB(B0, 0, 0); PG8_LDB(B1, 0, 1); PG8_SCHED; PG8_LDA(At, 0, 0); PG8_STAGE(PG8_SA(1, 1), a1 + hstepA, voffA);
;             PG8_WAIT_V(8); PG8_WAIT_L(0); PG8_BAR; PG8_MMA(0, 0, At, B0); PG8_MMA(0, 1, At, B1); PG8_BAR; PG8_SCHED;
;             PG8_LDA(At, 0, 1); PG8_STAGE(PG8_SB(0, 0), b2, voffB); PG8_STAGE(PG8_SB(0, 1), b2 + hstepB, voffB); PG8_STAGE(PG8_SA(0, 0), a2, voffA);
;             PG8_WAIT_V(8); PG8_WAIT_L(0); PG8_BAR; PG8_MMA(1, 0, At, B0); PG8_MMA(1, 1, At, B1); PG8_BAR; PG8_SCHED;
.LBB0_1251:
	ds_read_b128 v[128:131], v178
	ds_read_b128 v[132:135], v178 offset:1024
	ds_read_b128 v[136:139], v178 offset:2048
	ds_read_b128 v[140:143], v178 offset:3072
	ds_read_b128 v[170:173], v179
	ds_read_b128 v[184:187], v179 offset:1024
	ds_read_b128 v[188:191], v179 offset:2048
	ds_read_b128 v[192:195], v179 offset:3072
	s_add_u32 s36, s34, 0xfffc0080
	s_addc_u32 s37, s35, -1
	s_cmp_eq_u32 s67, 12
	s_cselect_b32 s39, s25, s37
	s_cselect_b32 s38, s63, s36
	s_cselect_b32 s37, s23, s66
	s_cselect_b32 s36, s64, s65
	v_lshl_add_u64 v[174:175], s[34:35], 0, v[162:163]
	s_add_i32 m0, s49, 0xc000
	ds_read_b128 v[196:199], v180
	ds_read_b128 v[200:203], v180 offset:1024
	ds_read_b128 v[204:207], v180 offset:2048
	ds_read_b128 v[208:211], v180 offset:3072
	ds_read_b128 v[212:215], v180 offset:4096
	ds_read_b128 v[216:219], v180 offset:5120
	ds_read_b128 v[220:223], v180 offset:6144
	ds_read_b128 v[224:227], v180 offset:7168
	global_load_lds_dwordx4 v[174:175], off
	v_lshl_add_u64 v[174:175], s[34:35], 0, v[164:165]
	s_add_i32 m0, s49, 0xe000
	s_nop 0
	global_load_lds_dwordx4 v[174:175], off
	s_waitcnt vmcnt(8)
	s_waitcnt lgkmcnt(0)
	s_barrier
	s_setprio 1
	s_waitcnt lgkmcnt(0)
	v_mfma_f32_16x16x32_bf16 v[124:127], v[128:131], v[196:199], v[124:127]
	v_mfma_f32_16x16x32_bf16 v[120:123], v[136:139], v[196:199], v[120:123]
	v_mfma_f32_16x16x32_bf16 v[108:111], v[128:131], v[204:207], v[108:111]
	v_mfma_f32_16x16x32_bf16 v[104:107], v[136:139], v[204:207], v[104:107]
	v_mfma_f32_16x16x32_bf16 v[92:95], v[128:131], v[212:215], v[92:95]
	v_mfma_f32_16x16x32_bf16 v[88:91], v[136:139], v[212:215], v[88:91]
	v_mfma_f32_16x16x32_bf16 v[76:79], v[128:131], v[220:223], v[76:79]
	v_mfma_f32_16x16x32_bf16 v[72:75], v[136:139], v[220:223], v[72:75]
	v_mfma_f32_16x16x32_bf16 v[124:127], v[132:135], v[200:203], v[124:127]
	v_mfma_f32_16x16x32_bf16 v[120:123], v[140:143], v[200:203], v[120:123]
	v_mfma_f32_16x16x32_bf16 v[108:111], v[132:135], v[208:211], v[108:111]
	v_mfma_f32_16x16x32_bf16 v[104:107], v[140:143], v[208:211], v[104:107]
	v_mfma_f32_16x16x32_bf16 v[92:95], v[132:135], v[216:219], v[92:95]
	v_mfma_f32_16x16x32_bf16 v[88:91], v[140:143], v[216:219], v[88:91]
	v_mfma_f32_16x16x32_bf16 v[76:79], v[132:135], v[224:227], v[76:79]
	v_mfma_f32_16x16x32_bf16 v[72:75], v[140:143], v[224:227], v[72:75]
	s_setprio 0
	s_setprio 1
	v_mfma_f32_16x16x32_bf16 v[116:119], v[170:173], v[196:199], v[116:119]
	v_mfma_f32_16x16x32_bf16 v[112:115], v[188:191], v[196:199], v[112:115]
	v_mfma_f32_16x16x32_bf16 v[100:103], v[170:173], v[204:207], v[100:103]
	v_mfma_f32_16x16x32_bf16 v[96:99], v[188:191], v[204:207], v[96:99]
	v_mfma_f32_16x16x32_bf16 v[84:87], v[170:173], v[212:215], v[84:87]
	v_mfma_f32_16x16x32_bf16 v[80:83], v[188:191], v[212:215], v[80:83]
	v_mfma_f32_16x16x32_bf16 v[68:71], v[170:173], v[220:223], v[68:71]
	v_mfma_f32_16x16x32_bf16 v[64:67], v[188:191], v[220:223], v[64:67]
	v_mfma_f32_16x16x32_bf16 v[116:119], v[184:187], v[200:203], v[116:119]
	v_mfma_f32_16x16x32_bf16 v[112:115], v[192:195], v[200:203], v[112:115]
	v_mfma_f32_16x16x32_bf16 v[100:103], v[184:187], v[208:211], v[100:103]
	v_mfma_f32_16x16x32_bf16 v[96:99], v[192:195], v[208:211], v[96:99]
	v_mfma_f32_16x16x32_bf16 v[84:87], v[184:187], v[216:219], v[84:87]
	v_mfma_f32_16x16x32_bf16 v[80:83], v[192:195], v[216:219], v[80:83]
	v_mfma_f32_16x16x32_bf16 v[68:71], v[184:187], v[224:227], v[68:71]
	v_mfma_f32_16x16x32_bf16 v[64:67], v[192:195], v[224:227], v[64:67]
	s_setprio 0
	s_barrier
	s_add_i32 s72, s60, s2
	v_lshl_add_u64 v[174:175], s[36:37], 0, v[146:147]
	s_mov_b32 m0, s72
	ds_read_b128 v[196:199], v180 offset:16384
	ds_read_b128 v[200:203], v180 offset:17408
	ds_read_b128 v[204:207], v180 offset:18432
	ds_read_b128 v[208:211], v180 offset:19456
	ds_read_b128 v[212:215], v180 offset:20480
	ds_read_b128 v[216:219], v180 offset:21504
	ds_read_b128 v[220:223], v180 offset:22528
	ds_read_b128 v[224:227], v180 offset:23552
	global_load_lds_dwordx4 v[174:175], off
	s_add_i32 m0, s72, 0x2000
	s_add_u32 s72, s36, 0x40000
	v_lshl_add_u64 v[228:229], s[36:37], 0, v[150:151]
	s_addc_u32 s73, s37, 0
	s_add_i32 s74, s61, s2
	global_load_lds_dwordx4 v[228:229], off
	v_lshl_add_u64 v[230:231], s[72:73], 0, v[146:147]
	s_mov_b32 m0, s74
	v_lshl_add_u64 v[232:233], s[38:39], 0, v[148:149]
	global_load_lds_dwordx4 v[230:231], off
	v_lshl_add_u64 v[230:231], s[72:73], 0, v[150:151]
	s_add_i32 m0, s74, 0x2000
	s_nop 0
	global_load_lds_dwordx4 v[230:231], off
	v_lshl_add_u64 v[230:231], s[38:39], 0, v[144:145]
	s_mov_b32 m0, s49
	s_nop 0
	global_load_lds_dwordx4 v[230:231], off
	s_mov_b32 m0, s50
	s_nop 0
	global_load_lds_dwordx4 v[232:233], off
	s_waitcnt vmcnt(8)
	s_waitcnt lgkmcnt(0)
	s_barrier
; #define PG8_STAGE(bufoff, gbase, voff) do { _Pragma("unroll") for (int _i = 0; _i < 2; ++_i) \
;         __builtin_amdgcn_global_load_lds((const unsigned*)((const char*)(gbase) + (voff)[_i]), (LAS unsigned*)(lds + (bufoff) + ldsw + _i * 8192), 16, 0, 0); } while (0)
; #define PG8_LDA(dst, b, h) do { _Pragma("unroll") for (int m = 0; m < 4; ++m) _Pragma("unroll") for (int k = 0; k < 2; ++k) dst[m][k] = *(const LAS bf16x8*)(lds + PG8_SA(b, h) + aoff + m * 2048 + k * 1024); } while (0)
; #define PG8_LDB(dst, b, h) do { _Pragma("unroll") for (int n = 0; n < 2; ++n) _Pragma("unroll") for (int k = 0; k < 2; ++k) dst[n][k] = *(const LAS bf16x8*)(lds + PG8_SB(b, h) + boff + n * 2048 + k * 1024); } while (0)
; #define PG8_MMA(ai, bj, At, Bt) do { __builtin_amdgcn_s_setprio(1); _Pragma("unroll") for (int m = 0; m < 4; ++m) _Pragma("unroll") for (int n = 0; n < 2; ++n) _Pragma("unroll") for (int k = 0; k < 2; ++k) \
;         acc[ai][bj][m][n] = __builtin_amdgcn_mfma_f32_16x16x32_bf16(Bt[n][k], At[m][k], acc[ai][bj][m][n], 0, 0, 0); __builtin_amdgcn_s_setprio(0); } while (0)
; #define PG8_WAIT_V(n) asm volatile("s_waitcnt vmcnt(" #n ")" ::: "memory")
; #define PG8_WAIT_L(n) asm volatile("s_waitcnt lgkmcnt(" #n ")" ::: "memory")
; #define PG8_BAR __builtin_amdgcn_s_barrier()
; #define PG8_SCHED __builtin_amdgcn_sched_barrier(0)
; template <class Epi, class Sched>
; __device__ __forceinline__ void gemm_phase(LAS unsigned char* lds, const Gemm g, const Sched& S, const Epi& E, int wave_id) {
;     ...
;             PG8_WAIT_V(8); PG8_WAIT_L(0); PG8_BAR; PG8_MMA(1, 0, At, B0); PG8_MMA(1, 1, At, B1); PG8_BAR; PG8_SCHED;
;             PG8_LDB(B0, 1, 0); PG8_LDB(B1, 1, 1); PG8_SCHED; PG8_LDA(At, 1, 0); PG8_STAGE(PG8_SA(0, 1), a2 + hstepA, voffA);
;             PG8_WAIT_V(8); PG8_WAIT_L(0); PG8_BAR; PG8_MMA(0, 0, At, B0); PG8_MMA(0, 1, At, B1); PG8_BAR; PG8_SCHED;
	s_setprio 1
	s_waitcnt lgkmcnt(0)
	v_mfma_f32_16x16x32_bf16 v[60:63], v[128:131], v[196:199], v[60:63]
	v_mfma_f32_16x16x32_bf16 v[56:59], v[136:139], v[196:199], v[56:59]
	v_mfma_f32_16x16x32_bf16 v[44:47], v[128:131], v[204:207], v[44:47]
	v_mfma_f32_16x16x32_bf16 v[40:43], v[136:139], v[204:207], v[40:43]
	v_mfma_f32_16x16x32_bf16 v[28:31], v[128:131], v[212:215], v[28:31]
	v_mfma_f32_16x16x32_bf16 v[24:27], v[136:139], v[212:215], v[24:27]
	v_mfma_f32_16x16x32_bf16 v[12:15], v[128:131], v[220:223], v[12:15]
	v_mfma_f32_16x16x32_bf16 v[8:11], v[136:139], v[220:223], v[8:11]
	v_mfma_f32_16x16x32_bf16 v[60:63], v[132:135], v[200:203], v[60:63]
	v_mfma_f32_16x16x32_bf16 v[56:59], v[140:143], v[200:203], v[56:59]
	v_mfma_f32_16x16x32_bf16 v[44:47], v[132:135], v[208:211], v[44:47]
	v_mfma_f32_16x16x32_bf16 v[40:43], v[140:143], v[208:211], v[40:43]
	v_mfma_f32_16x16x32_bf16 v[28:31], v[132:135], v[216:219], v[28:31]
	v_mfma_f32_16x16x32_bf16 v[24:27], v[140:143], v[216:219], v[24:27]
	v_mfma_f32_16x16x32_bf16 v[12:15], v[132:135], v[224:227], v[12:15]
	v_mfma_f32_16x16x32_bf16 v[8:11], v[140:143], v[224:227], v[8:11]
	s_setprio 0
	s_setprio 1
	v_mfma_f32_16x16x32_bf16 v[52:55], v[170:173], v[196:199], v[52:55]
	v_mfma_f32_16x16x32_bf16 v[48:51], v[188:191], v[196:199], v[48:51]
	v_mfma_f32_16x16x32_bf16 v[36:39], v[170:173], v[204:207], v[36:39]
	v_mfma_f32_16x16x32_bf16 v[32:35], v[188:191], v[204:207], v[32:35]
	v_mfma_f32_16x16x32_bf16 v[20:23], v[170:173], v[212:215], v[20:23]
	v_mfma_f32_16x16x32_bf16 v[16:19], v[188:191], v[212:215], v[16:19]
	v_mfma_f32_16x16x32_bf16 v[4:7], v[170:173], v[220:223], v[4:7]
	v_mfma_f32_16x16x32_bf16 v[0:3], v[188:191], v[220:223], v[0:3]
	v_mfma_f32_16x16x32_bf16 v[52:55], v[184:187], v[200:203], v[52:55]
	v_mfma_f32_16x16x32_bf16 v[48:51], v[192:195], v[200:203], v[48:51]
	v_mfma_f32_16x16x32_bf16 v[36:39], v[184:187], v[208:211], v[36:39]
	v_mfma_f32_16x16x32_bf16 v[32:35], v[192:195], v[208:211], v[32:35]
	v_mfma_f32_16x16x32_bf16 v[20:23], v[184:187], v[216:219], v[20:23]
	v_mfma_f32_16x16x32_bf16 v[16:19], v[192:195], v[216:219], v[16:19]
	v_mfma_f32_16x16x32_bf16 v[4:7], v[184:187], v[224:227], v[4:7]
	v_mfma_f32_16x16x32_bf16 v[0:3], v[192:195], v[224:227], v[0:3]
	s_setprio 0
	s_barrier
	s_add_i32 s72, 0, 0x18000
	s_add_i32 s73, 0, 0x1c000
	v_add_u32_e32 v140, s72, v177
	v_add_u32_e32 v192, s73, v177
	ds_read_b128 v[128:131], v140
	ds_read_b128 v[132:135], v140 offset:1024
	ds_read_b128 v[136:139], v140 offset:2048
	ds_read_b128 v[140:143], v140 offset:3072
	ds_read_b128 v[170:173], v192
	ds_read_b128 v[184:187], v192 offset:1024
	ds_read_b128 v[188:191], v192 offset:2048
	ds_read_b128 v[192:195], v192 offset:3072
	s_add_u32 s38, s38, 0x40000
	s_addc_u32 s39, s39, 0
	s_mov_b32 m0, s51
	v_lshl_add_u64 v[234:235], s[38:39], 0, v[144:145]
	ds_read_b128 v[196:199], v180 offset:32768
	ds_read_b128 v[200:203], v180 offset:33792
	ds_read_b128 v[204:207], v180 offset:34816
	ds_read_b128 v[208:211], v180 offset:35840
	ds_read_b128 v[212:215], v180 offset:36864
	ds_read_b128 v[216:219], v180 offset:37888
	ds_read_b128 v[220:223], v180 offset:38912
	ds_read_b128 v[224:227], v180 offset:39936
	global_load_lds_dwordx4 v[234:235], off
	v_lshl_add_u64 v[234:235], s[38:39], 0, v[148:149]
	s_mov_b32 m0, s52
	s_nop 0
	global_load_lds_dwordx4 v[234:235], off
	s_waitcnt vmcnt(8)
	s_waitcnt lgkmcnt(0)
	s_barrier
	s_setprio 1
	s_waitcnt lgkmcnt(0)
	v_mfma_f32_16x16x32_bf16 v[124:127], v[128:131], v[196:199], v[124:127]
	v_mfma_f32_16x16x32_bf16 v[120:123], v[136:139], v[196:199], v[120:123]
	v_mfma_f32_16x16x32_bf16 v[108:111], v[128:131], v[204:207], v[108:111]
	v_mfma_f32_16x16x32_bf16 v[104:107], v[136:139], v[204:207], v[104:107]
	v_mfma_f32_16x16x32_bf16 v[92:95], v[128:131], v[212:215], v[92:95]
	v_mfma_f32_16x16x32_bf16 v[88:91], v[136:139], v[212:215], v[88:91]
	v_mfma_f32_16x16x32_bf16 v[76:79], v[128:131], v[220:223], v[76:79]
	v_mfma_f32_16x16x32_bf16 v[72:75], v[136:139], v[220:223], v[72:75]
	v_mfma_f32_16x16x32_bf16 v[124:127], v[132:135], v[200:203], v[124:127]
	v_mfma_f32_16x16x32_bf16 v[120:123], v[140:143], v[200:203], v[120:123]
	v_mfma_f32_16x16x32_bf16 v[108:111], v[132:135], v[208:211], v[108:111]
	v_mfma_f32_16x16x32_bf16 v[104:107], v[140:143], v[208:211], v[104:107]
	v_mfma_f32_16x16x32_bf16 v[92:95], v[132:135], v[216:219], v[92:95]
	v_mfma_f32_16x16x32_bf16 v[88:91], v[140:143], v[216:219], v[88:91]
	v_mfma_f32_16x16x32_bf16 v[76:79], v[132:135], v[224:227], v[76:79]
	v_mfma_f32_16x16x32_bf16 v[72:75], v[140:143], v[224:227], v[72:75]
	s_setprio 0
	s_setprio 1
	v_mfma_f32_16x16x32_bf16 v[116:119], v[170:173], v[196:199], v[116:119]
	v_mfma_f32_16x16x32_bf16 v[112:115], v[188:191], v[196:199], v[112:115]
	v_mfma_f32_16x16x32_bf16 v[100:103], v[170:173], v[204:207], v[100:103]
	v_mfma_f32_16x16x32_bf16 v[96:99], v[188:191], v[204:207], v[96:99]
	v_mfma_f32_16x16x32_bf16 v[84:87], v[170:173], v[212:215], v[84:87]
	v_mfma_f32_16x16x32_bf16 v[80:83], v[188:191], v[212:215], v[80:83]
	v_mfma_f32_16x16x32_bf16 v[68:71], v[170:173], v[220:223], v[68:71]
	v_mfma_f32_16x16x32_bf16 v[64:67], v[188:191], v[220:223], v[64:67]
	v_mfma_f32_16x16x32_bf16 v[116:119], v[184:187], v[200:203], v[116:119]
	v_mfma_f32_16x16x32_bf16 v[112:115], v[192:195], v[200:203], v[112:115]
	v_mfma_f32_16x16x32_bf16 v[100:103], v[184:187], v[208:211], v[100:103]
	v_mfma_f32_16x16x32_bf16 v[96:99], v[192:195], v[208:211], v[96:99]
	v_mfma_f32_16x16x32_bf16 v[84:87], v[184:187], v[216:219], v[84:87]
	v_mfma_f32_16x16x32_bf16 v[80:83], v[192:195], v[216:219], v[80:83]
	v_mfma_f32_16x16x32_bf16 v[68:71], v[184:187], v[224:227], v[68:71]
	v_mfma_f32_16x16x32_bf16 v[64:67], v[192:195], v[224:227], v[64:67]
	s_setprio 0
	s_barrier
; #define PG8_STAGE(bufoff, gbase, voff) do { _Pragma("unroll") for (int _i = 0; _i < 2; ++_i) \
;         __builtin_amdgcn_global_load_lds((const unsigned*)((const char*)(gbase) + (voff)[_i]), (LAS unsigned*)(lds + (bufoff) + ldsw + _i * 8192), 16, 0, 0); } while (0)
; #define PG8_LDA(dst, b, h) do { _Pragma("unroll") for (int m = 0; m < 4; ++m) _Pragma("unroll") for (int k = 0; k < 2; ++k) dst[m][k] = *(const LAS bf16x8*)(lds + PG8_SA(b, h) + aoff + m * 2048 + k * 1024); } while (0)
; #define PG8_MMA(ai, bj, At, Bt) do { __builtin_amdgcn_s_setprio(1); _Pragma("unroll") for (int m = 0; m < 4; ++m) _Pragma("unroll") for (int n = 0; n < 2; ++n) _Pragma("unroll") for (int k = 0; k < 2; ++k) \
;         acc[ai][bj][m][n] = __builtin_amdgcn_mfma_f32_16x16x32_bf16(Bt[n][k], At[m][k], acc[ai][bj][m][n], 0, 0, 0); __builtin_amdgcn_s_setprio(0); } while (0)
; #define PG8_WAIT_V(n) asm volatile("s_waitcnt vmcnt(" #n ")" ::: "memory")
; #define PG8_WAIT_L(n) asm volatile("s_waitcnt lgkmcnt(" #n ")" ::: "memory")
; #define PG8_BAR __builtin_amdgcn_s_barrier()
; #define PG8_SCHED __builtin_amdgcn_sched_barrier(0)
; template <class Epi, class Sched>
; __device__ __forceinline__ void gemm_phase(LAS unsigned char* lds, const Gemm g, const Sched& S, const Epi& E, int wave_id) {
;     ...
;             PG8_LDA(At, 1, 1); PG8_STAGE(PG8_SB(1, 0), b3, voffB); PG8_STAGE(PG8_SB(1, 1), b3 + hstepB, voffB); PG8_STAGE(PG8_SA(1, 0), a3, voffA);
;             PG8_WAIT_V(8); PG8_WAIT_L(0); PG8_BAR; PG8_MMA(1, 0, At, B0); PG8_MMA(1, 1, At, B1); PG8_BAR; PG8_SCHED;
;         }
	s_add_i32 s38, s72, s2
	v_lshl_add_u64 v[174:175], v[174:175], 0, s[16:17]
	s_mov_b32 m0, s38
	ds_read_b128 v[196:199], v180 offset:49152
	ds_read_b128 v[200:203], v180 offset:50176
	ds_read_b128 v[204:207], v180 offset:51200
	ds_read_b128 v[208:211], v180 offset:52224
	ds_read_b128 v[212:215], v180 offset:53248
	ds_read_b128 v[216:219], v180 offset:54272
	ds_read_b128 v[220:223], v180 offset:55296
	ds_read_b128 v[224:227], v180 offset:56320
	global_load_lds_dwordx4 v[174:175], off
	s_add_i32 m0, s38, 0x2000
	s_add_u32 s36, s36, 0x40080
	v_lshl_add_u64 v[174:175], v[228:229], 0, s[16:17]
	s_addc_u32 s37, s37, 0
	s_add_i32 s38, s73, s2
	global_load_lds_dwordx4 v[174:175], off
	v_lshl_add_u64 v[174:175], s[36:37], 0, v[146:147]
	s_mov_b32 m0, s38
	s_nop 0
	global_load_lds_dwordx4 v[174:175], off
	v_lshl_add_u64 v[174:175], s[36:37], 0, v[150:151]
	s_add_i32 m0, s38, 0x2000
	s_nop 0
	global_load_lds_dwordx4 v[174:175], off
	v_lshl_add_u64 v[174:175], v[230:231], 0, s[16:17]
	s_mov_b32 m0, s54
	s_nop 0
	global_load_lds_dwordx4 v[174:175], off
	v_lshl_add_u64 v[174:175], v[232:233], 0, s[16:17]
	s_mov_b32 m0, s55
	s_nop 0
	global_load_lds_dwordx4 v[174:175], off
	s_waitcnt vmcnt(8)
	s_waitcnt lgkmcnt(0)
	s_barrier
	s_setprio 1
	s_waitcnt lgkmcnt(0)
	v_mfma_f32_16x16x32_bf16 v[60:63], v[128:131], v[196:199], v[60:63]
	v_mfma_f32_16x16x32_bf16 v[56:59], v[136:139], v[196:199], v[56:59]
	v_mfma_f32_16x16x32_bf16 v[44:47], v[128:131], v[204:207], v[44:47]
	v_mfma_f32_16x16x32_bf16 v[40:43], v[136:139], v[204:207], v[40:43]
	v_mfma_f32_16x16x32_bf16 v[28:31], v[128:131], v[212:215], v[28:31]
	v_mfma_f32_16x16x32_bf16 v[24:27], v[136:139], v[212:215], v[24:27]
	v_mfma_f32_16x16x32_bf16 v[12:15], v[128:131], v[220:223], v[12:15]
	v_mfma_f32_16x16x32_bf16 v[8:11], v[136:139], v[220:223], v[8:11]
	v_mfma_f32_16x16x32_bf16 v[60:63], v[132:135], v[200:203], v[60:63]
	v_mfma_f32_16x16x32_bf16 v[56:59], v[140:143], v[200:203], v[56:59]
	v_mfma_f32_16x16x32_bf16 v[44:47], v[132:135], v[208:211], v[44:47]
	v_mfma_f32_16x16x32_bf16 v[40:43], v[140:143], v[208:211], v[40:43]
	v_mfma_f32_16x16x32_bf16 v[28:31], v[132:135], v[216:219], v[28:31]
	v_mfma_f32_16x16x32_bf16 v[24:27], v[140:143], v[216:219], v[24:27]
	v_mfma_f32_16x16x32_bf16 v[12:15], v[132:135], v[224:227], v[12:15]
	v_mfma_f32_16x16x32_bf16 v[8:11], v[140:143], v[224:227], v[8:11]
	s_setprio 0
	s_setprio 1
	v_mfma_f32_16x16x32_bf16 v[52:55], v[170:173], v[196:199], v[52:55]
	v_mfma_f32_16x16x32_bf16 v[48:51], v[188:191], v[196:199], v[48:51]
	v_mfma_f32_16x16x32_bf16 v[36:39], v[170:173], v[204:207], v[36:39]
	v_mfma_f32_16x16x32_bf16 v[32:35], v[188:191], v[204:207], v[32:35]
	v_mfma_f32_16x16x32_bf16 v[20:23], v[170:173], v[212:215], v[20:23]
	v_mfma_f32_16x16x32_bf16 v[16:19], v[188:191], v[212:215], v[16:19]
	v_mfma_f32_16x16x32_bf16 v[4:7], v[170:173], v[220:223], v[4:7]
	v_mfma_f32_16x16x32_bf16 v[0:3], v[188:191], v[220:223], v[0:3]
	v_mfma_f32_16x16x32_bf16 v[52:55], v[184:187], v[200:203], v[52:55]
	v_mfma_f32_16x16x32_bf16 v[48:51], v[192:195], v[200:203], v[48:51]
	v_mfma_f32_16x16x32_bf16 v[36:39], v[184:187], v[208:211], v[36:39]
	v_mfma_f32_16x16x32_bf16 v[32:35], v[192:195], v[208:211], v[32:35]
	v_mfma_f32_16x16x32_bf16 v[20:23], v[184:187], v[216:219], v[20:23]
	v_mfma_f32_16x16x32_bf16 v[16:19], v[192:195], v[216:219], v[16:19]
	v_mfma_f32_16x16x32_bf16 v[4:7], v[184:187], v[224:227], v[4:7]
	v_mfma_f32_16x16x32_bf16 v[0:3], v[192:195], v[224:227], v[0:3]
	s_setprio 0
	s_add_i32 s67, s67, 2
	s_add_u32 s34, s34, 0x100
	s_addc_u32 s35, s35, 0
	s_add_u32 s65, s65, 0x100
	s_addc_u32 s66, s66, 0
	s_cmp_gt_u32 s67, 13
	s_barrier
	s_cbranch_scc0 .LBB0_1251
	s_and_b64 vcc, exec, s[18:19]
	s_cbranch_vccz .LBB0_1254
	s_barrier

; #define PG8_STAGE(bufoff, gbase, voff) do { _Pragma("unroll") for (int _i = 0; _i < 2; ++_i) \
;         __builtin_amdgcn_global_load_lds((const unsigned*)((const char*)(gbase) + (voff)[_i]), (LAS unsigned*)(lds + (bufoff) + ldsw + _i * 8192), 16, 0, 0); } while (0)
; #define PG8_LDA(dst, b, h) do { _Pragma("unroll") for (int m = 0; m < 4; ++m) _Pragma("unroll") for (int k = 0; k < 2; ++k) dst[m][k] = *(const LAS bf16x8*)(lds + PG8_SA(b, h) + aoff + m * 2048 + k * 1024); } while (0)
; #define PG8_LDB(dst, b, h) do { _Pragma("unroll") for (int n = 0; n < 2; ++n) _Pragma("unroll") for (int k = 0; k < 2; ++k) dst[n][k] = *(const LAS bf16x8*)(lds + PG8_SB(b, h) + boff + n * 2048 + k * 1024); } while (0)
; #define PG8_MMA(ai, bj, At, Bt) do { __builtin_amdgcn_s_setprio(1); _Pragma("unroll") for (int m = 0; m < 4; ++m) _Pragma("unroll") for (int n = 0; n < 2; ++n) _Pragma("unroll") for (int k = 0; k < 2; ++k) \
;         acc[ai][bj][m][n] = __builtin_amdgcn_mfma_f32_16x16x32_bf16(Bt[n][k], At[m][k], acc[ai][bj][m][n], 0, 0, 0); __builtin_amdgcn_s_setprio(0); } while (0)
; #define PG8_WAIT_V(n) asm volatile("s_waitcnt vmcnt(" #n ")" ::: "memory")
; #define PG8_WAIT_L(n) asm volatile("s_waitcnt lgkmcnt(" #n ")" ::: "memory")
; #define PG8_BAR __builtin_amdgcn_s_barrier()
; #define PG8_SCHED __builtin_amdgcn_sched_barrier(0)
; template <class Epi, class Sched>
; __device__ __forceinline__ void gemm_phase(LAS unsigned char* lds, const Gemm g, const Sched& S, const Epi& E, int wave_id) {
;     ...
;         for (int t = 0; t < nt; t += 2) {
;             const bool last = (t == nt - 2);
;             const char* a1 = cA + (size_t)(t + 1) * kstep;
;             const char* a2 = last ? nA : cA + (size_t)(t + 2) * kstep; const char* b2 = last ? nB : cB + (size_t)(t + 2) * kstep;
;             const char* a3 = a2 + kstep; const char* b3 = b2 + kstep;
;             PG8_LDB(B0, 0, 0); PG8_LDB(B1, 0, 1); PG8_SCHED; PG8_LDA(At, 0, 0); PG8_STAGE(PG8_SA(1, 1), a1 + hstepA, voffA);
;             PG8_WAIT_V(8); PG8_WAIT_L(0); PG8_BAR; PG8_MMA(0, 0, At, B0); PG8_MMA(0, 1, At, B1); PG8_BAR; PG8_SCHED;
;             PG8_LDA(At, 0, 1); PG8_STAGE(PG8_SB(0, 0), b2, voffB); PG8_STAGE(PG8_SB(0, 1), b2 + hstepB, voffB); PG8_STAGE(PG8_SA(0, 0), a2, voffA);
;             PG8_WAIT_V(8); PG8_WAIT_L(0); PG8_BAR; PG8_MMA(1, 0, At, B0); PG8_MMA(1, 1, At, B1); PG8_BAR; PG8_SCHED;
.LBB0_1382:
	ds_read_b128 v[8:11], v200
	ds_read_b128 v[12:15], v200 offset:1024
	ds_read_b128 v[16:19], v200 offset:2048
	ds_read_b128 v[20:23], v200 offset:3072
	ds_read_b128 v[144:147], v201
	ds_read_b128 v[148:151], v201 offset:1024
	ds_read_b128 v[176:179], v201 offset:2048
	ds_read_b128 v[180:183], v201 offset:3072
	s_add_u32 s46, s12, 0xfffc0080
	s_addc_u32 s47, s13, -1
	s_cmp_eq_u32 s67, 12
	s_cselect_b32 s49, s41, s47
	s_cselect_b32 s48, s50, s46
	s_cselect_b32 s47, s39, s66
	s_cselect_b32 s46, s51, s65
	v_lshl_add_u64 v[222:223], s[12:13], 0, v[168:169]
	s_add_i32 m0, s37, 0xc000
	ds_read_b128 v[184:187], v202
	ds_read_b128 v[188:191], v202 offset:1024
	ds_read_b128 v[192:195], v202 offset:2048
	ds_read_b128 v[196:199], v202 offset:3072
	ds_read_b128 v[206:209], v202 offset:4096
	ds_read_b128 v[210:213], v202 offset:5120
	ds_read_b128 v[214:217], v202 offset:6144
	ds_read_b128 v[218:221], v202 offset:7168
	global_load_lds_dwordx4 v[222:223], off
	v_lshl_add_u64 v[222:223], s[12:13], 0, v[170:171]
	s_add_i32 m0, s37, 0xe000
	s_nop 0
	global_load_lds_dwordx4 v[222:223], off
	s_waitcnt vmcnt(8)
	s_waitcnt lgkmcnt(0)
	s_barrier
	s_setprio 1
	s_waitcnt lgkmcnt(0)
	v_mfma_f32_16x16x32_bf16 v[140:143], v[8:11], v[184:187], v[140:143]
	v_mfma_f32_16x16x32_bf16 v[136:139], v[16:19], v[184:187], v[136:139]
	v_mfma_f32_16x16x32_bf16 v[124:127], v[8:11], v[192:195], v[124:127]
	v_mfma_f32_16x16x32_bf16 v[120:123], v[16:19], v[192:195], v[120:123]
	v_mfma_f32_16x16x32_bf16 v[108:111], v[8:11], v[206:209], v[108:111]
	v_mfma_f32_16x16x32_bf16 v[104:107], v[16:19], v[206:209], v[104:107]
	v_mfma_f32_16x16x32_bf16 v[92:95], v[8:11], v[214:217], v[92:95]
	v_mfma_f32_16x16x32_bf16 v[88:91], v[16:19], v[214:217], v[88:91]
	v_mfma_f32_16x16x32_bf16 v[140:143], v[12:15], v[188:191], v[140:143]
	v_mfma_f32_16x16x32_bf16 v[136:139], v[20:23], v[188:191], v[136:139]
	v_mfma_f32_16x16x32_bf16 v[124:127], v[12:15], v[196:199], v[124:127]
	v_mfma_f32_16x16x32_bf16 v[120:123], v[20:23], v[196:199], v[120:123]
	v_mfma_f32_16x16x32_bf16 v[108:111], v[12:15], v[210:213], v[108:111]
	v_mfma_f32_16x16x32_bf16 v[104:107], v[20:23], v[210:213], v[104:107]
	v_mfma_f32_16x16x32_bf16 v[92:95], v[12:15], v[218:221], v[92:95]
	v_mfma_f32_16x16x32_bf16 v[88:91], v[20:23], v[218:221], v[88:91]
	s_setprio 0
	s_setprio 1
	v_mfma_f32_16x16x32_bf16 v[132:135], v[144:147], v[184:187], v[132:135]
	v_mfma_f32_16x16x32_bf16 v[128:131], v[176:179], v[184:187], v[128:131]
	v_mfma_f32_16x16x32_bf16 v[116:119], v[144:147], v[192:195], v[116:119]
	v_mfma_f32_16x16x32_bf16 v[112:115], v[176:179], v[192:195], v[112:115]
	v_mfma_f32_16x16x32_bf16 v[100:103], v[144:147], v[206:209], v[100:103]
	v_mfma_f32_16x16x32_bf16 v[96:99], v[176:179], v[206:209], v[96:99]
	v_mfma_f32_16x16x32_bf16 v[84:87], v[144:147], v[214:217], v[84:87]
	v_mfma_f32_16x16x32_bf16 v[80:83], v[176:179], v[214:217], v[80:83]
	v_mfma_f32_16x16x32_bf16 v[132:135], v[148:151], v[188:191], v[132:135]
	v_mfma_f32_16x16x32_bf16 v[128:131], v[180:183], v[188:191], v[128:131]
	v_mfma_f32_16x16x32_bf16 v[116:119], v[148:151], v[196:199], v[116:119]
	v_mfma_f32_16x16x32_bf16 v[112:115], v[180:183], v[196:199], v[112:115]
	v_mfma_f32_16x16x32_bf16 v[100:103], v[148:151], v[210:213], v[100:103]
	v_mfma_f32_16x16x32_bf16 v[96:99], v[180:183], v[210:213], v[96:99]
	v_mfma_f32_16x16x32_bf16 v[84:87], v[148:151], v[218:221], v[84:87]
	v_mfma_f32_16x16x32_bf16 v[80:83], v[180:183], v[218:221], v[80:83]
	s_setprio 0
	s_barrier
	s_add_i32 s72, s61, s35
	v_lshl_add_u64 v[222:223], s[46:47], 0, v[154:155]
	s_mov_b32 m0, s72
	ds_read_b128 v[184:187], v202 offset:16384
	ds_read_b128 v[188:191], v202 offset:17408
	ds_read_b128 v[192:195], v202 offset:18432
	ds_read_b128 v[196:199], v202 offset:19456
	ds_read_b128 v[206:209], v202 offset:20480
	ds_read_b128 v[210:213], v202 offset:21504
	ds_read_b128 v[214:217], v202 offset:22528
	ds_read_b128 v[218:221], v202 offset:23552
	global_load_lds_dwordx4 v[222:223], off
	s_add_i32 m0, s72, 0x2000
	s_add_u32 s72, s46, 0x40000
	v_lshl_add_u64 v[224:225], s[46:47], 0, v[158:159]
	s_addc_u32 s73, s47, 0
	s_add_i32 s74, s62, s35
	global_load_lds_dwordx4 v[224:225], off
	v_lshl_add_u64 v[226:227], s[72:73], 0, v[154:155]
	s_mov_b32 m0, s74
	v_lshl_add_u64 v[228:229], s[48:49], 0, v[156:157]
	global_load_lds_dwordx4 v[226:227], off
	v_lshl_add_u64 v[226:227], s[72:73], 0, v[158:159]
	s_add_i32 m0, s74, 0x2000
	s_nop 0
	global_load_lds_dwordx4 v[226:227], off
	v_lshl_add_u64 v[226:227], s[48:49], 0, v[152:153]
	s_mov_b32 m0, s37
	s_nop 0
	global_load_lds_dwordx4 v[226:227], off
	s_mov_b32 m0, s52
	s_nop 0
	global_load_lds_dwordx4 v[228:229], off
	s_waitcnt vmcnt(8)
	s_waitcnt lgkmcnt(0)
	s_barrier
; #define PG8_STAGE(bufoff, gbase, voff) do { _Pragma("unroll") for (int _i = 0; _i < 2; ++_i) \
;         __builtin_amdgcn_global_load_lds((const unsigned*)((const char*)(gbase) + (voff)[_i]), (LAS unsigned*)(lds + (bufoff) + ldsw + _i * 8192), 16, 0, 0); } while (0)
; #define PG8_LDA(dst, b, h) do { _Pragma("unroll") for (int m = 0; m < 4; ++m) _Pragma("unroll") for (int k = 0; k < 2; ++k) dst[m][k] = *(const LAS bf16x8*)(lds + PG8_SA(b, h) + aoff + m * 2048 + k * 1024); } while (0)
; #define PG8_LDB(dst, b, h) do { _Pragma("unroll") for (int n = 0; n < 2; ++n) _Pragma("unroll") for (int k = 0; k < 2; ++k) dst[n][k] = *(const LAS bf16x8*)(lds + PG8_SB(b, h) + boff + n * 2048 + k * 1024); } while (0)
; #define PG8_MMA(ai, bj, At, Bt) do { __builtin_amdgcn_s_setprio(1); _Pragma("unroll") for (int m = 0; m < 4; ++m) _Pragma("unroll") for (int n = 0; n < 2; ++n) _Pragma("unroll") for (int k = 0; k < 2; ++k) \
;         acc[ai][bj][m][n] = __builtin_amdgcn_mfma_f32_16x16x32_bf16(Bt[n][k], At[m][k], acc[ai][bj][m][n], 0, 0, 0); __builtin_amdgcn_s_setprio(0); } while (0)
; #define PG8_WAIT_V(n) asm volatile("s_waitcnt vmcnt(" #n ")" ::: "memory")
; #define PG8_WAIT_L(n) asm volatile("s_waitcnt lgkmcnt(" #n ")" ::: "memory")
; #define PG8_BAR __builtin_amdgcn_s_barrier()
; #define PG8_SCHED __builtin_amdgcn_sched_barrier(0)
; template <class Epi, class Sched>
; __device__ __forceinline__ void gemm_phase(LAS unsigned char* lds, const Gemm g, const Sched& S, const Epi& E, int wave_id) {
;     ...
;             PG8_WAIT_V(8); PG8_WAIT_L(0); PG8_BAR; PG8_MMA(1, 0, At, B0); PG8_MMA(1, 1, At, B1); PG8_BAR; PG8_SCHED;
;             PG8_LDB(B0, 1, 0); PG8_LDB(B1, 1, 1); PG8_SCHED; PG8_LDA(At, 1, 0); PG8_STAGE(PG8_SA(0, 1), a2 + hstepA, voffA);
;             PG8_WAIT_V(8); PG8_WAIT_L(0); PG8_BAR; PG8_MMA(0, 0, At, B0); PG8_MMA(0, 1, At, B1); PG8_BAR; PG8_SCHED;
	s_setprio 1
	s_waitcnt lgkmcnt(0)
	v_mfma_f32_16x16x32_bf16 v[76:79], v[8:11], v[184:187], v[76:79]
	v_mfma_f32_16x16x32_bf16 v[72:75], v[16:19], v[184:187], v[72:75]
	v_mfma_f32_16x16x32_bf16 v[60:63], v[8:11], v[192:195], v[60:63]
	v_mfma_f32_16x16x32_bf16 v[56:59], v[16:19], v[192:195], v[56:59]
	v_mfma_f32_16x16x32_bf16 v[44:47], v[8:11], v[206:209], v[44:47]
	v_mfma_f32_16x16x32_bf16 v[40:43], v[16:19], v[206:209], v[40:43]
	v_mfma_f32_16x16x32_bf16 v[8:11], v[8:11], v[214:217], v[28:31]
	v_mfma_f32_16x16x32_bf16 v[76:79], v[12:15], v[188:191], v[76:79]
	v_mfma_f32_16x16x32_bf16 v[72:75], v[20:23], v[188:191], v[72:75]
	v_mfma_f32_16x16x32_bf16 v[60:63], v[12:15], v[196:199], v[60:63]
	v_mfma_f32_16x16x32_bf16 v[56:59], v[20:23], v[196:199], v[56:59]
	v_mfma_f32_16x16x32_bf16 v[44:47], v[12:15], v[210:213], v[44:47]
	v_mfma_f32_16x16x32_bf16 v[40:43], v[20:23], v[210:213], v[40:43]
	v_mfma_f32_16x16x32_bf16 v[8:11], v[12:15], v[218:221], v[8:11]
	v_mfma_f32_16x16x32_bf16 v[12:15], v[16:19], v[214:217], v[24:27]
	v_mfma_f32_16x16x32_bf16 v[12:15], v[20:23], v[218:221], v[12:15]
	s_setprio 0
	s_setprio 1
	v_mfma_f32_16x16x32_bf16 v[24:27], v[144:147], v[192:195], v[52:55]
	v_mfma_f32_16x16x32_bf16 v[52:55], v[148:151], v[196:199], v[24:27]
	v_mfma_f32_16x16x32_bf16 v[24:27], v[176:179], v[192:195], v[48:51]
	v_mfma_f32_16x16x32_bf16 v[48:51], v[180:183], v[196:199], v[24:27]
	v_mfma_f32_16x16x32_bf16 v[24:27], v[144:147], v[206:209], v[36:39]
	v_mfma_f32_16x16x32_bf16 v[36:39], v[148:151], v[210:213], v[24:27]
	v_mfma_f32_16x16x32_bf16 v[24:27], v[176:179], v[206:209], v[32:35]
	v_mfma_f32_16x16x32_bf16 v[4:7], v[144:147], v[214:217], v[4:7]
	v_mfma_f32_16x16x32_bf16 v[0:3], v[176:179], v[214:217], v[0:3]
	v_mfma_f32_16x16x32_bf16 v[16:19], v[144:147], v[184:187], v[68:71]
	v_mfma_f32_16x16x32_bf16 v[20:23], v[176:179], v[184:187], v[64:67]
	v_mfma_f32_16x16x32_bf16 v[32:35], v[180:183], v[210:213], v[24:27]
	v_mfma_f32_16x16x32_bf16 v[4:7], v[148:151], v[218:221], v[4:7]
	v_mfma_f32_16x16x32_bf16 v[0:3], v[180:183], v[218:221], v[0:3]
	v_mfma_f32_16x16x32_bf16 v[16:19], v[148:151], v[188:191], v[16:19]
	v_mfma_f32_16x16x32_bf16 v[20:23], v[180:183], v[188:191], v[20:23]
	s_setprio 0
	s_barrier
	s_add_i32 s72, 0, 0x18000
	s_add_i32 s73, 0, 0x1c000
	v_add_u32_e32 v68, s72, v165
	v_add_u32_e32 v180, s73, v165
	ds_read_b128 v[24:27], v68
	ds_read_b128 v[28:31], v68 offset:1024
	ds_read_b128 v[64:67], v68 offset:2048
	ds_read_b128 v[68:71], v68 offset:3072
	ds_read_b128 v[144:147], v180
	ds_read_b128 v[148:151], v180 offset:1024
	ds_read_b128 v[176:179], v180 offset:2048
	ds_read_b128 v[180:183], v180 offset:3072
	s_add_u32 s48, s48, 0x40000
	s_addc_u32 s49, s49, 0
	s_mov_b32 m0, s53
	v_lshl_add_u64 v[230:231], s[48:49], 0, v[152:153]
	ds_read_b128 v[184:187], v202 offset:32768
	ds_read_b128 v[188:191], v202 offset:33792
	ds_read_b128 v[192:195], v202 offset:34816
	ds_read_b128 v[196:199], v202 offset:35840
	ds_read_b128 v[206:209], v202 offset:36864
	ds_read_b128 v[210:213], v202 offset:37888
	ds_read_b128 v[214:217], v202 offset:38912
	ds_read_b128 v[218:221], v202 offset:39936
	global_load_lds_dwordx4 v[230:231], off
	v_lshl_add_u64 v[230:231], s[48:49], 0, v[156:157]
	s_mov_b32 m0, s54
	s_nop 0
	global_load_lds_dwordx4 v[230:231], off
	s_waitcnt vmcnt(8)
	s_waitcnt lgkmcnt(0)
	s_barrier
	s_setprio 1
	s_waitcnt lgkmcnt(0)
	v_mfma_f32_16x16x32_bf16 v[140:143], v[24:27], v[184:187], v[140:143]
	v_mfma_f32_16x16x32_bf16 v[136:139], v[64:67], v[184:187], v[136:139]
	v_mfma_f32_16x16x32_bf16 v[124:127], v[24:27], v[192:195], v[124:127]
	v_mfma_f32_16x16x32_bf16 v[120:123], v[64:67], v[192:195], v[120:123]
	v_mfma_f32_16x16x32_bf16 v[108:111], v[24:27], v[206:209], v[108:111]
	v_mfma_f32_16x16x32_bf16 v[104:107], v[64:67], v[206:209], v[104:107]
	v_mfma_f32_16x16x32_bf16 v[92:95], v[24:27], v[214:217], v[92:95]
	v_mfma_f32_16x16x32_bf16 v[88:91], v[64:67], v[214:217], v[88:91]
	v_mfma_f32_16x16x32_bf16 v[140:143], v[28:31], v[188:191], v[140:143]
	v_mfma_f32_16x16x32_bf16 v[136:139], v[68:71], v[188:191], v[136:139]
	v_mfma_f32_16x16x32_bf16 v[124:127], v[28:31], v[196:199], v[124:127]
	v_mfma_f32_16x16x32_bf16 v[120:123], v[68:71], v[196:199], v[120:123]
	v_mfma_f32_16x16x32_bf16 v[108:111], v[28:31], v[210:213], v[108:111]
	v_mfma_f32_16x16x32_bf16 v[104:107], v[68:71], v[210:213], v[104:107]
	v_mfma_f32_16x16x32_bf16 v[92:95], v[28:31], v[218:221], v[92:95]
	v_mfma_f32_16x16x32_bf16 v[88:91], v[68:71], v[218:221], v[88:91]
	s_setprio 0
	s_setprio 1
	v_mfma_f32_16x16x32_bf16 v[132:135], v[144:147], v[184:187], v[132:135]
	v_mfma_f32_16x16x32_bf16 v[128:131], v[176:179], v[184:187], v[128:131]
	v_mfma_f32_16x16x32_bf16 v[116:119], v[144:147], v[192:195], v[116:119]
	v_mfma_f32_16x16x32_bf16 v[112:115], v[176:179], v[192:195], v[112:115]
	v_mfma_f32_16x16x32_bf16 v[100:103], v[144:147], v[206:209], v[100:103]
	v_mfma_f32_16x16x32_bf16 v[96:99], v[176:179], v[206:209], v[96:99]
	v_mfma_f32_16x16x32_bf16 v[84:87], v[144:147], v[214:217], v[84:87]
	v_mfma_f32_16x16x32_bf16 v[80:83], v[176:179], v[214:217], v[80:83]
	v_mfma_f32_16x16x32_bf16 v[132:135], v[148:151], v[188:191], v[132:135]
	v_mfma_f32_16x16x32_bf16 v[128:131], v[180:183], v[188:191], v[128:131]
	v_mfma_f32_16x16x32_bf16 v[116:119], v[148:151], v[196:199], v[116:119]
	v_mfma_f32_16x16x32_bf16 v[112:115], v[180:183], v[196:199], v[112:115]
	v_mfma_f32_16x16x32_bf16 v[100:103], v[148:151], v[210:213], v[100:103]
	v_mfma_f32_16x16x32_bf16 v[96:99], v[180:183], v[210:213], v[96:99]
	v_mfma_f32_16x16x32_bf16 v[84:87], v[148:151], v[218:221], v[84:87]
	v_mfma_f32_16x16x32_bf16 v[80:83], v[180:183], v[218:221], v[80:83]
	s_setprio 0
	s_barrier
; #define PG8_STAGE(bufoff, gbase, voff) do { _Pragma("unroll") for (int _i = 0; _i < 2; ++_i) \
;         __builtin_amdgcn_global_load_lds((const unsigned*)((const char*)(gbase) + (voff)[_i]), (LAS unsigned*)(lds + (bufoff) + ldsw + _i * 8192), 16, 0, 0); } while (0)
; #define PG8_LDA(dst, b, h) do { _Pragma("unroll") for (int m = 0; m < 4; ++m) _Pragma("unroll") for (int k = 0; k < 2; ++k) dst[m][k] = *(const LAS bf16x8*)(lds + PG8_SA(b, h) + aoff + m * 2048 + k * 1024); } while (0)
; #define PG8_MMA(ai, bj, At, Bt) do { __builtin_amdgcn_s_setprio(1); _Pragma("unroll") for (int m = 0; m < 4; ++m) _Pragma("unroll") for (int n = 0; n < 2; ++n) _Pragma("unroll") for (int k = 0; k < 2; ++k) \
;         acc[ai][bj][m][n] = __builtin_amdgcn_mfma_f32_16x16x32_bf16(Bt[n][k], At[m][k], acc[ai][bj][m][n], 0, 0, 0); __builtin_amdgcn_s_setprio(0); } while (0)
; #define PG8_WAIT_V(n) asm volatile("s_waitcnt vmcnt(" #n ")" ::: "memory")
; #define PG8_WAIT_L(n) asm volatile("s_waitcnt lgkmcnt(" #n ")" ::: "memory")
; #define PG8_BAR __builtin_amdgcn_s_barrier()
; #define PG8_SCHED __builtin_amdgcn_sched_barrier(0)
; template <class Epi, class Sched>
; __device__ __forceinline__ void gemm_phase(LAS unsigned char* lds, const Gemm g, const Sched& S, const Epi& E, int wave_id) {
;     ...
;             PG8_LDA(At, 1, 1); PG8_STAGE(PG8_SB(1, 0), b3, voffB); PG8_STAGE(PG8_SB(1, 1), b3 + hstepB, voffB); PG8_STAGE(PG8_SA(1, 0), a3, voffA);
;             PG8_WAIT_V(8); PG8_WAIT_L(0); PG8_BAR; PG8_MMA(1, 0, At, B0); PG8_MMA(1, 1, At, B1); PG8_BAR; PG8_SCHED;
;         }
	s_add_i32 s48, s72, s35
	v_lshl_add_u64 v[222:223], v[222:223], 0, s[22:23]
	s_mov_b32 m0, s48
	ds_read_b128 v[184:187], v202 offset:49152
	ds_read_b128 v[188:191], v202 offset:50176
	ds_read_b128 v[192:195], v202 offset:51200
	ds_read_b128 v[196:199], v202 offset:52224
	ds_read_b128 v[206:209], v202 offset:53248
	ds_read_b128 v[210:213], v202 offset:54272
	ds_read_b128 v[214:217], v202 offset:55296
	ds_read_b128 v[218:221], v202 offset:56320
	global_load_lds_dwordx4 v[222:223], off
	s_add_i32 m0, s48, 0x2000
	s_add_u32 s46, s46, 0x40080
	v_lshl_add_u64 v[222:223], v[224:225], 0, s[22:23]
	s_addc_u32 s47, s47, 0
	s_add_i32 s48, s73, s35
	global_load_lds_dwordx4 v[222:223], off
	v_lshl_add_u64 v[222:223], s[46:47], 0, v[154:155]
	s_mov_b32 m0, s48
	s_nop 0
	global_load_lds_dwordx4 v[222:223], off
	v_lshl_add_u64 v[222:223], s[46:47], 0, v[158:159]
	s_add_i32 m0, s48, 0x2000
	s_nop 0
	global_load_lds_dwordx4 v[222:223], off
	v_lshl_add_u64 v[222:223], v[226:227], 0, s[22:23]
	s_mov_b32 m0, s55
	s_nop 0
	global_load_lds_dwordx4 v[222:223], off
	v_lshl_add_u64 v[222:223], v[228:229], 0, s[22:23]
	s_mov_b32 m0, s56
	s_nop 0
	global_load_lds_dwordx4 v[222:223], off
	s_waitcnt vmcnt(8)
	s_waitcnt lgkmcnt(0)
	s_barrier
	s_setprio 1
	s_waitcnt lgkmcnt(0)
	v_mfma_f32_16x16x32_bf16 v[76:79], v[24:27], v[184:187], v[76:79]
	v_mfma_f32_16x16x32_bf16 v[60:63], v[24:27], v[192:195], v[60:63]
	v_mfma_f32_16x16x32_bf16 v[44:47], v[24:27], v[206:209], v[44:47]
	v_mfma_f32_16x16x32_bf16 v[8:11], v[24:27], v[214:217], v[8:11]
	v_mfma_f32_16x16x32_bf16 v[76:79], v[28:31], v[188:191], v[76:79]
	v_mfma_f32_16x16x32_bf16 v[72:75], v[64:67], v[184:187], v[72:75]
	v_mfma_f32_16x16x32_bf16 v[60:63], v[28:31], v[196:199], v[60:63]
	v_mfma_f32_16x16x32_bf16 v[56:59], v[64:67], v[192:195], v[56:59]
	v_mfma_f32_16x16x32_bf16 v[44:47], v[28:31], v[210:213], v[44:47]
	v_mfma_f32_16x16x32_bf16 v[40:43], v[64:67], v[206:209], v[40:43]
	v_mfma_f32_16x16x32_bf16 v[28:31], v[28:31], v[218:221], v[8:11]
	v_mfma_f32_16x16x32_bf16 v[8:11], v[64:67], v[214:217], v[12:15]
	v_mfma_f32_16x16x32_bf16 v[72:75], v[68:71], v[188:191], v[72:75]
	v_mfma_f32_16x16x32_bf16 v[56:59], v[68:71], v[196:199], v[56:59]
	v_mfma_f32_16x16x32_bf16 v[40:43], v[68:71], v[210:213], v[40:43]
	v_mfma_f32_16x16x32_bf16 v[24:27], v[68:71], v[218:221], v[8:11]
	s_setprio 0
	s_setprio 1
	v_mfma_f32_16x16x32_bf16 v[8:11], v[144:147], v[184:187], v[16:19]
	v_mfma_f32_16x16x32_bf16 v[68:71], v[148:151], v[188:191], v[8:11]
	v_mfma_f32_16x16x32_bf16 v[8:11], v[176:179], v[184:187], v[20:23]
	v_mfma_f32_16x16x32_bf16 v[64:67], v[180:183], v[188:191], v[8:11]
	v_mfma_f32_16x16x32_bf16 v[8:11], v[144:147], v[192:195], v[52:55]
	v_mfma_f32_16x16x32_bf16 v[52:55], v[148:151], v[196:199], v[8:11]
	v_mfma_f32_16x16x32_bf16 v[8:11], v[176:179], v[192:195], v[48:51]
	v_mfma_f32_16x16x32_bf16 v[48:51], v[180:183], v[196:199], v[8:11]
	v_mfma_f32_16x16x32_bf16 v[8:11], v[144:147], v[206:209], v[36:39]
	v_mfma_f32_16x16x32_bf16 v[36:39], v[148:151], v[210:213], v[8:11]
	v_mfma_f32_16x16x32_bf16 v[8:11], v[176:179], v[206:209], v[32:35]
	v_mfma_f32_16x16x32_bf16 v[4:7], v[144:147], v[214:217], v[4:7]
	v_mfma_f32_16x16x32_bf16 v[0:3], v[176:179], v[214:217], v[0:3]
	v_mfma_f32_16x16x32_bf16 v[32:35], v[180:183], v[210:213], v[8:11]
	v_mfma_f32_16x16x32_bf16 v[4:7], v[148:151], v[218:221], v[4:7]
	v_mfma_f32_16x16x32_bf16 v[0:3], v[180:183], v[218:221], v[0:3]
	s_setprio 0
	s_add_i32 s67, s67, 2
	s_add_u32 s12, s12, 0x100
	s_addc_u32 s13, s13, 0
	s_add_u32 s65, s65, 0x100
	s_addc_u32 s66, s66, 0
	s_cmp_gt_u32 s67, 13
	s_barrier
	s_cbranch_scc0 .LBB0_1382
	s_and_b64 vcc, exec, s[24:25]
	s_cbranch_vccz .LBB0_1385
	s_barrier
